# packed f32 FFN-in epilogue, dead transposed-table stores removed, flat to global memory ops in QKV/RetIn epilogues
# speedup vs baseline: 1.0023x; 1.0023x over previous
; DI u32x4 pk8(const f32x4& v0, const f32x4& v1) { u32x4 w; w.x = cvt_pk_bf16(v0[0], v0[1]); w.y = cvt_pk_bf16(v0[2], v0[3]); w.z = cvt_pk_bf16(v1[0], v1[1]); w.w = cvt_pk_bf16(v1[2], v1[3]); return w; }
;   DI void epi(const Acc& acc, const Unit& u, int wr, int wc, int fr, int fq, LAS unsigned char* lds) const {
;     ...
;     } else {
; #pragma unroll
;       for (int ai = 0; ai < 2; ++ai)
; #pragma unroll
;         for (int m = 0; m < 4; ++m) {
;           const int row = (u.pm - 4) * 256 + ai * 128 + wr * 64 + m * 16 + fr;
; #pragma unroll
;           for (int bj = 0; bj < 2; ++bj) {
;             const int tl = u.pn * 256 + bj * 128 + wc * 32 + 8 * fq;
;             const unsigned ro = (unsigned)((tl >> 7) * 4 + (row >> 9)) * 131072u + (unsigned)((row & 511) >> 5) * 8192u + (unsigned)((tl & 127) >> 4) * 1024u + (unsigned)((tl >> 3) & 1) * 512u + (unsigned)(row & 31) * 16u;
;             st16(vT, ro, pk8(acc[ai][bj][m][0], acc[ai][bj][m][1]));
;           }
;         }
.LBB0_134:
	s_mov_b64 s[12:13], s[86:87]
	s_add_u32 s24, s12, 0xbe00000
	s_addc_u32 s25, s13, 0
	s_cmp_lg_u32 s2, 0
	s_cbranch_scc0 .LBB0_205
	s_cmp_lt_i32 s53, 4
	s_mov_b64 s[0:1], -1
	s_cbranch_scc1 .LBB0_137
	s_add_u32 s0, s12, 0xde00000
	s_addc_u32 s1, s13, 0
	s_lshl_b32 s2, s53, 8
	s_add_i32 s4, s43, s2
	s_lshr_b32 s5, s4, 9
	s_lshl_b32 s4, s4, 8
	s_and_b32 s4, s4, 0x1c000
	s_lshl_b32 s28, s26, 3
	v_or_b32_e32 v148, s4, v153
	s_lshl_b32 s4, s26, 20
	s_lshl_b32 s27, s5, 17
	s_or_b32 s28, s28, 4
	v_or_b32_e32 v149, v148, v154
	s_add_i32 s27, s27, s4
	s_add_i32 s5, s5, s28
	v_or_b32_e32 v176, s27, v149
	s_lshl_b32 s5, s5, 17
	v_lshl_add_u64 v[146:147], s[0:1], 0, v[176:177]
	v_or_b32_e32 v176, s5, v149
	v_or_b32_e32 v148, v148, v155
	v_cvt_pk_bf16_f32 v142, v124, v125
	v_cvt_pk_bf16_f32 v143, v126, v127
	v_cvt_pk_bf16_f32 v144, v120, v121
	v_cvt_pk_bf16_f32 v145, v122, v123
	global_store_dwordx4 v[146:147], v[142:145], off
	v_lshl_add_u64 v[146:147], s[0:1], 0, v[176:177]
	v_or_b32_e32 v176, s27, v148
	v_cvt_pk_bf16_f32 v142, v116, v117
	v_cvt_pk_bf16_f32 v143, v118, v119
	v_cvt_pk_bf16_f32 v144, v112, v113
	v_cvt_pk_bf16_f32 v145, v114, v115
	global_store_dwordx4 v[146:147], v[142:145], off
	v_lshl_add_u64 v[146:147], s[0:1], 0, v[176:177]
	v_or_b32_e32 v176, s5, v148
	v_or_b32_e32 v149, 0x2000, v149
	v_cvt_pk_bf16_f32 v142, v108, v109
	v_cvt_pk_bf16_f32 v143, v110, v111
	v_cvt_pk_bf16_f32 v144, v104, v105
	v_cvt_pk_bf16_f32 v145, v106, v107
	global_store_dwordx4 v[146:147], v[142:145], off
	v_lshl_add_u64 v[146:147], s[0:1], 0, v[176:177]
	v_or_b32_e32 v176, s27, v149
	v_cvt_pk_bf16_f32 v142, v100, v101
	v_cvt_pk_bf16_f32 v143, v102, v103
	v_cvt_pk_bf16_f32 v144, v96, v97
	v_cvt_pk_bf16_f32 v145, v98, v99
	global_store_dwordx4 v[146:147], v[142:145], off
	v_lshl_add_u64 v[146:147], s[0:1], 0, v[176:177]
	v_or_b32_e32 v176, s5, v149
	v_or_b32_e32 v148, 0x2000, v148
	v_cvt_pk_bf16_f32 v142, v92, v93
	v_cvt_pk_bf16_f32 v143, v94, v95
	v_cvt_pk_bf16_f32 v144, v88, v89
	v_cvt_pk_bf16_f32 v145, v90, v91
	global_store_dwordx4 v[146:147], v[142:145], off
	v_lshl_add_u64 v[146:147], s[0:1], 0, v[176:177]
	v_or_b32_e32 v176, s27, v148
	s_add_i32 s2, s44, s2
	v_cvt_pk_bf16_f32 v142, v84, v85
	v_cvt_pk_bf16_f32 v143, v86, v87
	v_cvt_pk_bf16_f32 v144, v80, v81
	v_cvt_pk_bf16_f32 v145, v82, v83
	global_store_dwordx4 v[146:147], v[142:145], off
	v_lshl_add_u64 v[146:147], s[0:1], 0, v[176:177]
	v_or_b32_e32 v176, s5, v148
	s_lshr_b32 s5, s2, 9
	s_lshl_b32 s2, s2, 8
	s_and_b32 s2, s2, 0x1c000
	v_or_b32_e32 v148, s2, v153
	s_lshl_b32 s2, s5, 17
	v_or_b32_e32 v149, v148, v154
	s_add_i32 s2, s2, s4
	s_add_i32 s5, s5, s28
	v_cvt_pk_bf16_f32 v142, v76, v77
	v_cvt_pk_bf16_f32 v143, v78, v79
	v_cvt_pk_bf16_f32 v144, v72, v73
	v_cvt_pk_bf16_f32 v145, v74, v75
	global_store_dwordx4 v[146:147], v[142:145], off
	v_lshl_add_u64 v[146:147], s[0:1], 0, v[176:177]
	v_or_b32_e32 v176, s2, v149
	s_lshl_b32 s4, s5, 17
	v_cvt_pk_bf16_f32 v142, v68, v69
	v_cvt_pk_bf16_f32 v143, v70, v71
	v_cvt_pk_bf16_f32 v144, v64, v65
	v_cvt_pk_bf16_f32 v145, v66, v67
	global_store_dwordx4 v[146:147], v[142:145], off
	v_lshl_add_u64 v[146:147], s[0:1], 0, v[176:177]
	v_or_b32_e32 v176, s4, v149
	v_or_b32_e32 v148, v148, v155
	v_cvt_pk_bf16_f32 v142, v60, v61
	v_cvt_pk_bf16_f32 v143, v62, v63
	v_cvt_pk_bf16_f32 v144, v56, v57
	v_cvt_pk_bf16_f32 v145, v58, v59
	global_store_dwordx4 v[146:147], v[142:145], off
	v_lshl_add_u64 v[146:147], s[0:1], 0, v[176:177]
	v_or_b32_e32 v176, s2, v148
	v_cvt_pk_bf16_f32 v142, v52, v53
	v_cvt_pk_bf16_f32 v143, v54, v55
	v_cvt_pk_bf16_f32 v144, v48, v49
	v_cvt_pk_bf16_f32 v145, v50, v51
	global_store_dwordx4 v[146:147], v[142:145], off
	v_lshl_add_u64 v[146:147], s[0:1], 0, v[176:177]
	v_or_b32_e32 v176, s4, v148
	v_or_b32_e32 v149, 0x2000, v149
	v_cvt_pk_bf16_f32 v142, v44, v45
	v_cvt_pk_bf16_f32 v143, v46, v47
	v_cvt_pk_bf16_f32 v144, v40, v41
	v_cvt_pk_bf16_f32 v145, v42, v43
	global_store_dwordx4 v[146:147], v[142:145], off
	v_lshl_add_u64 v[146:147], s[0:1], 0, v[176:177]
	v_or_b32_e32 v176, s2, v149
	v_cvt_pk_bf16_f32 v142, v36, v37
	v_cvt_pk_bf16_f32 v143, v38, v39
	v_cvt_pk_bf16_f32 v144, v32, v33
	v_cvt_pk_bf16_f32 v145, v34, v35
	global_store_dwordx4 v[146:147], v[142:145], off
	v_lshl_add_u64 v[146:147], s[0:1], 0, v[176:177]
	v_or_b32_e32 v176, s4, v149
	v_or_b32_e32 v148, 0x2000, v148
	v_cvt_pk_bf16_f32 v142, v28, v29
	v_cvt_pk_bf16_f32 v143, v30, v31
	v_cvt_pk_bf16_f32 v144, v24, v25
	v_cvt_pk_bf16_f32 v145, v26, v27
	global_store_dwordx4 v[146:147], v[142:145], off
	v_lshl_add_u64 v[146:147], s[0:1], 0, v[176:177]
	v_or_b32_e32 v176, s2, v148
	v_cvt_pk_bf16_f32 v142, v20, v21
	v_cvt_pk_bf16_f32 v143, v22, v23
	v_cvt_pk_bf16_f32 v144, v16, v17
	v_cvt_pk_bf16_f32 v145, v18, v19
	global_store_dwordx4 v[146:147], v[142:145], off
	v_lshl_add_u64 v[146:147], s[0:1], 0, v[176:177]
	v_or_b32_e32 v176, s4, v148
	v_cvt_pk_bf16_f32 v142, v12, v13
	v_cvt_pk_bf16_f32 v143, v14, v15
	v_cvt_pk_bf16_f32 v144, v8, v9
	v_cvt_pk_bf16_f32 v145, v10, v11
	global_store_dwordx4 v[146:147], v[142:145], off
	v_lshl_add_u64 v[146:147], s[0:1], 0, v[176:177]
	s_mov_b64 s[0:1], 0
	v_cvt_pk_bf16_f32 v142, v4, v5
	v_cvt_pk_bf16_f32 v143, v6, v7
	v_cvt_pk_bf16_f32 v144, v0, v1
	v_cvt_pk_bf16_f32 v145, v2, v3
	global_store_dwordx4 v[146:147], v[142:145], off
; DI u32x4 pk8(const f32x4& v0, const f32x4& v1) { u32x4 w; w.x = cvt_pk_bf16(v0[0], v0[1]); w.y = cvt_pk_bf16(v0[2], v0[3]); w.z = cvt_pk_bf16(v1[0], v1[1]); w.w = cvt_pk_bf16(v1[2], v1[3]); return w; }
;   DI void epi(const Acc& acc, const Unit& u, int wr, int wc, int fr, int fq, LAS unsigned char* lds) const {
;     ...
;       const int tl0 = u.pn * 256 + wc * 32 + 8 * fq;
; #pragma unroll
;       for (int m = 0; m < 4; ++m) {
;         const int d = wr * 64 + m * 16 + fr;
; #pragma unroll
;         for (int bj = 0; bj < 2; ++bj) {
;           const int tl = tl0 + bj * 128; const int pos = tok_pos(rb + tl);
;           const unsigned to = (unsigned)(d * 4096 + pos) * 4u; const f32x4 c0 = ldf4(cosRT, to), c1 = ldf4(cosRT, to + 16u);
;           const f32x4 s0 = ldf4(sinRT, to), s1 = ldf4(sinRT, to + 16u);
;           const f32x4 a0 = acc[0][bj][m][0], a1 = acc[0][bj][m][1], b0 = acc[1][bj][m][0], b1 = acc[1][bj][m][1];
;           const f32x4 x0 = (a0 * c0 - b0 * s0) * 0.0625f, x1 = (a1 * c1 - b1 * s1) * 0.0625f, y0 = (b0 * c0 + a0 * s0) * 0.0625f, y1 = (b1 * c1 + a1 * s1) * 0.0625f;
;           const unsigned ro = (unsigned)((tl >> 7) * 4 + u.pm) * 65536u + (unsigned)(d >> 5) * 8192u + (unsigned)((tl & 127) >> 4) * 1024u + (unsigned)((tl >> 3) & 1) * 512u + (unsigned)(d & 31) * 16u;
;           st16(kT, ro, pk8(x0, x1));
;           st16(kT, ro + 4u * 8192u, pk8(y0, y1));
;           __builtin_amdgcn_sched_barrier(0);
;         }
.LBB0_137:
	s_andn2_b64 vcc, exec, s[0:1]
	s_cbranch_vccnz .LBB0_139
	v_lshl_or_b32 v151, s26, 8, v156
	v_add_u32_e32 v142, s34, v151
	v_cmp_gt_i32_e32 vcc, s55, v142
	v_mov_b32_e32 v143, 0xf78
	v_mov_b32_e32 v144, 0x778
	v_cndmask_b32_e32 v143, v143, v144, vcc
	v_and_b32_e32 v142, v143, v142
	s_add_u32 s4, s12, 0x3540000
	v_lshlrev_b32_e32 v150, 2, v142
	s_addc_u32 s5, s13, 0
	v_or_b32_e32 v176, v150, v158
	s_add_u32 s0, s12, 0x3740000
	v_or_b32_e32 v174, 16, v176
	v_mov_b32_e32 v175, v177
	s_addc_u32 s1, s13, 0
	v_lshl_add_u64 v[142:143], s[4:5], 0, v[176:177]
	v_lshl_add_u64 v[146:147], s[4:5], 0, v[174:175]
	global_load_dwordx4 v[142:145], v[142:143], off
	v_lshl_add_u64 v[174:175], s[0:1], 0, v[174:175]
	global_load_dwordx4 v[178:181], v[146:147], off
	v_lshl_add_u64 v[146:147], s[0:1], 0, v[176:177]
	global_load_dwordx4 v[146:149], v[146:147], off
	s_lshl_b32 s2, s26, 3
	global_load_dwordx4 v[182:185], v[174:175], off
	s_add_i32 s2, s2, s53
	s_lshl_b32 s2, s2, 16
	v_add_u32_e32 v176, s2, v159
	s_waitcnt vmcnt(0) lgkmcnt(0)
	v_pk_mul_f32 v[174:175], v[62:63], v[148:149]
	v_pk_mul_f32 v[186:187], v[60:61], v[146:147]
	v_pk_fma_f32 v[174:175], v[126:127], v[144:145], v[174:175] neg_lo:[0,0,1] neg_hi:[0,0,1]
	v_pk_mul_f32 v[148:149], v[126:127], v[148:149]
	v_pk_mul_f32 v[146:147], v[124:125], v[146:147]
	v_pk_fma_f32 v[186:187], v[124:125], v[142:143], v[186:187] neg_lo:[0,0,1] neg_hi:[0,0,1]
	v_pk_mul_f32 v[174:175], v[174:175], s[80:81] op_sel_hi:[1,0]
	v_pk_mul_f32 v[188:189], v[58:59], v[184:185]
	v_pk_mul_f32 v[190:191], v[56:57], v[182:183]
	v_pk_fma_f32 v[144:145], v[62:63], v[144:145], v[148:149]
	v_pk_fma_f32 v[146:147], v[60:61], v[142:143], v[146:147]
	v_pk_mul_f32 v[148:149], v[120:121], v[182:183]
	v_pk_mul_f32 v[186:187], v[186:187], s[80:81] op_sel_hi:[1,0]
	v_pk_fma_f32 v[188:189], v[122:123], v[180:181], v[188:189] neg_lo:[0,0,1] neg_hi:[0,0,1]
	v_pk_fma_f32 v[190:191], v[120:121], v[178:179], v[190:191] neg_lo:[0,0,1] neg_hi:[0,0,1]
	v_pk_mul_f32 v[142:143], v[144:145], s[80:81] op_sel_hi:[1,0]
	v_pk_mul_f32 v[146:147], v[146:147], s[80:81] op_sel_hi:[1,0]
	v_pk_mul_f32 v[144:145], v[122:123], v[184:185]
	v_pk_fma_f32 v[148:149], v[56:57], v[178:179], v[148:149]
	v_cvt_pk_bf16_f32 v178, v186, v187
	v_cvt_pk_bf16_f32 v179, v174, v175
	v_lshl_add_u64 v[174:175], s[24:25], 0, v[176:177]
	v_add_u32_e32 v176, 0x8000, v176
	v_pk_mul_f32 v[188:189], v[188:189], s[80:81] op_sel_hi:[1,0]
	v_pk_mul_f32 v[190:191], v[190:191], s[80:81] op_sel_hi:[1,0]
	v_pk_fma_f32 v[144:145], v[58:59], v[180:181], v[144:145]
	v_pk_mul_f32 v[148:149], v[148:149], s[80:81] op_sel_hi:[1,0]
	v_cvt_pk_bf16_f32 v180, v190, v191
	v_cvt_pk_bf16_f32 v181, v188, v189
	global_store_dwordx4 v[174:175], v[178:181], off
	v_cvt_pk_bf16_f32 v146, v146, v147
	v_cvt_pk_bf16_f32 v147, v142, v143
	v_lshl_add_u64 v[142:143], s[24:25], 0, v[176:177]
	v_pk_mul_f32 v[144:145], v[144:145], s[80:81] op_sel_hi:[1,0]
	v_cvt_pk_bf16_f32 v148, v148, v149
	s_nop 0
	v_cvt_pk_bf16_f32 v149, v144, v145
	global_store_dwordx4 v[142:143], v[146:149], off
	v_or_b32_e32 v194, 0x80, v151
	v_add_u32_e32 v142, s34, v194
	v_cmp_gt_i32_e32 vcc, s55, v142
	v_mov_b32_e32 v143, 0xff8
	v_mov_b32_e32 v144, 0x7f8
	v_cndmask_b32_e32 v143, v143, v144, vcc
	v_and_b32_e32 v142, v143, v142
	v_lshlrev_b32_e32 v151, 2, v142
	v_or_b32_e32 v176, v151, v158
	v_or_b32_e32 v174, 16, v176
	v_mov_b32_e32 v175, v177
	v_lshl_add_u64 v[142:143], s[4:5], 0, v[176:177]
	v_lshl_add_u64 v[146:147], s[4:5], 0, v[174:175]
	global_load_dwordx4 v[142:145], v[142:143], off
	v_lshl_add_u64 v[174:175], s[0:1], 0, v[174:175]
	global_load_dwordx4 v[178:181], v[146:147], off
	v_lshl_add_u64 v[146:147], s[0:1], 0, v[176:177]
	global_load_dwordx4 v[146:149], v[146:147], off
	s_nop 0
	global_load_dwordx4 v[182:185], v[174:175], off
	s_waitcnt vmcnt(0) lgkmcnt(0)
	v_pk_mul_f32 v[174:175], v[54:55], v[148:149]
	s_nop 0
	v_pk_fma_f32 v[174:175], v[118:119], v[144:145], v[174:175] neg_lo:[0,0,1] neg_hi:[0,0,1]
	v_pk_mul_f32 v[186:187], v[52:53], v[146:147]
	v_pk_mul_f32 v[188:189], v[174:175], s[80:81] op_sel_hi:[1,0]
	v_pk_mul_f32 v[174:175], v[50:51], v[184:185]
	v_pk_mul_f32 v[148:149], v[118:119], v[148:149]
	v_pk_fma_f32 v[174:175], v[114:115], v[180:181], v[174:175] neg_lo:[0,0,1] neg_hi:[0,0,1]
	v_pk_mul_f32 v[146:147], v[116:117], v[146:147]
	v_pk_mul_f32 v[192:193], v[174:175], s[80:81] op_sel_hi:[1,0]
	v_lshrrev_b32_e32 v174, 5, v194
	v_and_b32_e32 v174, 0xfffc, v174
	v_add_lshl_u32 v174, v174, s53, 16
	v_pk_mul_f32 v[190:191], v[48:49], v[182:183]
	v_pk_fma_f32 v[144:145], v[54:55], v[144:145], v[148:149]
	v_pk_fma_f32 v[146:147], v[52:53], v[142:143], v[146:147]
	v_pk_mul_f32 v[148:149], v[112:113], v[182:183]
	v_add_u32_e32 v176, v174, v159
	v_pk_fma_f32 v[186:187], v[116:117], v[142:143], v[186:187] neg_lo:[0,0,1] neg_hi:[0,0,1]
	v_pk_fma_f32 v[190:191], v[112:113], v[178:179], v[190:191] neg_lo:[0,0,1] neg_hi:[0,0,1]
	v_pk_mul_f32 v[142:143], v[144:145], s[80:81] op_sel_hi:[1,0]
	v_pk_mul_f32 v[146:147], v[146:147], s[80:81] op_sel_hi:[1,0]
	v_pk_mul_f32 v[144:145], v[114:115], v[184:185]
	v_pk_fma_f32 v[148:149], v[48:49], v[178:179], v[148:149]
	v_lshl_add_u64 v[182:183], s[24:25], 0, v[176:177]
	v_add_u32_e32 v176, 0x8000, v176
	v_pk_mul_f32 v[186:187], v[186:187], s[80:81] op_sel_hi:[1,0]
	v_pk_mul_f32 v[190:191], v[190:191], s[80:81] op_sel_hi:[1,0]
	v_pk_fma_f32 v[144:145], v[50:51], v[180:181], v[144:145]
	v_pk_mul_f32 v[148:149], v[148:149], s[80:81] op_sel_hi:[1,0]
	v_cvt_pk_bf16_f32 v178, v186, v187
	v_cvt_pk_bf16_f32 v179, v188, v189
	v_cvt_pk_bf16_f32 v180, v190, v191
	v_cvt_pk_bf16_f32 v181, v192, v193
	global_store_dwordx4 v[182:183], v[178:181], off
	v_cvt_pk_bf16_f32 v146, v146, v147
	v_cvt_pk_bf16_f32 v147, v142, v143
	v_lshl_add_u64 v[142:143], s[24:25], 0, v[176:177]
	v_pk_mul_f32 v[144:145], v[144:145], s[80:81] op_sel_hi:[1,0]
	v_cvt_pk_bf16_f32 v148, v148, v149
	s_nop 0
	v_cvt_pk_bf16_f32 v149, v144, v145
	global_store_dwordx4 v[142:143], v[146:149], off
	v_or_b32_e32 v176, v150, v160
	v_or_b32_e32 v182, 16, v176
	v_mov_b32_e32 v183, v177
	v_lshl_add_u64 v[142:143], s[4:5], 0, v[176:177]
	v_lshl_add_u64 v[146:147], s[4:5], 0, v[182:183]
	global_load_dwordx4 v[142:145], v[142:143], off
	v_lshl_add_u64 v[182:183], s[0:1], 0, v[182:183]
	global_load_dwordx4 v[178:181], v[146:147], off
	v_lshl_add_u64 v[146:147], s[0:1], 0, v[176:177]
	global_load_dwordx4 v[146:149], v[146:147], off
	v_add_u32_e32 v176, s2, v161
	global_load_dwordx4 v[182:185], v[182:183], off
	s_waitcnt vmcnt(0) lgkmcnt(0)
; DI u32x4 pk8(const f32x4& v0, const f32x4& v1) { u32x4 w; w.x = cvt_pk_bf16(v0[0], v0[1]); w.y = cvt_pk_bf16(v0[2], v0[3]); w.z = cvt_pk_bf16(v1[0], v1[1]); w.w = cvt_pk_bf16(v1[2], v1[3]); return w; }
;   DI void epi(const Acc& acc, const Unit& u, int wr, int wc, int fr, int fq, LAS unsigned char* lds) const {
;     ...
;       const int tl0 = u.pn * 256 + wc * 32 + 8 * fq;
; #pragma unroll
;       for (int m = 0; m < 4; ++m) {
;         const int d = wr * 64 + m * 16 + fr;
; #pragma unroll
;         for (int bj = 0; bj < 2; ++bj) {
;           const int tl = tl0 + bj * 128; const int pos = tok_pos(rb + tl);
;           const unsigned to = (unsigned)(d * 4096 + pos) * 4u; const f32x4 c0 = ldf4(cosRT, to), c1 = ldf4(cosRT, to + 16u);
;           const f32x4 s0 = ldf4(sinRT, to), s1 = ldf4(sinRT, to + 16u);
;           const f32x4 a0 = acc[0][bj][m][0], a1 = acc[0][bj][m][1], b0 = acc[1][bj][m][0], b1 = acc[1][bj][m][1];
;           const f32x4 x0 = (a0 * c0 - b0 * s0) * 0.0625f, x1 = (a1 * c1 - b1 * s1) * 0.0625f, y0 = (b0 * c0 + a0 * s0) * 0.0625f, y1 = (b1 * c1 + a1 * s1) * 0.0625f;
;           const unsigned ro = (unsigned)((tl >> 7) * 4 + u.pm) * 65536u + (unsigned)(d >> 5) * 8192u + (unsigned)((tl & 127) >> 4) * 1024u + (unsigned)((tl >> 3) & 1) * 512u + (unsigned)(d & 31) * 16u;
;           st16(kT, ro, pk8(x0, x1));
;           st16(kT, ro + 4u * 8192u, pk8(y0, y1));
;           __builtin_amdgcn_sched_barrier(0);
;         }
	v_pk_mul_f32 v[186:187], v[46:47], v[148:149]
	v_pk_mul_f32 v[188:189], v[44:45], v[146:147]
	v_pk_mul_f32 v[148:149], v[110:111], v[148:149]
	v_pk_mul_f32 v[146:147], v[108:109], v[146:147]
	v_pk_fma_f32 v[186:187], v[110:111], v[144:145], v[186:187] neg_lo:[0,0,1] neg_hi:[0,0,1]
	v_pk_mul_f32 v[190:191], v[42:43], v[184:185]
	v_pk_mul_f32 v[192:193], v[40:41], v[182:183]
	v_pk_fma_f32 v[144:145], v[46:47], v[144:145], v[148:149]
	v_pk_fma_f32 v[146:147], v[44:45], v[142:143], v[146:147]
	v_pk_mul_f32 v[148:149], v[104:105], v[182:183]
	v_pk_fma_f32 v[188:189], v[108:109], v[142:143], v[188:189] neg_lo:[0,0,1] neg_hi:[0,0,1]
	v_pk_fma_f32 v[190:191], v[106:107], v[180:181], v[190:191] neg_lo:[0,0,1] neg_hi:[0,0,1]
	v_pk_fma_f32 v[192:193], v[104:105], v[178:179], v[192:193] neg_lo:[0,0,1] neg_hi:[0,0,1]
	v_pk_mul_f32 v[142:143], v[144:145], s[80:81] op_sel_hi:[1,0]
	v_pk_mul_f32 v[146:147], v[146:147], s[80:81] op_sel_hi:[1,0]
	v_pk_mul_f32 v[144:145], v[106:107], v[184:185]
	v_pk_fma_f32 v[148:149], v[40:41], v[178:179], v[148:149]
	v_lshl_add_u64 v[182:183], s[24:25], 0, v[176:177]
	v_add_u32_e32 v176, 0x8000, v176
	v_pk_mul_f32 v[186:187], v[186:187], s[80:81] op_sel_hi:[1,0]
	v_pk_mul_f32 v[188:189], v[188:189], s[80:81] op_sel_hi:[1,0]
	v_pk_mul_f32 v[190:191], v[190:191], s[80:81] op_sel_hi:[1,0]
	v_pk_mul_f32 v[192:193], v[192:193], s[80:81] op_sel_hi:[1,0]
	v_pk_fma_f32 v[144:145], v[42:43], v[180:181], v[144:145]
	v_pk_mul_f32 v[148:149], v[148:149], s[80:81] op_sel_hi:[1,0]
	v_cvt_pk_bf16_f32 v178, v188, v189
	v_cvt_pk_bf16_f32 v179, v186, v187
	v_cvt_pk_bf16_f32 v180, v192, v193
	v_cvt_pk_bf16_f32 v181, v190, v191
	global_store_dwordx4 v[182:183], v[178:181], off
	v_cvt_pk_bf16_f32 v146, v146, v147
	v_cvt_pk_bf16_f32 v147, v142, v143
	v_lshl_add_u64 v[142:143], s[24:25], 0, v[176:177]
	v_pk_mul_f32 v[144:145], v[144:145], s[80:81] op_sel_hi:[1,0]
	v_cvt_pk_bf16_f32 v148, v148, v149
	s_nop 0
	v_cvt_pk_bf16_f32 v149, v144, v145
	global_store_dwordx4 v[142:143], v[146:149], off
	v_or_b32_e32 v176, v151, v160
	v_or_b32_e32 v182, 16, v176
	v_mov_b32_e32 v183, v177
	v_lshl_add_u64 v[142:143], s[4:5], 0, v[176:177]
	v_lshl_add_u64 v[146:147], s[4:5], 0, v[182:183]
	global_load_dwordx4 v[142:145], v[142:143], off
	v_lshl_add_u64 v[182:183], s[0:1], 0, v[182:183]
	global_load_dwordx4 v[178:181], v[146:147], off
	v_lshl_add_u64 v[146:147], s[0:1], 0, v[176:177]
	global_load_dwordx4 v[146:149], v[146:147], off
	v_add_u32_e32 v176, v174, v161
	global_load_dwordx4 v[182:185], v[182:183], off
	s_waitcnt vmcnt(0) lgkmcnt(0)
	v_pk_mul_f32 v[186:187], v[38:39], v[148:149]
	v_pk_mul_f32 v[188:189], v[36:37], v[146:147]
	v_pk_mul_f32 v[148:149], v[102:103], v[148:149]
	v_pk_mul_f32 v[146:147], v[100:101], v[146:147]
	v_pk_fma_f32 v[186:187], v[102:103], v[144:145], v[186:187] neg_lo:[0,0,1] neg_hi:[0,0,1]
	v_pk_mul_f32 v[190:191], v[34:35], v[184:185]
	v_pk_mul_f32 v[192:193], v[32:33], v[182:183]
	v_pk_fma_f32 v[144:145], v[38:39], v[144:145], v[148:149]
	v_pk_fma_f32 v[146:147], v[36:37], v[142:143], v[146:147]
	v_pk_mul_f32 v[148:149], v[96:97], v[182:183]
	v_pk_fma_f32 v[188:189], v[100:101], v[142:143], v[188:189] neg_lo:[0,0,1] neg_hi:[0,0,1]
	v_pk_fma_f32 v[190:191], v[98:99], v[180:181], v[190:191] neg_lo:[0,0,1] neg_hi:[0,0,1]
	v_pk_fma_f32 v[192:193], v[96:97], v[178:179], v[192:193] neg_lo:[0,0,1] neg_hi:[0,0,1]
	v_pk_mul_f32 v[142:143], v[144:145], s[80:81] op_sel_hi:[1,0]
	v_pk_mul_f32 v[146:147], v[146:147], s[80:81] op_sel_hi:[1,0]
	v_pk_mul_f32 v[144:145], v[98:99], v[184:185]
	v_pk_fma_f32 v[148:149], v[32:33], v[178:179], v[148:149]
	v_lshl_add_u64 v[182:183], s[24:25], 0, v[176:177]
	v_add_u32_e32 v176, 0x8000, v176
	v_pk_mul_f32 v[186:187], v[186:187], s[80:81] op_sel_hi:[1,0]
	v_pk_mul_f32 v[188:189], v[188:189], s[80:81] op_sel_hi:[1,0]
	v_pk_mul_f32 v[190:191], v[190:191], s[80:81] op_sel_hi:[1,0]
	v_pk_mul_f32 v[192:193], v[192:193], s[80:81] op_sel_hi:[1,0]
	v_pk_fma_f32 v[144:145], v[34:35], v[180:181], v[144:145]
	v_pk_mul_f32 v[148:149], v[148:149], s[80:81] op_sel_hi:[1,0]
	v_cvt_pk_bf16_f32 v178, v188, v189
	v_cvt_pk_bf16_f32 v179, v186, v187
	v_cvt_pk_bf16_f32 v180, v192, v193
	v_cvt_pk_bf16_f32 v181, v190, v191
	global_store_dwordx4 v[182:183], v[178:181], off
	v_cvt_pk_bf16_f32 v146, v146, v147
	v_cvt_pk_bf16_f32 v147, v142, v143
	v_lshl_add_u64 v[142:143], s[24:25], 0, v[176:177]
	v_pk_mul_f32 v[144:145], v[144:145], s[80:81] op_sel_hi:[1,0]
	v_cvt_pk_bf16_f32 v148, v148, v149
	s_nop 0
	v_cvt_pk_bf16_f32 v149, v144, v145
	global_store_dwordx4 v[142:143], v[146:149], off
	v_or_b32_e32 v176, v150, v162
	v_or_b32_e32 v182, 16, v176
	v_mov_b32_e32 v183, v177
	v_lshl_add_u64 v[142:143], s[4:5], 0, v[176:177]
	v_lshl_add_u64 v[146:147], s[4:5], 0, v[182:183]
	global_load_dwordx4 v[142:145], v[142:143], off
	v_lshl_add_u64 v[182:183], s[0:1], 0, v[182:183]
	global_load_dwordx4 v[178:181], v[146:147], off
	v_lshl_add_u64 v[146:147], s[0:1], 0, v[176:177]
	global_load_dwordx4 v[146:149], v[146:147], off
	v_add_u32_e32 v176, s2, v163
	global_load_dwordx4 v[182:185], v[182:183], off
	s_waitcnt vmcnt(0) lgkmcnt(0)
; DI u32x4 pk8(const f32x4& v0, const f32x4& v1) { u32x4 w; w.x = cvt_pk_bf16(v0[0], v0[1]); w.y = cvt_pk_bf16(v0[2], v0[3]); w.z = cvt_pk_bf16(v1[0], v1[1]); w.w = cvt_pk_bf16(v1[2], v1[3]); return w; }
;   DI void epi(const Acc& acc, const Unit& u, int wr, int wc, int fr, int fq, LAS unsigned char* lds) const {
;     ...
;       const int tl0 = u.pn * 256 + wc * 32 + 8 * fq;
; #pragma unroll
;       for (int m = 0; m < 4; ++m) {
;         const int d = wr * 64 + m * 16 + fr;
; #pragma unroll
;         for (int bj = 0; bj < 2; ++bj) {
;           const int tl = tl0 + bj * 128; const int pos = tok_pos(rb + tl);
;           const unsigned to = (unsigned)(d * 4096 + pos) * 4u; const f32x4 c0 = ldf4(cosRT, to), c1 = ldf4(cosRT, to + 16u);
;           const f32x4 s0 = ldf4(sinRT, to), s1 = ldf4(sinRT, to + 16u);
;           const f32x4 a0 = acc[0][bj][m][0], a1 = acc[0][bj][m][1], b0 = acc[1][bj][m][0], b1 = acc[1][bj][m][1];
;           const f32x4 x0 = (a0 * c0 - b0 * s0) * 0.0625f, x1 = (a1 * c1 - b1 * s1) * 0.0625f, y0 = (b0 * c0 + a0 * s0) * 0.0625f, y1 = (b1 * c1 + a1 * s1) * 0.0625f;
;           const unsigned ro = (unsigned)((tl >> 7) * 4 + u.pm) * 65536u + (unsigned)(d >> 5) * 8192u + (unsigned)((tl & 127) >> 4) * 1024u + (unsigned)((tl >> 3) & 1) * 512u + (unsigned)(d & 31) * 16u;
;           st16(kT, ro, pk8(x0, x1));
;           st16(kT, ro + 4u * 8192u, pk8(y0, y1));
;           __builtin_amdgcn_sched_barrier(0);
;         }
	v_pk_mul_f32 v[186:187], v[30:31], v[148:149]
	v_pk_mul_f32 v[188:189], v[28:29], v[146:147]
	v_pk_mul_f32 v[148:149], v[94:95], v[148:149]
	v_pk_mul_f32 v[146:147], v[92:93], v[146:147]
	v_pk_fma_f32 v[186:187], v[94:95], v[144:145], v[186:187] neg_lo:[0,0,1] neg_hi:[0,0,1]
	v_pk_mul_f32 v[190:191], v[26:27], v[184:185]
	v_pk_mul_f32 v[192:193], v[24:25], v[182:183]
	v_pk_fma_f32 v[144:145], v[30:31], v[144:145], v[148:149]
	v_pk_fma_f32 v[146:147], v[28:29], v[142:143], v[146:147]
	v_pk_mul_f32 v[148:149], v[88:89], v[182:183]
	v_pk_fma_f32 v[188:189], v[92:93], v[142:143], v[188:189] neg_lo:[0,0,1] neg_hi:[0,0,1]
	v_pk_fma_f32 v[190:191], v[90:91], v[180:181], v[190:191] neg_lo:[0,0,1] neg_hi:[0,0,1]
	v_pk_fma_f32 v[192:193], v[88:89], v[178:179], v[192:193] neg_lo:[0,0,1] neg_hi:[0,0,1]
	v_pk_mul_f32 v[142:143], v[144:145], s[80:81] op_sel_hi:[1,0]
	v_pk_mul_f32 v[146:147], v[146:147], s[80:81] op_sel_hi:[1,0]
	v_pk_mul_f32 v[144:145], v[90:91], v[184:185]
	v_pk_fma_f32 v[148:149], v[24:25], v[178:179], v[148:149]
	v_lshl_add_u64 v[182:183], s[24:25], 0, v[176:177]
	v_add_u32_e32 v176, 0x8000, v176
	v_pk_mul_f32 v[186:187], v[186:187], s[80:81] op_sel_hi:[1,0]
	v_pk_mul_f32 v[188:189], v[188:189], s[80:81] op_sel_hi:[1,0]
	v_pk_mul_f32 v[190:191], v[190:191], s[80:81] op_sel_hi:[1,0]
	v_pk_mul_f32 v[192:193], v[192:193], s[80:81] op_sel_hi:[1,0]
	v_pk_fma_f32 v[144:145], v[26:27], v[180:181], v[144:145]
	v_pk_mul_f32 v[148:149], v[148:149], s[80:81] op_sel_hi:[1,0]
	v_cvt_pk_bf16_f32 v178, v188, v189
	v_cvt_pk_bf16_f32 v179, v186, v187
	v_cvt_pk_bf16_f32 v180, v192, v193
	v_cvt_pk_bf16_f32 v181, v190, v191
	global_store_dwordx4 v[182:183], v[178:181], off
	v_cvt_pk_bf16_f32 v146, v146, v147
	v_cvt_pk_bf16_f32 v147, v142, v143
	v_lshl_add_u64 v[142:143], s[24:25], 0, v[176:177]
	v_pk_mul_f32 v[144:145], v[144:145], s[80:81] op_sel_hi:[1,0]
	v_cvt_pk_bf16_f32 v148, v148, v149
	s_nop 0
	v_cvt_pk_bf16_f32 v149, v144, v145
	global_store_dwordx4 v[142:143], v[146:149], off
	v_or_b32_e32 v176, v151, v162
	v_or_b32_e32 v182, 16, v176
	v_mov_b32_e32 v183, v177
	v_lshl_add_u64 v[142:143], s[4:5], 0, v[176:177]
	v_lshl_add_u64 v[146:147], s[4:5], 0, v[182:183]
	global_load_dwordx4 v[142:145], v[142:143], off
	v_lshl_add_u64 v[182:183], s[0:1], 0, v[182:183]
	global_load_dwordx4 v[178:181], v[146:147], off
	v_lshl_add_u64 v[146:147], s[0:1], 0, v[176:177]
	global_load_dwordx4 v[146:149], v[146:147], off
	v_add_u32_e32 v176, v174, v163
	global_load_dwordx4 v[182:185], v[182:183], off
	s_waitcnt vmcnt(0) lgkmcnt(0)
	v_pk_mul_f32 v[186:187], v[22:23], v[148:149]
	v_pk_mul_f32 v[188:189], v[20:21], v[146:147]
	v_pk_mul_f32 v[148:149], v[86:87], v[148:149]
	v_pk_mul_f32 v[146:147], v[84:85], v[146:147]
	v_pk_fma_f32 v[186:187], v[86:87], v[144:145], v[186:187] neg_lo:[0,0,1] neg_hi:[0,0,1]
	v_pk_mul_f32 v[190:191], v[18:19], v[184:185]
	v_pk_mul_f32 v[192:193], v[16:17], v[182:183]
	v_pk_fma_f32 v[144:145], v[22:23], v[144:145], v[148:149]
	v_pk_fma_f32 v[146:147], v[20:21], v[142:143], v[146:147]
	v_pk_mul_f32 v[148:149], v[80:81], v[182:183]
	v_pk_fma_f32 v[188:189], v[84:85], v[142:143], v[188:189] neg_lo:[0,0,1] neg_hi:[0,0,1]
	v_pk_fma_f32 v[190:191], v[82:83], v[180:181], v[190:191] neg_lo:[0,0,1] neg_hi:[0,0,1]
	v_pk_fma_f32 v[192:193], v[80:81], v[178:179], v[192:193] neg_lo:[0,0,1] neg_hi:[0,0,1]
	v_pk_mul_f32 v[142:143], v[144:145], s[80:81] op_sel_hi:[1,0]
	v_pk_mul_f32 v[146:147], v[146:147], s[80:81] op_sel_hi:[1,0]
	v_pk_mul_f32 v[144:145], v[82:83], v[184:185]
	v_pk_fma_f32 v[148:149], v[16:17], v[178:179], v[148:149]
	v_lshl_add_u64 v[182:183], s[24:25], 0, v[176:177]
	v_add_u32_e32 v176, 0x8000, v176
	v_pk_mul_f32 v[186:187], v[186:187], s[80:81] op_sel_hi:[1,0]
	v_pk_mul_f32 v[188:189], v[188:189], s[80:81] op_sel_hi:[1,0]
	v_pk_mul_f32 v[190:191], v[190:191], s[80:81] op_sel_hi:[1,0]
	v_pk_mul_f32 v[192:193], v[192:193], s[80:81] op_sel_hi:[1,0]
	v_pk_fma_f32 v[144:145], v[18:19], v[180:181], v[144:145]
	v_pk_mul_f32 v[148:149], v[148:149], s[80:81] op_sel_hi:[1,0]
	v_cvt_pk_bf16_f32 v178, v188, v189
	v_cvt_pk_bf16_f32 v179, v186, v187
	v_cvt_pk_bf16_f32 v180, v192, v193
	v_cvt_pk_bf16_f32 v181, v190, v191
	global_store_dwordx4 v[182:183], v[178:181], off
	v_cvt_pk_bf16_f32 v146, v146, v147
	v_cvt_pk_bf16_f32 v147, v142, v143
	v_lshl_add_u64 v[142:143], s[24:25], 0, v[176:177]
	v_pk_mul_f32 v[144:145], v[144:145], s[80:81] op_sel_hi:[1,0]
	v_cvt_pk_bf16_f32 v148, v148, v149
	s_nop 0
	v_cvt_pk_bf16_f32 v149, v144, v145
	global_store_dwordx4 v[142:143], v[146:149], off
	v_or_b32_e32 v176, v150, v164
	v_or_b32_e32 v182, 16, v176
	v_mov_b32_e32 v183, v177
	v_lshl_add_u64 v[142:143], s[4:5], 0, v[176:177]
	v_lshl_add_u64 v[146:147], s[4:5], 0, v[182:183]
	global_load_dwordx4 v[142:145], v[142:143], off
	v_lshl_add_u64 v[182:183], s[0:1], 0, v[182:183]
	global_load_dwordx4 v[178:181], v[146:147], off
	v_lshl_add_u64 v[146:147], s[0:1], 0, v[176:177]
	global_load_dwordx4 v[146:149], v[146:147], off
	v_add_u32_e32 v176, s2, v165
	global_load_dwordx4 v[182:185], v[182:183], off
	s_waitcnt vmcnt(0) lgkmcnt(0)
; DI u32x4 pk8(const f32x4& v0, const f32x4& v1) { u32x4 w; w.x = cvt_pk_bf16(v0[0], v0[1]); w.y = cvt_pk_bf16(v0[2], v0[3]); w.z = cvt_pk_bf16(v1[0], v1[1]); w.w = cvt_pk_bf16(v1[2], v1[3]); return w; }
;   DI void epi(const Acc& acc, const Unit& u, int wr, int wc, int fr, int fq, LAS unsigned char* lds) const {
;     ...
;       const int tl0 = u.pn * 256 + wc * 32 + 8 * fq;
; #pragma unroll
;       for (int m = 0; m < 4; ++m) {
;         const int d = wr * 64 + m * 16 + fr;
; #pragma unroll
;         for (int bj = 0; bj < 2; ++bj) {
;           const int tl = tl0 + bj * 128; const int pos = tok_pos(rb + tl);
;           const unsigned to = (unsigned)(d * 4096 + pos) * 4u; const f32x4 c0 = ldf4(cosRT, to), c1 = ldf4(cosRT, to + 16u);
;           const f32x4 s0 = ldf4(sinRT, to), s1 = ldf4(sinRT, to + 16u);
;           const f32x4 a0 = acc[0][bj][m][0], a1 = acc[0][bj][m][1], b0 = acc[1][bj][m][0], b1 = acc[1][bj][m][1];
;           const f32x4 x0 = (a0 * c0 - b0 * s0) * 0.0625f, x1 = (a1 * c1 - b1 * s1) * 0.0625f, y0 = (b0 * c0 + a0 * s0) * 0.0625f, y1 = (b1 * c1 + a1 * s1) * 0.0625f;
;           const unsigned ro = (unsigned)((tl >> 7) * 4 + u.pm) * 65536u + (unsigned)(d >> 5) * 8192u + (unsigned)((tl & 127) >> 4) * 1024u + (unsigned)((tl >> 3) & 1) * 512u + (unsigned)(d & 31) * 16u;
;           st16(kT, ro, pk8(x0, x1));
;           st16(kT, ro + 4u * 8192u, pk8(y0, y1));
;           __builtin_amdgcn_sched_barrier(0);
;         }
	v_pk_mul_f32 v[186:187], v[14:15], v[148:149]
	v_pk_mul_f32 v[188:189], v[12:13], v[146:147]
	v_pk_mul_f32 v[148:149], v[78:79], v[148:149]
	v_pk_mul_f32 v[146:147], v[76:77], v[146:147]
	v_pk_fma_f32 v[186:187], v[78:79], v[144:145], v[186:187] neg_lo:[0,0,1] neg_hi:[0,0,1]
	v_pk_mul_f32 v[190:191], v[10:11], v[184:185]
	v_pk_mul_f32 v[192:193], v[8:9], v[182:183]
	v_pk_fma_f32 v[144:145], v[14:15], v[144:145], v[148:149]
	v_pk_fma_f32 v[146:147], v[12:13], v[142:143], v[146:147]
	v_pk_mul_f32 v[148:149], v[72:73], v[182:183]
	v_pk_fma_f32 v[188:189], v[76:77], v[142:143], v[188:189] neg_lo:[0,0,1] neg_hi:[0,0,1]
	v_pk_fma_f32 v[190:191], v[74:75], v[180:181], v[190:191] neg_lo:[0,0,1] neg_hi:[0,0,1]
	v_pk_fma_f32 v[192:193], v[72:73], v[178:179], v[192:193] neg_lo:[0,0,1] neg_hi:[0,0,1]
	v_pk_mul_f32 v[142:143], v[144:145], s[80:81] op_sel_hi:[1,0]
	v_pk_mul_f32 v[146:147], v[146:147], s[80:81] op_sel_hi:[1,0]
	v_pk_mul_f32 v[144:145], v[74:75], v[184:185]
	v_pk_fma_f32 v[148:149], v[8:9], v[178:179], v[148:149]
	v_lshl_add_u64 v[182:183], s[24:25], 0, v[176:177]
	v_add_u32_e32 v176, 0x8000, v176
	v_pk_mul_f32 v[186:187], v[186:187], s[80:81] op_sel_hi:[1,0]
	v_pk_mul_f32 v[188:189], v[188:189], s[80:81] op_sel_hi:[1,0]
	v_pk_mul_f32 v[190:191], v[190:191], s[80:81] op_sel_hi:[1,0]
	v_pk_mul_f32 v[192:193], v[192:193], s[80:81] op_sel_hi:[1,0]
	v_pk_fma_f32 v[144:145], v[10:11], v[180:181], v[144:145]
	v_pk_mul_f32 v[148:149], v[148:149], s[80:81] op_sel_hi:[1,0]
	v_cvt_pk_bf16_f32 v178, v188, v189
	v_cvt_pk_bf16_f32 v179, v186, v187
	v_cvt_pk_bf16_f32 v180, v192, v193
	v_cvt_pk_bf16_f32 v181, v190, v191
	global_store_dwordx4 v[182:183], v[178:181], off
	v_cvt_pk_bf16_f32 v146, v146, v147
	v_cvt_pk_bf16_f32 v147, v142, v143
	v_lshl_add_u64 v[142:143], s[24:25], 0, v[176:177]
	v_pk_mul_f32 v[144:145], v[144:145], s[80:81] op_sel_hi:[1,0]
	v_cvt_pk_bf16_f32 v148, v148, v149
	s_nop 0
	v_cvt_pk_bf16_f32 v149, v144, v145
	global_store_dwordx4 v[142:143], v[146:149], off
	v_or_b32_e32 v176, v151, v164
	s_nop 0
	v_or_b32_e32 v146, 16, v176
	v_mov_b32_e32 v147, v177
	v_lshl_add_u64 v[148:149], s[4:5], 0, v[146:147]
	v_lshl_add_u64 v[178:179], s[0:1], 0, v[176:177]
	v_lshl_add_u64 v[142:143], s[4:5], 0, v[176:177]
	global_load_dwordx4 v[148:151], v[148:149], off
	v_lshl_add_u64 v[146:147], s[0:1], 0, v[146:147]
	global_load_dwordx4 v[178:181], v[178:179], off
	v_add_u32_e32 v176, v174, v165
	global_load_dwordx4 v[142:145], v[142:143], off
	s_waitcnt vmcnt(0) lgkmcnt(0)
	v_pk_mul_f32 v[186:187], v[4:5], v[178:179]
	global_load_dwordx4 v[182:185], v[146:147], off
	v_pk_mul_f32 v[146:147], v[6:7], v[180:181]
	v_pk_mul_f32 v[178:179], v[68:69], v[178:179]
	v_pk_fma_f32 v[146:147], v[70:71], v[144:145], v[146:147] neg_lo:[0,0,1] neg_hi:[0,0,1]
	v_pk_fma_f32 v[186:187], v[68:69], v[142:143], v[186:187] neg_lo:[0,0,1] neg_hi:[0,0,1]
	v_pk_mul_f32 v[188:189], v[146:147], s[80:81] op_sel_hi:[1,0]
	v_pk_mul_f32 v[186:187], v[186:187], s[80:81] op_sel_hi:[1,0]
	s_waitcnt vmcnt(0) lgkmcnt(0)
	v_pk_mul_f32 v[146:147], v[2:3], v[184:185]
	s_nop 0
	v_pk_fma_f32 v[146:147], v[66:67], v[150:151], v[146:147] neg_lo:[0,0,1] neg_hi:[0,0,1]
	v_pk_mul_f32 v[190:191], v[0:1], v[182:183]
	v_pk_mul_f32 v[192:193], v[146:147], s[80:81] op_sel_hi:[1,0]
	v_pk_mul_f32 v[146:147], v[70:71], v[180:181]
	v_pk_fma_f32 v[190:191], v[64:65], v[148:149], v[190:191] neg_lo:[0,0,1] neg_hi:[0,0,1]
	v_pk_fma_f32 v[144:145], v[6:7], v[144:145], v[146:147]
	v_pk_fma_f32 v[146:147], v[4:5], v[142:143], v[178:179]
	v_pk_mul_f32 v[142:143], v[144:145], s[80:81] op_sel_hi:[1,0]
	v_pk_mul_f32 v[144:145], v[66:67], v[184:185]
	v_pk_mul_f32 v[178:179], v[64:65], v[182:183]
	v_pk_mul_f32 v[146:147], v[146:147], s[80:81] op_sel_hi:[1,0]
	v_pk_fma_f32 v[144:145], v[2:3], v[150:151], v[144:145]
	v_pk_fma_f32 v[148:149], v[0:1], v[148:149], v[178:179]
	v_lshl_add_u64 v[150:151], s[24:25], 0, v[176:177]
	v_add_u32_e32 v176, 0x8000, v176
	v_pk_mul_f32 v[190:191], v[190:191], s[80:81] op_sel_hi:[1,0]
	v_pk_mul_f32 v[148:149], v[148:149], s[80:81] op_sel_hi:[1,0]
	v_cvt_pk_bf16_f32 v178, v186, v187
	v_cvt_pk_bf16_f32 v179, v188, v189
	v_cvt_pk_bf16_f32 v180, v190, v191
	v_cvt_pk_bf16_f32 v181, v192, v193
	global_store_dwordx4 v[150:151], v[178:181], off
	v_cvt_pk_bf16_f32 v146, v146, v147
	v_cvt_pk_bf16_f32 v147, v142, v143
	v_lshl_add_u64 v[142:143], s[24:25], 0, v[176:177]
	v_pk_mul_f32 v[144:145], v[144:145], s[80:81] op_sel_hi:[1,0]
	v_cvt_pk_bf16_f32 v148, v148, v149
	s_nop 0
	v_cvt_pk_bf16_f32 v149, v144, v145
	global_store_dwordx4 v[142:143], v[146:149], off

; DI u32x4 pk8(const f32x4& v0, const f32x4& v1) { u32x4 w; w.x = cvt_pk_bf16(v0[0], v0[1]); w.y = cvt_pk_bf16(v0[2], v0[3]); w.z = cvt_pk_bf16(v1[0], v1[1]); w.w = cvt_pk_bf16(v1[2], v1[3]); return w; }
;   DI void epi(const Acc& acc, const Unit& u, int wr, int wc, int fr, int fq, LAS unsigned char* lds) const {
;     ...
;     if (u.seg == 0) {
;       const bool isq = u.pn < 4; const float sc = isq ? 1.0f : 0.0625f;
;       bf16_t* base = isq ? qr : kr; const int hd = isq ? u.pn : u.pn - 4;
;       const int d0 = wc * 32 + 8 * fq;
;       const unsigned fo = (unsigned)hd * 65536u + (unsigned)(d0 >> 4) * 1024u + (unsigned)((d0 >> 3) & 1) * 512u;
; #pragma unroll
;       for (int ai = 0; ai < 2; ++ai)
; #pragma unroll
;         for (int m = 0; m < 4; ++m) {
;           const int rl = u.pm * 256 + ai * 128 + wr * 64 + m * 16 + fr; const int pos = tok_pos(rb + rl);
;           const unsigned to = (unsigned)(pos * 128 + d0) * 4u; const f32x4 c0 = ldf4(cosR, to), c1 = ldf4(cosR, to + 16u);
;           const f32x4 s0 = ldf4(sinR, to), s1 = ldf4(sinR, to + 16u);
;           const f32x4 a0 = acc[ai][0][m][0], a1 = acc[ai][0][m][1], b0 = acc[ai][1][m][0], b1 = acc[ai][1][m][1];
;           const f32x4 x0 = (a0 * c0 - b0 * s0) * sc, x1 = (a1 * c1 - b1 * s1) * sc, y0 = (b0 * c0 + a0 * s0) * sc, y1 = (b1 * c1 + a1 * s1) * sc;
;           const unsigned ro = fo + (unsigned)(rl >> 7) * 262144u + (unsigned)((rl >> 5) & 3) * 16384u + (unsigned)(rl & 31) * 16u;
;           st16(base, ro, pk8(x0, x1));
;           st16(base, ro + 8192u, pk8(y0, y1));
;           if (!isq) {
;             float vx[8] = {x0[0], x0[1], x0[2], x0[3], x1[0], x1[1], x1[2], x1[3]}, vy[8] = {y0[0], y0[1], y0[2], y0[3], y1[0], y1[1], y1[2], y1[3]};
;             const int lane = fq * 16 + fr;
;             transpose8(vx, lane); transpose8(vy, lane);
;             const int tl = rl & ~7, dk = d0 + (fr & 7);
;             const unsigned kro = (unsigned)((tl >> 7) * 4 + hd) * 65536u + (unsigned)(dk >> 5) * 8192u + (unsigned)((tl & 127) >> 4) * 1024u + (unsigned)((tl >> 3) & 1) * 512u + (unsigned)(dk & 31) * 16u;
;             st16(kT, kro, pk8((f32x4){vx[0], vx[1], vx[2], vx[3]}, (f32x4){vx[4], vx[5], vx[6], vx[7]}));
;             st16(kT, kro + 4u * 8192u, pk8((f32x4){vy[0], vy[1], vy[2], vy[3]}, (f32x4){vy[4], vy[5], vy[6], vy[7]}));
;           }
;           __builtin_amdgcn_sched_barrier(0);
;         }
.LBB0_140:
	s_add_u32 s28, s12, 0x3140000
	s_addc_u32 s29, s13, 0
	s_add_u32 s30, s12, 0x3340000
	s_addc_u32 s31, s13, 0
	s_cmp_gt_i32 s26, 3
	s_cselect_b64 s[0:1], -1, 0
	s_add_i32 s54, s26, -4
	s_cmp_lt_i32 s26, 4
	s_cselect_b64 s[4:5], -1, 0
	s_and_b64 vcc, s[4:5], exec
	s_mov_b32 s2, 0x7e00000
	v_mov_b32_e32 v142, 0x3d800000
	s_cselect_b32 s2, s2, 0x9e00000
	v_cndmask_b32_e64 v142, v142, 1.0, s[4:5]
	s_cselect_b32 s4, s26, s54
	s_add_u32 s26, s12, s2
	s_addc_u32 s27, s13, 0
	s_lshl_b32 s2, s53, 8
	s_add_i32 s2, s2, s40
	v_or_b32_e32 v143, s2, v137
	v_add_u32_e32 v143, s34, v143
	v_cmp_gt_i32_e64 s[12:13], s55, v143
	v_mov_b32_e32 v144, 0xfcf
	v_mov_b32_e32 v145, 0x7cf
	v_cndmask_b32_e64 v144, v144, v145, s[12:13]
	v_and_b32_e32 v143, v144, v143
	v_lshl_or_b32 v176, v143, 9, v166
	v_lshl_add_u64 v[144:145], s[28:29], 0, v[176:177]
	global_load_dwordx4 v[178:181], v[144:145], off
	v_or_b32_e32 v144, 16, v176
	v_mov_b32_e32 v145, v177
	v_lshl_add_u64 v[146:147], s[28:29], 0, v[144:145]
	v_lshl_add_u64 v[144:145], s[30:31], 0, v[144:145]
	global_load_dwordx4 v[182:185], v[146:147], off
	global_load_dwordx4 v[190:193], v[144:145], off
	v_lshl_add_u64 v[146:147], s[30:31], 0, v[176:177]
	global_load_dwordx4 v[186:189], v[146:147], off
	v_lshl_or_b32 v174, s4, 16, v157
	s_lshl_b32 s4, s2, 11
	s_and_b32 s4, s4, 0xfffc0000
	s_waitcnt vmcnt(0) lgkmcnt(0)
	v_pk_mul_f32 v[148:149], v[112:113], v[190:191]
	s_nop 0
	v_pk_fma_f32 v[148:149], v[120:121], v[182:183], v[148:149] neg_lo:[0,0,1] neg_hi:[0,0,1]
	v_pk_mul_f32 v[144:145], v[118:119], v[188:189]
	v_pk_mul_f32 v[146:147], v[116:117], v[186:187]
	v_pk_fma_f32 v[144:145], v[126:127], v[180:181], v[144:145] neg_lo:[0,0,1] neg_hi:[0,0,1]
	v_pk_mul_f32 v[126:127], v[126:127], v[188:189]
	v_pk_fma_f32 v[146:147], v[124:125], v[178:179], v[146:147] neg_lo:[0,0,1] neg_hi:[0,0,1]
	v_pk_fma_f32 v[118:119], v[118:119], v[180:181], v[126:127]
	v_add_u32_e32 v126, s4, v174
	v_pk_mul_f32 v[150:151], v[142:143], v[146:147] op_sel_hi:[0,1]
	v_pk_mul_f32 v[146:147], v[114:115], v[192:193]
	v_or_b32_e32 v127, s46, v126
	v_pk_fma_f32 v[146:147], v[122:123], v[184:185], v[146:147] neg_lo:[0,0,1] neg_hi:[0,0,1]
	v_pk_mul_f32 v[124:125], v[124:125], v[186:187]
	v_pk_mul_f32 v[122:123], v[122:123], v[192:193]
	v_pk_mul_f32 v[120:121], v[120:121], v[190:191]
	v_or_b32_e32 v176, v127, v154
	v_pk_fma_f32 v[116:117], v[116:117], v[178:179], v[124:125]
	v_pk_fma_f32 v[114:115], v[114:115], v[184:185], v[122:123]
	v_pk_fma_f32 v[120:121], v[112:113], v[182:183], v[120:121]
	v_lshl_add_u64 v[124:125], s[26:27], 0, v[176:177]
	v_or_b32_e32 v176, 0x2000, v176
	v_pk_mul_f32 v[144:145], v[142:143], v[144:145] op_sel_hi:[0,1]
	v_pk_mul_f32 v[146:147], v[142:143], v[146:147] op_sel_hi:[0,1]
	v_pk_mul_f32 v[148:149], v[142:143], v[148:149] op_sel_hi:[0,1]
	v_pk_mul_f32 v[118:119], v[142:143], v[118:119] op_sel_hi:[0,1]
	v_pk_mul_f32 v[116:117], v[142:143], v[116:117] op_sel_hi:[0,1]
	v_pk_mul_f32 v[112:113], v[142:143], v[114:115] op_sel_hi:[0,1]
	v_pk_mul_f32 v[114:115], v[142:143], v[120:121] op_sel_hi:[0,1]
	v_cvt_pk_bf16_f32 v120, v150, v151
	v_cvt_pk_bf16_f32 v121, v144, v145
	v_cvt_pk_bf16_f32 v122, v148, v149
	v_cvt_pk_bf16_f32 v123, v146, v147
	global_store_dwordx4 v[124:125], v[120:123], off
	v_lshl_add_u64 v[124:125], s[26:27], 0, v[176:177]
	s_nop 0
	v_cvt_pk_bf16_f32 v120, v116, v117
	v_cvt_pk_bf16_f32 v121, v118, v119
	v_cvt_pk_bf16_f32 v122, v114, v115
	v_cvt_pk_bf16_f32 v123, v112, v113
	global_store_dwordx4 v[124:125], v[120:123], off
	s_cbranch_vccnz .LBB0_148
	s_nop 0
	v_cndmask_b32_e64 v120, v150, v148, s[6:7]
	v_cndmask_b32_e64 v121, v144, v146, s[6:7]
	ds_bpermute_b32 v182, v167, v120
	v_cndmask_b32_e64 v120, v151, v149, s[6:7]
	ds_bpermute_b32 v121, v167, v121
	v_cndmask_b32_e64 v122, v145, v147, s[6:7]
	ds_bpermute_b32 v120, v167, v120
	ds_bpermute_b32 v176, v167, v122
	s_waitcnt lgkmcnt(0)
	v_cndmask_b32_e64 v150, v182, v150, s[6:7]
	v_cndmask_b32_e64 v175, v146, v121, s[6:7]
	v_cndmask_b32_e64 v146, v121, v144, s[6:7]
	v_cndmask_b32_e64 v149, v149, v120, s[6:7]
	v_cndmask_b32_e64 v151, v120, v151, s[6:7]
	v_cndmask_b32_e64 v180, v176, v145, s[6:7]
	v_cndmask_b32_e64 v120, v150, v146, s[10:11]
	ds_bpermute_b32 v144, v168, v120
	v_cndmask_b32_e64 v120, v151, v180, s[10:11]
	ds_bpermute_b32 v143, v168, v120
	v_cndmask_b32_e64 v178, v148, v182, s[6:7]
	v_mov_b64_e32 v[124:125], 1
	v_mov_b64_e32 v[120:121], 4
	v_cndmask_b32_e64 v179, v147, v176, s[6:7]
	v_mov_b32_e32 v125, v149
	v_mov_b64_e32 v[122:123], 1
	v_mov_b32_e32 v121, v178
	s_waitcnt lgkmcnt(0)
	v_mov_b32_e32 v181, v143
	s_and_saveexec_b64 s[4:5], s[10:11]
	v_mov_b64_e32 v[120:121], 6
	v_mov_b64_e32 v[122:123], 3
	v_mov_b32_e32 v125, v179
	v_mov_b32_e32 v121, v175
	v_mov_b32_e32 v180, v143
	v_mov_b32_e32 v181, v151
	s_or_b64 exec, exec, s[4:5]
	ds_bpermute_b32 v123, v168, v125
	v_cndmask_b32_e64 v125, v146, v144, s[10:11]
	v_cndmask_b32_e64 v125, v125, v180, s[8:9]
	ds_bpermute_b32 v121, v168, v121
	v_cndmask_b32_e64 v183, v144, v150, s[10:11]
	s_waitcnt lgkmcnt(0)
	v_cndmask_b32_e64 v186, v179, v123, s[10:11]
	ds_bpermute_b32 v179, v169, v125
	v_cndmask_b32_e64 v125, v116, v114, s[6:7]
	ds_bpermute_b32 v187, v167, v125
	v_cndmask_b32_e64 v185, v121, v178, s[10:11]
	v_cndmask_b32_e64 v188, v123, v149, s[10:11]
	v_cndmask_b32_e64 v125, v185, v188, s[8:9]
	v_cndmask_b32_e64 v178, v183, v181, s[8:9]
	s_waitcnt lgkmcnt(0)
	v_cndmask_b32_e64 v185, v114, v187, s[6:7]
	v_cndmask_b32_e64 v114, v117, v115, s[6:7]
	ds_bpermute_b32 v183, v167, v114
	v_cndmask_b32_e64 v114, v118, v112, s[6:7]
	ds_bpermute_b32 v114, v167, v114
	v_cndmask_b32_e64 v184, v175, v121, s[10:11]
	ds_bpermute_b32 v180, v169, v125
	v_cndmask_b32_e64 v125, v184, v186, s[8:9]
	v_cndmask_b32_e64 v192, v187, v116, s[6:7]
	s_waitcnt lgkmcnt(0)
; DI float shx(float v, int lane, int mask) { return __int_as_float(__builtin_amdgcn_ds_bpermute((lane ^ mask) << 2, __float_as_int(v))); }
; DI u32x4 pk8(const f32x4& v0, const f32x4& v1) { u32x4 w; w.x = cvt_pk_bf16(v0[0], v0[1]); w.y = cvt_pk_bf16(v0[2], v0[3]); w.z = cvt_pk_bf16(v1[0], v1[1]); w.w = cvt_pk_bf16(v1[2], v1[3]); return w; }
; template <int K> DI void tstage8(float (&v)[8], int lane) {
;   const bool up = (lane & K) != 0;
; #pragma unroll
;   for (int j = 0; j < 8; ++j) {
;     if ((j & K) == 0) {
;       const float send = up ? v[j] : v[j | K];
;       const float recv = shx(send, lane, K);
;       if (up) v[j] = recv; else v[j | K] = recv;
;     }
;   }
; }
; DI void transpose8(float (&v)[8], int lane) { tstage8<4>(v, lane); tstage8<2>(v, lane); tstage8<1>(v, lane); }
;   DI void epi(const Acc& acc, const Unit& u, int wr, int wc, int fr, int fq, LAS unsigned char* lds) const {
;     ...
;           if (!isq) {
;             float vx[8] = {x0[0], x0[1], x0[2], x0[3], x1[0], x1[1], x1[2], x1[3]}, vy[8] = {y0[0], y0[1], y0[2], y0[3], y1[0], y1[1], y1[2], y1[3]};
;             const int lane = fq * 16 + fr;
;             transpose8(vx, lane); transpose8(vy, lane);
;             const int tl = rl & ~7, dk = d0 + (fr & 7);
;             const unsigned kro = (unsigned)((tl >> 7) * 4 + hd) * 65536u + (unsigned)(dk >> 5) * 8192u + (unsigned)((tl & 127) >> 4) * 1024u + (unsigned)((tl >> 3) & 1) * 512u + (unsigned)(dk & 31) * 16u;
;             st16(kT, kro, pk8((f32x4){vx[0], vx[1], vx[2], vx[3]}, (f32x4){vx[4], vx[5], vx[6], vx[7]}));
;             st16(kT, kro + 4u * 8192u, pk8((f32x4){vy[0], vy[1], vy[2], vy[3]}, (f32x4){vy[4], vy[5], vy[6], vy[7]}));
	v_cndmask_b32_e64 v190, v114, v118, s[6:7]
	ds_bpermute_b32 v181, v169, v125
	v_cndmask_b32_e64 v125, v119, v113, s[6:7]
	v_cndmask_b32_e64 v191, v112, v114, s[6:7]
	v_cndmask_b32_e64 v112, v192, v190, s[10:11]
	ds_bpermute_b32 v184, v167, v125
	ds_bpermute_b32 v189, v168, v112
	ds_bpermute_b32 v178, v169, v178
	v_cndmask_b32_e64 v186, v183, v117, s[6:7]
	v_mov_b32_e32 v112, v185
	s_waitcnt lgkmcnt(0)
	v_cndmask_b32_e64 v188, v184, v119, s[6:7]
	v_mov_b64_e32 v[118:119], 0
	v_mov_b32_e32 v125, v186
	v_mov_b32_e32 v114, v190
	v_mov_b32_e32 v117, v189
	s_and_saveexec_b64 s[4:5], s[10:11]
	v_mov_b64_e32 v[124:125], 3
	v_mov_b64_e32 v[118:119], 2
	v_mov_b32_e32 v112, v191
	v_mov_b32_e32 v125, v188
	v_mov_b32_e32 v114, v189
	v_mov_b32_e32 v117, v192
	s_or_b64 exec, exec, s[4:5]
	v_cndmask_b32_e64 v115, v115, v183, s[6:7]
	ds_bpermute_b32 v183, v168, v112
	ds_bpermute_b32 v192, v168, v125
	v_cndmask_b32_e64 v119, v113, v184, s[6:7]
	v_mov_b64_e32 v[112:113], 4
	v_mov_b32_e32 v184, v115
	v_mov_b32_e32 v113, v191
	s_waitcnt lgkmcnt(0)
	v_mov_b32_e32 v125, v183
	s_and_saveexec_b64 s[4:5], s[10:11]
	v_mov_b64_e32 v[112:113], 6
	v_mov_b32_e32 v184, v119
	v_mov_b32_e32 v113, v183
	v_mov_b32_e32 v125, v185
	s_or_b64 exec, exec, s[4:5]
	v_cmp_eq_u32_e32 vcc, 3, v118
	v_cndmask_b32_e64 v148, v148, v182, s[6:7]
	v_cndmask_b32_e64 v116, v187, v116, s[6:7]
	v_cndmask_b32_e32 v182, v188, v189, vcc
	v_cmp_eq_u32_e32 vcc, 7, v118
	v_cndmask_b32_e64 v145, v176, v145, s[6:7]
	v_cndmask_b32_e64 v147, v147, v176, s[6:7]
	v_cndmask_b32_e32 v187, v119, v189, vcc
	v_cmp_eq_u32_e32 vcc, 6, v118
	v_cndmask_b32_e64 v188, v188, v192, s[10:11]
	v_cndmask_b32_e64 v114, v114, v188, s[8:9]
	v_cndmask_b32_e32 v191, v191, v189, vcc
	v_cmp_eq_u32_e32 vcc, 4, v118
	ds_bpermute_b32 v114, v169, v114
	s_lshr_b32 s4, s2, 5
	v_cndmask_b32_e32 v185, v185, v189, vcc
	v_cmp_eq_u32_e32 vcc, 2, v118
	s_and_b32 s4, s4, 0xfffc
	s_add_i32 s4, s4, s54
	v_cndmask_b32_e32 v190, v190, v189, vcc
	v_cmp_eq_u32_e32 vcc, 1, v118
	v_lshl_or_b32 v176, s4, 16, v172
	s_nop 0
	v_cndmask_b32_e32 v193, v186, v189, vcc
	v_cmp_eq_u32_e32 vcc, 0, v118
	v_cndmask_b32_e64 v186, v192, v186, s[10:11]
	v_cndmask_b32_e64 v117, v117, v186, s[8:9]
	v_cndmask_b32_e32 v116, v116, v189, vcc
	v_cmp_eq_u32_e32 vcc, 5, v118
	ds_bpermute_b32 v117, v169, v117
	s_nop 0
	v_cndmask_b32_e32 v118, v115, v189, vcc
	v_cmp_eq_u32_e32 vcc, 7, v124
	s_nop 1
	v_cndmask_b32_e32 v187, v187, v192, vcc
	v_cmp_eq_u32_e32 vcc, 5, v124
	s_nop 1
	v_cndmask_b32_e32 v118, v118, v192, vcc
	v_cmp_eq_u32_e32 vcc, 0, v124
	s_nop 1
	v_cndmask_b32_e32 v116, v116, v192, vcc
	v_cmp_eq_u32_e32 vcc, 1, v124
	s_nop 1
	v_cndmask_b32_e32 v189, v193, v192, vcc
	v_cmp_eq_u32_e32 vcc, 2, v124
	s_nop 1
	v_cndmask_b32_e32 v190, v190, v192, vcc
	v_cmp_eq_u32_e32 vcc, 3, v124
	s_nop 1
	v_cndmask_b32_e32 v182, v182, v192, vcc
	v_cmp_eq_u32_e32 vcc, 4, v124
	s_nop 1
	v_cndmask_b32_e32 v185, v185, v192, vcc
	v_cmp_eq_u32_e32 vcc, 6, v124
	s_nop 1
	v_cndmask_b32_e32 v124, v191, v192, vcc
	v_cmp_eq_u32_e32 vcc, 3, v136
	s_nop 1
	v_cndmask_b32_e32 v145, v145, v144, vcc
	v_cmp_eq_u32_e32 vcc, 7, v136
	s_nop 1
	v_cndmask_b32_e32 v147, v147, v144, vcc
	v_cmp_eq_u32_e32 vcc, 6, v136
	s_nop 1
	v_cndmask_b32_e32 v175, v175, v144, vcc
	v_cmp_eq_u32_e32 vcc, 4, v136
	s_nop 1
	v_cndmask_b32_e32 v148, v148, v144, vcc
	v_cmp_eq_u32_e32 vcc, 2, v136
	s_nop 1
	v_cndmask_b32_e32 v146, v146, v144, vcc
	v_cmp_eq_u32_e32 vcc, 1, v136
	s_nop 1
	v_cndmask_b32_e32 v151, v151, v144, vcc
	v_cmp_eq_u32_e32 vcc, 0, v136
	s_nop 1
	v_cndmask_b32_e32 v150, v150, v144, vcc
	v_cmp_eq_u32_e32 vcc, 5, v136
	s_nop 1
	v_cndmask_b32_e32 v144, v149, v144, vcc
	v_cmp_eq_u32_e32 vcc, 7, v122
	s_nop 1
	v_cndmask_b32_e32 v147, v147, v143, vcc
	v_cmp_eq_u32_e32 vcc, 5, v122
	s_nop 1
	v_cndmask_b32_e32 v144, v144, v143, vcc
	v_cmp_eq_u32_e32 vcc, 0, v122
	s_nop 1
	v_cndmask_b32_e32 v149, v150, v143, vcc
	v_cmp_eq_u32_e32 vcc, 1, v122
	s_nop 1
	v_cndmask_b32_e32 v150, v151, v143, vcc
	v_cmp_eq_u32_e32 vcc, 2, v122
	ds_bpermute_b32 v151, v168, v184
	s_waitcnt lgkmcnt(0)
	v_cndmask_b32_e64 v119, v119, v151, s[10:11]
	v_cndmask_b32_e32 v146, v146, v143, vcc
	v_cmp_eq_u32_e32 vcc, 3, v122
	v_cndmask_b32_e64 v115, v151, v115, s[10:11]
	v_cndmask_b32_e64 v115, v125, v115, s[8:9]
	v_cndmask_b32_e32 v145, v145, v143, vcc
	v_cmp_eq_u32_e32 vcc, 4, v122
	v_cndmask_b32_e64 v113, v113, v119, s[8:9]
	ds_bpermute_b32 v115, v169, v115
	v_cndmask_b32_e32 v148, v148, v143, vcc
	v_cmp_eq_u32_e32 vcc, 6, v122
	ds_bpermute_b32 v113, v169, v113
	s_nop 0
	v_cndmask_b32_e32 v122, v175, v143, vcc
	v_cmp_eq_u32_e32 vcc, 6, v120
	s_nop 1
	v_cndmask_b32_e32 v122, v122, v121, vcc
	v_cmp_eq_u32_e32 vcc, 4, v120
	v_cndmask_b32_e64 v122, v181, v122, s[8:9]
	s_nop 0
	v_cndmask_b32_e32 v143, v148, v121, vcc
	v_cmp_eq_u32_e32 vcc, 3, v120
	v_cndmask_b32_e64 v143, v180, v143, s[8:9]
	s_nop 0
	v_cndmask_b32_e32 v145, v145, v121, vcc
	v_cmp_eq_u32_e32 vcc, 2, v120
	v_cndmask_b32_e64 v145, v145, v179, s[8:9]
	s_nop 0
	v_cndmask_b32_e32 v146, v146, v121, vcc
	v_cmp_eq_u32_e32 vcc, 1, v120
	v_cndmask_b32_e64 v146, v179, v146, s[8:9]
	s_nop 0
	v_cndmask_b32_e32 v148, v150, v121, vcc
	v_cmp_eq_u32_e32 vcc, 0, v120
	s_nop 1
	v_cndmask_b32_e32 v149, v149, v121, vcc
	v_cmp_eq_u32_e32 vcc, 5, v120
	s_nop 1
	v_cndmask_b32_e32 v144, v144, v121, vcc
	v_cmp_eq_u32_e32 vcc, 7, v120
	s_nop 1
	v_cndmask_b32_e32 v120, v147, v121, vcc
	v_cmp_eq_u32_e32 vcc, 6, v112
	v_cndmask_b32_e64 v121, v123, v144, s[10:11]
	v_cndmask_b32_e64 v144, v148, v178, s[8:9]
	v_cndmask_b32_e32 v124, v124, v183, vcc
	v_cmp_eq_u32_e32 vcc, 4, v112
	v_cndmask_b32_e64 v120, v120, v123, s[10:11]
	v_cndmask_b32_e64 v123, v178, v149, s[8:9]
	v_cndmask_b32_e32 v147, v185, v183, vcc
	v_cmp_eq_u32_e32 vcc, 3, v112
	v_cndmask_b32_e64 v121, v121, v180, s[8:9]
	v_cndmask_b32_e64 v120, v120, v181, s[8:9]
	v_cndmask_b32_e32 v148, v182, v183, vcc
	v_cmp_eq_u32_e32 vcc, 2, v112
	v_cndmask_b32_e64 v125, v148, v114, s[8:9]
	s_waitcnt lgkmcnt(0)
; DI u32x4 pk8(const f32x4& v0, const f32x4& v1) { u32x4 w; w.x = cvt_pk_bf16(v0[0], v0[1]); w.y = cvt_pk_bf16(v0[2], v0[3]); w.z = cvt_pk_bf16(v1[0], v1[1]); w.w = cvt_pk_bf16(v1[2], v1[3]); return w; }
; DI void transpose8(float (&v)[8], int lane) { tstage8<4>(v, lane); tstage8<2>(v, lane); tstage8<1>(v, lane); }
;   DI void epi(const Acc& acc, const Unit& u, int wr, int wc, int fr, int fq, LAS unsigned char* lds) const {
;     ...
;           const int rl = u.pm * 256 + ai * 128 + wr * 64 + m * 16 + fr; const int pos = tok_pos(rb + rl);
;           const unsigned to = (unsigned)(pos * 128 + d0) * 4u; const f32x4 c0 = ldf4(cosR, to), c1 = ldf4(cosR, to + 16u);
;           const f32x4 s0 = ldf4(sinR, to), s1 = ldf4(sinR, to + 16u);
;           const f32x4 a0 = acc[ai][0][m][0], a1 = acc[ai][0][m][1], b0 = acc[ai][1][m][0], b1 = acc[ai][1][m][1];
;           const f32x4 x0 = (a0 * c0 - b0 * s0) * sc, x1 = (a1 * c1 - b1 * s1) * sc, y0 = (b0 * c0 + a0 * s0) * sc, y1 = (b1 * c1 + a1 * s1) * sc;
;           const unsigned ro = fo + (unsigned)(rl >> 7) * 262144u + (unsigned)((rl >> 5) & 3) * 16384u + (unsigned)(rl & 31) * 16u;
;           st16(base, ro, pk8(x0, x1));
;           st16(base, ro + 8192u, pk8(y0, y1));
;           if (!isq) {
;             float vx[8] = {x0[0], x0[1], x0[2], x0[3], x1[0], x1[1], x1[2], x1[3]}, vy[8] = {y0[0], y0[1], y0[2], y0[3], y1[0], y1[1], y1[2], y1[3]};
;             const int lane = fq * 16 + fr;
;             transpose8(vx, lane); transpose8(vy, lane);
;             const int tl = rl & ~7, dk = d0 + (fr & 7);
;             const unsigned kro = (unsigned)((tl >> 7) * 4 + hd) * 65536u + (unsigned)(dk >> 5) * 8192u + (unsigned)((tl & 127) >> 4) * 1024u + (unsigned)((tl >> 3) & 1) * 512u + (unsigned)(dk & 31) * 16u;
;             st16(kT, kro, pk8((f32x4){vx[0], vx[1], vx[2], vx[3]}, (f32x4){vx[4], vx[5], vx[6], vx[7]}));
;             st16(kT, kro + 4u * 8192u, pk8((f32x4){vy[0], vy[1], vy[2], vy[3]}, (f32x4){vy[4], vy[5], vy[6], vy[7]}));
;           }
;           __builtin_amdgcn_sched_barrier(0);
;         }
	v_cndmask_b32_e64 v147, v115, v147, s[8:9]
	v_cndmask_b32_e32 v149, v190, v183, vcc
	v_cmp_eq_u32_e32 vcc, 1, v112
	v_cndmask_b32_e64 v119, v114, v149, s[8:9]
	v_cndmask_b32_e64 v124, v113, v124, s[8:9]
	v_cndmask_b32_e32 v150, v189, v183, vcc
	v_cmp_eq_u32_e32 vcc, 0, v112
	v_cndmask_b32_e64 v150, v150, v117, s[8:9]
	s_nop 0
	v_cndmask_b32_e32 v116, v116, v183, vcc
	v_cmp_eq_u32_e32 vcc, 5, v112
	s_nop 1
	v_cndmask_b32_e32 v118, v118, v183, vcc
	v_cmp_eq_u32_e32 vcc, 7, v112
	v_cndmask_b32_e64 v118, v151, v118, s[10:11]
	v_cndmask_b32_e64 v118, v118, v115, s[8:9]
	v_cndmask_b32_e32 v112, v187, v183, vcc
	v_cndmask_b32_e64 v112, v112, v151, s[10:11]
	v_cndmask_b32_e64 v151, v117, v116, s[8:9]
	v_lshl_add_u64 v[116:117], s[24:25], 0, v[176:177]
	v_or_b32_e32 v176, 0x8000, v176
	v_cndmask_b32_e64 v148, v112, v113, s[8:9]
	v_cvt_pk_bf16_f32 v112, v123, v144
	v_cvt_pk_bf16_f32 v113, v146, v145
	v_cvt_pk_bf16_f32 v114, v143, v121
	v_cvt_pk_bf16_f32 v115, v122, v120
	global_store_dwordx4 v[116:117], v[112:115], off
	v_lshl_add_u64 v[116:117], s[24:25], 0, v[176:177]
	s_nop 0
	v_cvt_pk_bf16_f32 v112, v151, v150
	v_cvt_pk_bf16_f32 v113, v119, v125
	v_cvt_pk_bf16_f32 v114, v147, v118
	v_cvt_pk_bf16_f32 v115, v124, v148
	global_store_dwordx4 v[116:117], v[112:115], off
.LBB0_148:
	v_mov_b32_e32 v143, v142
	s_or_b32 s4, s2, 16
	v_or_b32_e32 v148, s4, v137
	v_add_u32_e32 v112, s34, v148
	v_cmp_gt_i32_e32 vcc, s55, v112
	v_mov_b32_e32 v113, 0xfdf
	v_mov_b32_e32 v114, 0x7df
	v_cndmask_b32_e32 v113, v113, v114, vcc
	v_and_b32_e32 v112, v113, v112
	v_lshl_or_b32 v176, v112, 9, v166
	v_lshl_add_u64 v[112:113], s[30:31], 0, v[176:177]
	global_load_dwordx4 v[114:117], v[112:113], off
	v_lshl_add_u64 v[112:113], s[28:29], 0, v[176:177]
	global_load_dwordx4 v[118:121], v[112:113], off
	v_or_b32_e32 v112, 16, v176
	v_mov_b32_e32 v113, v177
	v_lshl_add_u64 v[122:123], s[30:31], 0, v[112:113]
	global_load_dwordx4 v[122:125], v[122:123], off
	v_lshl_add_u64 v[112:113], s[28:29], 0, v[112:113]
	global_load_dwordx4 v[144:147], v[112:113], off
	v_lshlrev_b32_e32 v148, 4, v148
	s_movk_i32 s5, 0x1f0
	v_mov_b32_e32 v112, v142
	v_mov_b32_e32 v113, v142
	v_cndmask_b32_e64 v149, 0, 1, s[0:1]
	v_and_or_b32 v176, v148, s5, v127
	v_cmp_ne_u32_e64 s[12:13], 1, v149
	v_lshl_add_u64 v[148:149], s[26:27], 0, v[176:177]
	v_or_b32_e32 v176, 0x2000, v176
	v_lshl_add_u64 v[150:151], s[26:27], 0, v[176:177]
	s_andn2_b64 vcc, exec, s[0:1]
	s_waitcnt vmcnt(0) lgkmcnt(0)
	v_pk_mul_f32 v[178:179], v[102:103], v[116:117]
	v_pk_mul_f32 v[180:181], v[100:101], v[114:115]
	v_pk_mul_f32 v[116:117], v[110:111], v[116:117]
	v_pk_mul_f32 v[114:115], v[108:109], v[114:115]
	v_pk_fma_f32 v[110:111], v[110:111], v[120:121], v[178:179] neg_lo:[0,0,1] neg_hi:[0,0,1]
	v_pk_fma_f32 v[108:109], v[108:109], v[118:119], v[180:181] neg_lo:[0,0,1] neg_hi:[0,0,1]
	v_pk_mul_f32 v[178:179], v[98:99], v[124:125]
	v_pk_mul_f32 v[180:181], v[96:97], v[122:123]
	v_pk_fma_f32 v[116:117], v[102:103], v[120:121], v[116:117]
	v_pk_fma_f32 v[114:115], v[100:101], v[118:119], v[114:115]
	v_pk_mul_f32 v[118:119], v[106:107], v[124:125]
	v_pk_mul_f32 v[120:121], v[104:105], v[122:123]
	v_pk_mul_f32 v[100:101], v[112:113], v[110:111]
	v_pk_mul_f32 v[102:103], v[142:143], v[108:109]
	v_pk_fma_f32 v[106:107], v[106:107], v[146:147], v[178:179] neg_lo:[0,0,1] neg_hi:[0,0,1]
	v_pk_fma_f32 v[108:109], v[104:105], v[144:145], v[180:181] neg_lo:[0,0,1] neg_hi:[0,0,1]
	v_pk_fma_f32 v[110:111], v[98:99], v[146:147], v[118:119]
	v_pk_fma_f32 v[96:97], v[96:97], v[144:145], v[120:121]
	v_pk_mul_f32 v[116:117], v[112:113], v[116:117]
	v_pk_mul_f32 v[104:105], v[142:143], v[114:115]
	v_pk_mul_f32 v[98:99], v[112:113], v[106:107]
	v_pk_mul_f32 v[106:107], v[142:143], v[108:109]
	v_pk_mul_f32 v[110:111], v[112:113], v[110:111]
	v_pk_mul_f32 v[114:115], v[142:143], v[96:97]
	v_cvt_pk_bf16_f32 v118, v102, v103
	v_cvt_pk_bf16_f32 v119, v100, v101
	v_cvt_pk_bf16_f32 v120, v106, v107
	v_cvt_pk_bf16_f32 v121, v98, v99
	global_store_dwordx4 v[148:149], v[118:121], off
	s_nop 1
	v_cvt_pk_bf16_f32 v118, v104, v105
	v_cvt_pk_bf16_f32 v119, v116, v117
	v_cvt_pk_bf16_f32 v120, v114, v115
	v_cvt_pk_bf16_f32 v121, v110, v111
	global_store_dwordx4 v[150:151], v[118:121], off
	s_cbranch_vccnz .LBB0_156
; DI float shx(float v, int lane, int mask) { return __int_as_float(__builtin_amdgcn_ds_bpermute((lane ^ mask) << 2, __float_as_int(v))); }
; DI u32x4 pk8(const f32x4& v0, const f32x4& v1) { u32x4 w; w.x = cvt_pk_bf16(v0[0], v0[1]); w.y = cvt_pk_bf16(v0[2], v0[3]); w.z = cvt_pk_bf16(v1[0], v1[1]); w.w = cvt_pk_bf16(v1[2], v1[3]); return w; }
; DI void transpose8(float (&v)[8], int lane) { tstage8<4>(v, lane); tstage8<2>(v, lane); tstage8<1>(v, lane); }
; template <int K> DI void tstage8(float (&v)[8], int lane) {
;   const bool up = (lane & K) != 0;
; #pragma unroll
;   for (int j = 0; j < 8; ++j) {
;     if ((j & K) == 0) {
;       const float send = up ? v[j] : v[j | K];
;       const float recv = shx(send, lane, K);
;       if (up) v[j] = recv; else v[j | K] = recv;
;     }
;   }
; }
;   DI void epi(const Acc& acc, const Unit& u, int wr, int wc, int fr, int fq, LAS unsigned char* lds) const {
;     ...
;             float vx[8] = {x0[0], x0[1], x0[2], x0[3], x1[0], x1[1], x1[2], x1[3]}, vy[8] = {y0[0], y0[1], y0[2], y0[3], y1[0], y1[1], y1[2], y1[3]};
;             const int lane = fq * 16 + fr;
;             transpose8(vx, lane); transpose8(vy, lane);
;             const int tl = rl & ~7, dk = d0 + (fr & 7);
;             const unsigned kro = (unsigned)((tl >> 7) * 4 + hd) * 65536u + (unsigned)(dk >> 5) * 8192u + (unsigned)((tl & 127) >> 4) * 1024u + (unsigned)((tl >> 3) & 1) * 512u + (unsigned)(dk & 31) * 16u;
;             st16(kT, kro, pk8((f32x4){vx[0], vx[1], vx[2], vx[3]}, (f32x4){vx[4], vx[5], vx[6], vx[7]}));
;             st16(kT, kro + 4u * 8192u, pk8((f32x4){vy[0], vy[1], vy[2], vy[3]}, (f32x4){vy[4], vy[5], vy[6], vy[7]}));
	v_cndmask_b32_e64 v96, v102, v106, s[6:7]
	ds_bpermute_b32 v144, v167, v96
	v_cndmask_b32_e64 v97, v100, v98, s[6:7]
	v_cndmask_b32_e64 v96, v103, v107, s[6:7]
	ds_bpermute_b32 v97, v167, v97
	ds_bpermute_b32 v96, v167, v96
	s_waitcnt lgkmcnt(0)
	v_cndmask_b32_e64 v118, v144, v102, s[6:7]
	v_cndmask_b32_e64 v102, v101, v99, s[6:7]
	ds_bpermute_b32 v122, v167, v102
	v_cndmask_b32_e64 v120, v97, v100, s[6:7]
	v_cndmask_b32_e64 v107, v107, v96, s[6:7]
	v_cndmask_b32_e64 v119, v96, v103, s[6:7]
	v_cndmask_b32_e64 v96, v118, v120, s[10:11]
	s_waitcnt lgkmcnt(0)
	v_cndmask_b32_e64 v125, v122, v101, s[6:7]
	ds_bpermute_b32 v100, v168, v96
	v_cndmask_b32_e64 v96, v119, v125, s[10:11]
	v_cndmask_b32_e64 v121, v98, v97, s[6:7]
	ds_bpermute_b32 v98, v168, v96
	v_cndmask_b32_e64 v123, v106, v144, s[6:7]
	v_mov_b64_e32 v[108:109], 1
	v_mov_b64_e32 v[96:97], 4
	v_cndmask_b32_e64 v124, v99, v122, s[6:7]
	v_mov_b32_e32 v109, v107
	v_mov_b64_e32 v[102:103], 1
	v_mov_b32_e32 v97, v123
	s_waitcnt lgkmcnt(0)
	v_mov_b32_e32 v127, v98
	s_and_saveexec_b64 s[0:1], s[10:11]
	v_mov_b64_e32 v[96:97], 6
	v_mov_b64_e32 v[102:103], 3
	v_mov_b32_e32 v109, v124
	v_mov_b32_e32 v97, v121
	v_mov_b32_e32 v125, v98
	v_mov_b32_e32 v127, v119
	s_or_b64 exec, exec, s[0:1]
	ds_bpermute_b32 v103, v168, v109
	ds_bpermute_b32 v97, v168, v97
	v_cndmask_b32_e64 v109, v120, v100, s[10:11]
	v_cndmask_b32_e64 v109, v109, v125, s[8:9]
	v_cndmask_b32_e64 v145, v100, v118, s[10:11]
	s_waitcnt lgkmcnt(0)
	v_cndmask_b32_e64 v148, v124, v103, s[10:11]
	ds_bpermute_b32 v124, v169, v109
	v_cndmask_b32_e64 v109, v104, v114, s[6:7]
	ds_bpermute_b32 v149, v167, v109
	v_cndmask_b32_e64 v147, v97, v123, s[10:11]
	v_cndmask_b32_e64 v150, v103, v107, s[10:11]
	v_cndmask_b32_e64 v146, v121, v97, s[10:11]
	v_cndmask_b32_e64 v109, v147, v150, s[8:9]
	ds_bpermute_b32 v125, v169, v109
	v_cndmask_b32_e64 v109, v146, v148, s[8:9]
	v_cndmask_b32_e64 v123, v145, v127, s[8:9]
	ds_bpermute_b32 v127, v169, v109
	v_cndmask_b32_e64 v109, v105, v115, s[6:7]
	s_waitcnt lgkmcnt(0)
	v_cndmask_b32_e64 v147, v114, v149, s[6:7]
	ds_bpermute_b32 v114, v167, v109
	v_cndmask_b32_e64 v109, v116, v110, s[6:7]
	ds_bpermute_b32 v109, v167, v109
	v_cndmask_b32_e64 v145, v117, v111, s[6:7]
	v_cndmask_b32_e64 v146, v149, v104, s[6:7]
	ds_bpermute_b32 v145, v167, v145
	s_waitcnt lgkmcnt(0)
	v_cndmask_b32_e64 v148, v114, v105, s[6:7]
	v_cndmask_b32_e64 v175, v109, v116, s[6:7]
	v_cndmask_b32_e64 v105, v146, v175, s[10:11]
	ds_bpermute_b32 v151, v168, v105
	ds_bpermute_b32 v123, v169, v123
	v_cndmask_b32_e64 v150, v145, v117, s[6:7]
	v_mov_b64_e32 v[116:117], 0
	v_cndmask_b32_e64 v176, v110, v109, s[6:7]
	v_mov_b32_e32 v110, v147
	v_mov_b32_e32 v117, v148
	v_mov_b32_e32 v105, v175
	s_waitcnt lgkmcnt(0)
	v_mov_b32_e32 v109, v151
	s_and_saveexec_b64 s[0:1], s[10:11]
	v_mov_b64_e32 v[116:117], 2
	v_mov_b64_e32 v[108:109], 3
	v_mov_b32_e32 v110, v176
	v_mov_b32_e32 v117, v150
	v_mov_b32_e32 v105, v151
	v_mov_b32_e32 v109, v146
	s_or_b64 exec, exec, s[0:1]
	v_cndmask_b32_e64 v114, v115, v114, s[6:7]
	v_cndmask_b32_e64 v115, v111, v145, s[6:7]
	ds_bpermute_b32 v145, v168, v110
	ds_bpermute_b32 v178, v168, v117
	v_mov_b64_e32 v[110:111], 4
	v_mov_b32_e32 v146, v114
	v_mov_b32_e32 v111, v176
	s_waitcnt lgkmcnt(0)
	v_mov_b32_e32 v117, v145
	s_and_saveexec_b64 s[0:1], s[10:11]
	v_mov_b64_e32 v[110:111], 6
	v_mov_b32_e32 v146, v115
	v_mov_b32_e32 v111, v145
	v_mov_b32_e32 v117, v147
	s_or_b64 exec, exec, s[0:1]
	v_cmp_eq_u32_e32 vcc, 3, v116
	v_cndmask_b32_e64 v106, v106, v144, s[6:7]
	v_cndmask_b32_e64 v104, v149, v104, s[6:7]
	v_cndmask_b32_e32 v144, v150, v151, vcc
	v_cmp_eq_u32_e32 vcc, 7, v116
	v_cndmask_b32_e64 v101, v122, v101, s[6:7]
	v_cndmask_b32_e64 v99, v99, v122, s[6:7]
	v_cndmask_b32_e32 v149, v115, v151, vcc
	v_cmp_eq_u32_e32 vcc, 6, v116
	v_cndmask_b32_e64 v150, v150, v178, s[10:11]
	s_lshr_b32 s0, s2, 5
	v_cndmask_b32_e32 v176, v176, v151, vcc
	v_cmp_eq_u32_e32 vcc, 4, v116
	v_cndmask_b32_e64 v105, v105, v150, s[8:9]
	s_and_b32 s0, s0, 0xfffc
	v_cndmask_b32_e32 v147, v147, v151, vcc
	v_cmp_eq_u32_e32 vcc, 2, v116
	ds_bpermute_b32 v105, v169, v105
	s_add_i32 s0, s0, s54
	v_cndmask_b32_e32 v175, v175, v151, vcc
	v_cmp_eq_u32_e32 vcc, 1, v116
	s_lshl_b32 s1, s4, 6
	s_lshl_b32 s0, s0, 16
	v_cndmask_b32_e32 v179, v148, v151, vcc
	v_cmp_eq_u32_e32 vcc, 0, v116
	v_cndmask_b32_e64 v148, v178, v148, s[10:11]
	v_cndmask_b32_e64 v109, v109, v148, s[8:9]
	v_cndmask_b32_e32 v104, v104, v151, vcc
	v_cmp_eq_u32_e32 vcc, 5, v116
	ds_bpermute_b32 v109, v169, v109
	s_and_b32 s1, s1, 0x1400
	v_cndmask_b32_e32 v116, v114, v151, vcc
	v_cmp_eq_u32_e32 vcc, 7, v108
	s_or_b32 s0, s0, s1
	s_nop 0
	v_cndmask_b32_e32 v149, v149, v178, vcc
	v_cmp_eq_u32_e32 vcc, 5, v108
	s_nop 1
	v_cndmask_b32_e32 v116, v116, v178, vcc
	v_cmp_eq_u32_e32 vcc, 0, v108
	s_nop 1
	v_cndmask_b32_e32 v104, v104, v178, vcc
	v_cmp_eq_u32_e32 vcc, 1, v108
	s_nop 1
	v_cndmask_b32_e32 v151, v179, v178, vcc
	v_cmp_eq_u32_e32 vcc, 2, v108
	s_nop 1
	v_cndmask_b32_e32 v175, v175, v178, vcc
	v_cmp_eq_u32_e32 vcc, 3, v108
	s_nop 1
	v_cndmask_b32_e32 v144, v144, v178, vcc
	v_cmp_eq_u32_e32 vcc, 4, v108
	s_nop 1
	v_cndmask_b32_e32 v147, v147, v178, vcc
	v_cmp_eq_u32_e32 vcc, 6, v108
	s_nop 1
	v_cndmask_b32_e32 v108, v176, v178, vcc
	v_cmp_eq_u32_e32 vcc, 3, v136
	v_or_b32_e32 v176, s0, v171
	s_nop 0
	v_cndmask_b32_e32 v101, v101, v100, vcc
	v_cmp_eq_u32_e32 vcc, 7, v136
	s_nop 1
	v_cndmask_b32_e32 v99, v99, v100, vcc
	v_cmp_eq_u32_e32 vcc, 6, v136
	s_nop 1
	v_cndmask_b32_e32 v121, v121, v100, vcc
	v_cmp_eq_u32_e32 vcc, 4, v136
	s_nop 1
	v_cndmask_b32_e32 v106, v106, v100, vcc
	v_cmp_eq_u32_e32 vcc, 2, v136
	s_nop 1
	v_cndmask_b32_e32 v120, v120, v100, vcc
	v_cmp_eq_u32_e32 vcc, 1, v136
	s_nop 1
	v_cndmask_b32_e32 v119, v119, v100, vcc
	v_cmp_eq_u32_e32 vcc, 0, v136
	s_nop 1
	v_cndmask_b32_e32 v118, v118, v100, vcc
	v_cmp_eq_u32_e32 vcc, 5, v136
	s_nop 1
	v_cndmask_b32_e32 v100, v107, v100, vcc
	v_cmp_eq_u32_e32 vcc, 7, v102
	s_nop 1
	v_cndmask_b32_e32 v99, v99, v98, vcc
	v_cmp_eq_u32_e32 vcc, 5, v102
	s_nop 1
	v_cndmask_b32_e32 v100, v100, v98, vcc
	v_cmp_eq_u32_e32 vcc, 0, v102
	s_nop 1
	v_cndmask_b32_e32 v107, v118, v98, vcc
	v_cmp_eq_u32_e32 vcc, 1, v102
	s_nop 1
	v_cndmask_b32_e32 v118, v119, v98, vcc
	v_cmp_eq_u32_e32 vcc, 2, v102
	s_nop 1
	v_cndmask_b32_e32 v119, v120, v98, vcc
	v_cmp_eq_u32_e32 vcc, 3, v102
	ds_bpermute_b32 v120, v168, v146
	s_waitcnt lgkmcnt(0)
; DI u32x4 pk8(const f32x4& v0, const f32x4& v1) { u32x4 w; w.x = cvt_pk_bf16(v0[0], v0[1]); w.y = cvt_pk_bf16(v0[2], v0[3]); w.z = cvt_pk_bf16(v1[0], v1[1]); w.w = cvt_pk_bf16(v1[2], v1[3]); return w; }
; DI void transpose8(float (&v)[8], int lane) { tstage8<4>(v, lane); tstage8<2>(v, lane); tstage8<1>(v, lane); }
;   DI void epi(const Acc& acc, const Unit& u, int wr, int wc, int fr, int fq, LAS unsigned char* lds) const {
;     ...
;           const int rl = u.pm * 256 + ai * 128 + wr * 64 + m * 16 + fr; const int pos = tok_pos(rb + rl);
;           const unsigned to = (unsigned)(pos * 128 + d0) * 4u; const f32x4 c0 = ldf4(cosR, to), c1 = ldf4(cosR, to + 16u);
;           const f32x4 s0 = ldf4(sinR, to), s1 = ldf4(sinR, to + 16u);
;           const f32x4 a0 = acc[ai][0][m][0], a1 = acc[ai][0][m][1], b0 = acc[ai][1][m][0], b1 = acc[ai][1][m][1];
;           const f32x4 x0 = (a0 * c0 - b0 * s0) * sc, x1 = (a1 * c1 - b1 * s1) * sc, y0 = (b0 * c0 + a0 * s0) * sc, y1 = (b1 * c1 + a1 * s1) * sc;
;           const unsigned ro = fo + (unsigned)(rl >> 7) * 262144u + (unsigned)((rl >> 5) & 3) * 16384u + (unsigned)(rl & 31) * 16u;
;           st16(base, ro, pk8(x0, x1));
;           st16(base, ro + 8192u, pk8(y0, y1));
;           if (!isq) {
;             float vx[8] = {x0[0], x0[1], x0[2], x0[3], x1[0], x1[1], x1[2], x1[3]}, vy[8] = {y0[0], y0[1], y0[2], y0[3], y1[0], y1[1], y1[2], y1[3]};
;             const int lane = fq * 16 + fr;
;             transpose8(vx, lane); transpose8(vy, lane);
;             const int tl = rl & ~7, dk = d0 + (fr & 7);
;             const unsigned kro = (unsigned)((tl >> 7) * 4 + hd) * 65536u + (unsigned)(dk >> 5) * 8192u + (unsigned)((tl & 127) >> 4) * 1024u + (unsigned)((tl >> 3) & 1) * 512u + (unsigned)(dk & 31) * 16u;
;             st16(kT, kro, pk8((f32x4){vx[0], vx[1], vx[2], vx[3]}, (f32x4){vx[4], vx[5], vx[6], vx[7]}));
;             st16(kT, kro + 4u * 8192u, pk8((f32x4){vy[0], vy[1], vy[2], vy[3]}, (f32x4){vy[4], vy[5], vy[6], vy[7]}));
	v_cndmask_b32_e64 v115, v115, v120, s[10:11]
	v_cndmask_b32_e32 v101, v101, v98, vcc
	v_cmp_eq_u32_e32 vcc, 4, v102
	v_cndmask_b32_e64 v114, v120, v114, s[10:11]
	v_cndmask_b32_e64 v114, v117, v114, s[8:9]
	v_cndmask_b32_e32 v106, v106, v98, vcc
	v_cmp_eq_u32_e32 vcc, 6, v102
	v_cndmask_b32_e64 v111, v111, v115, s[8:9]
	ds_bpermute_b32 v114, v169, v114
	v_cndmask_b32_e32 v98, v121, v98, vcc
	v_cmp_eq_u32_e32 vcc, 6, v96
	ds_bpermute_b32 v111, v169, v111
	s_nop 0
	v_cndmask_b32_e32 v98, v98, v97, vcc
	v_cmp_eq_u32_e32 vcc, 4, v96
	s_nop 1
	v_cndmask_b32_e32 v102, v106, v97, vcc
	v_cmp_eq_u32_e32 vcc, 3, v96
	v_cndmask_b32_e64 v102, v125, v102, s[8:9]
	s_nop 0
	v_cndmask_b32_e32 v101, v101, v97, vcc
	v_cmp_eq_u32_e32 vcc, 2, v96
	v_cndmask_b32_e64 v101, v101, v124, s[8:9]
	s_nop 0
	v_cndmask_b32_e32 v106, v119, v97, vcc
	v_cmp_eq_u32_e32 vcc, 1, v96
	s_nop 1
	v_cndmask_b32_e32 v118, v118, v97, vcc
	v_cmp_eq_u32_e32 vcc, 0, v96
	s_nop 1
	v_cndmask_b32_e32 v107, v107, v97, vcc
	v_cmp_eq_u32_e32 vcc, 5, v96
	s_nop 1
	v_cndmask_b32_e32 v100, v100, v97, vcc
	v_cmp_eq_u32_e32 vcc, 7, v96
	s_nop 1
	v_cndmask_b32_e32 v96, v99, v97, vcc
	v_cndmask_b32_e64 v96, v96, v103, s[10:11]
	v_cmp_eq_u32_e32 vcc, 6, v110
	v_cndmask_b32_e64 v97, v103, v100, s[10:11]
	v_cndmask_b32_e64 v100, v118, v123, s[8:9]
	v_cndmask_b32_e64 v118, v96, v127, s[8:9]
	v_cndmask_b32_e32 v96, v108, v145, vcc
	v_cmp_eq_u32_e32 vcc, 4, v110
	v_cndmask_b32_e64 v103, v124, v106, s[8:9]
	v_cndmask_b32_e64 v106, v97, v125, s[8:9]
	v_cndmask_b32_e32 v97, v147, v145, vcc
	v_cmp_eq_u32_e32 vcc, 3, v110
	v_cndmask_b32_e64 v99, v123, v107, s[8:9]
	v_cndmask_b32_e64 v107, v127, v98, s[8:9]
	v_cndmask_b32_e32 v98, v144, v145, vcc
	v_cmp_eq_u32_e32 vcc, 2, v110
	s_waitcnt lgkmcnt(0)
	v_cndmask_b32_e64 v115, v114, v97, s[8:9]
	v_cndmask_b32_e32 v108, v175, v145, vcc
	v_cmp_eq_u32_e32 vcc, 1, v110
	v_cndmask_b32_e64 v108, v105, v108, s[8:9]
	v_cndmask_b32_e64 v105, v98, v105, s[8:9]
	v_cndmask_b32_e32 v119, v151, v145, vcc
	v_cmp_eq_u32_e32 vcc, 0, v110
	s_nop 1
	v_cndmask_b32_e32 v104, v104, v145, vcc
	v_cmp_eq_u32_e32 vcc, 5, v110
	v_cndmask_b32_e64 v104, v109, v104, s[8:9]
	v_cndmask_b32_e64 v109, v119, v109, s[8:9]
	v_cndmask_b32_e32 v116, v116, v145, vcc
	v_cmp_eq_u32_e32 vcc, 7, v110
	v_cndmask_b32_e64 v116, v120, v116, s[10:11]
	v_cndmask_b32_e64 v114, v116, v114, s[8:9]
	v_cndmask_b32_e32 v110, v149, v145, vcc
	v_cndmask_b32_e64 v116, v111, v96, s[8:9]
	v_cvt_pk_bf16_f32 v96, v99, v100
	v_cvt_pk_bf16_f32 v97, v103, v101
	v_lshl_add_u64 v[100:101], s[24:25], 0, v[176:177]
	v_or_b32_e32 v176, 0x8000, v176
	v_cndmask_b32_e64 v110, v110, v120, s[10:11]
	v_cvt_pk_bf16_f32 v98, v102, v106
	v_cvt_pk_bf16_f32 v99, v107, v118
	global_store_dwordx4 v[100:101], v[96:99], off
	v_lshl_add_u64 v[100:101], s[24:25], 0, v[176:177]
	v_cndmask_b32_e64 v110, v110, v111, s[8:9]
	v_cvt_pk_bf16_f32 v96, v104, v109
	v_cvt_pk_bf16_f32 v97, v108, v105
	v_cvt_pk_bf16_f32 v98, v115, v114
	v_cvt_pk_bf16_f32 v99, v116, v110
	global_store_dwordx4 v[100:101], v[96:99], off
.LBB0_156:
	s_or_b32 s4, s2, 32
	s_nop 0
	v_or_b32_e32 v96, s4, v137
	v_add_u32_e32 v96, s34, v96
	v_cmp_gt_i32_e32 vcc, s55, v96
	v_mov_b32_e32 v97, 0xfef
	v_mov_b32_e32 v98, 0x7ef
	v_cndmask_b32_e32 v97, v97, v98, vcc
	v_and_b32_e32 v96, v97, v96
	v_lshl_or_b32 v176, v96, 9, v166
	v_lshl_add_u64 v[96:97], s[30:31], 0, v[176:177]
	v_or_b32_e32 v108, 16, v176
	v_mov_b32_e32 v109, v177
	global_load_dwordx4 v[96:99], v[96:97], off
	v_lshl_add_u64 v[100:101], s[28:29], 0, v[176:177]
	v_lshl_add_u64 v[104:105], s[30:31], 0, v[108:109]
	global_load_dwordx4 v[100:103], v[100:101], off
	v_lshl_add_u64 v[108:109], s[28:29], 0, v[108:109]
	global_load_dwordx4 v[104:107], v[104:105], off
	s_lshl_b32 s0, s4, 9
	global_load_dwordx4 v[108:111], v[108:109], off
	s_and_b32 s0, s0, 0xc000
	v_or3_b32 v176, s0, v154, v126
	v_lshl_add_u64 v[114:115], s[26:27], 0, v[176:177]
	v_or_b32_e32 v176, 0x2000, v176
	v_lshl_add_u64 v[116:117], s[26:27], 0, v[176:177]
	s_and_b64 vcc, exec, s[12:13]
	s_waitcnt vmcnt(0) lgkmcnt(0)
	v_pk_mul_f32 v[118:119], v[86:87], v[98:99]
	v_pk_mul_f32 v[120:121], v[84:85], v[96:97]
	v_pk_mul_f32 v[98:99], v[94:95], v[98:99]
	v_pk_mul_f32 v[96:97], v[92:93], v[96:97]
	v_pk_fma_f32 v[94:95], v[94:95], v[102:103], v[118:119] neg_lo:[0,0,1] neg_hi:[0,0,1]
	v_pk_fma_f32 v[92:93], v[92:93], v[100:101], v[120:121] neg_lo:[0,0,1] neg_hi:[0,0,1]
	v_pk_mul_f32 v[118:119], v[82:83], v[106:107]
	v_pk_mul_f32 v[120:121], v[80:81], v[104:105]
	v_pk_fma_f32 v[98:99], v[86:87], v[102:103], v[98:99]
	v_pk_fma_f32 v[96:97], v[84:85], v[100:101], v[96:97]
	v_pk_mul_f32 v[100:101], v[90:91], v[106:107]
	v_pk_mul_f32 v[102:103], v[88:89], v[104:105]
	v_pk_mul_f32 v[86:87], v[142:143], v[92:93]
	v_pk_fma_f32 v[90:91], v[90:91], v[110:111], v[118:119] neg_lo:[0,0,1] neg_hi:[0,0,1]
	v_pk_fma_f32 v[92:93], v[88:89], v[108:109], v[120:121] neg_lo:[0,0,1] neg_hi:[0,0,1]
	v_pk_mul_f32 v[88:89], v[142:143], v[96:97]
	v_pk_fma_f32 v[82:83], v[82:83], v[110:111], v[100:101]
	v_pk_fma_f32 v[96:97], v[80:81], v[108:109], v[102:103]
	v_pk_mul_f32 v[84:85], v[112:113], v[94:95]
	v_pk_mul_f32 v[98:99], v[112:113], v[98:99]
	v_pk_mul_f32 v[80:81], v[112:113], v[90:91]
	v_pk_mul_f32 v[90:91], v[142:143], v[92:93]
	v_pk_mul_f32 v[94:95], v[112:113], v[82:83]
	v_pk_mul_f32 v[96:97], v[142:143], v[96:97]
	v_cvt_pk_bf16_f32 v100, v86, v87
	v_cvt_pk_bf16_f32 v101, v84, v85
	v_cvt_pk_bf16_f32 v102, v90, v91
	v_cvt_pk_bf16_f32 v103, v80, v81
	global_store_dwordx4 v[114:115], v[100:103], off
	s_nop 1
	v_cvt_pk_bf16_f32 v100, v88, v89
	v_cvt_pk_bf16_f32 v101, v98, v99
	v_cvt_pk_bf16_f32 v102, v96, v97
	v_cvt_pk_bf16_f32 v103, v94, v95
	global_store_dwordx4 v[116:117], v[100:103], off
	s_cbranch_vccnz .LBB0_164
; DI float shx(float v, int lane, int mask) { return __int_as_float(__builtin_amdgcn_ds_bpermute((lane ^ mask) << 2, __float_as_int(v))); }
; DI u32x4 pk8(const f32x4& v0, const f32x4& v1) { u32x4 w; w.x = cvt_pk_bf16(v0[0], v0[1]); w.y = cvt_pk_bf16(v0[2], v0[3]); w.z = cvt_pk_bf16(v1[0], v1[1]); w.w = cvt_pk_bf16(v1[2], v1[3]); return w; }
; DI void transpose8(float (&v)[8], int lane) { tstage8<4>(v, lane); tstage8<2>(v, lane); tstage8<1>(v, lane); }
; template <int K> DI void tstage8(float (&v)[8], int lane) {
;   const bool up = (lane & K) != 0;
; #pragma unroll
;   for (int j = 0; j < 8; ++j) {
;     if ((j & K) == 0) {
;       const float send = up ? v[j] : v[j | K];
;       const float recv = shx(send, lane, K);
;       if (up) v[j] = recv; else v[j | K] = recv;
;     }
;   }
; }
;   DI void epi(const Acc& acc, const Unit& u, int wr, int wc, int fr, int fq, LAS unsigned char* lds) const {
;     ...
;             float vx[8] = {x0[0], x0[1], x0[2], x0[3], x1[0], x1[1], x1[2], x1[3]}, vy[8] = {y0[0], y0[1], y0[2], y0[3], y1[0], y1[1], y1[2], y1[3]};
;             const int lane = fq * 16 + fr;
;             transpose8(vx, lane); transpose8(vy, lane);
;             const int tl = rl & ~7, dk = d0 + (fr & 7);
;             const unsigned kro = (unsigned)((tl >> 7) * 4 + hd) * 65536u + (unsigned)(dk >> 5) * 8192u + (unsigned)((tl & 127) >> 4) * 1024u + (unsigned)((tl >> 3) & 1) * 512u + (unsigned)(dk & 31) * 16u;
;             st16(kT, kro, pk8((f32x4){vx[0], vx[1], vx[2], vx[3]}, (f32x4){vx[4], vx[5], vx[6], vx[7]}));
;             st16(kT, kro + 4u * 8192u, pk8((f32x4){vy[0], vy[1], vy[2], vy[3]}, (f32x4){vy[4], vy[5], vy[6], vy[7]}));
	v_cndmask_b32_e64 v82, v86, v90, s[6:7]
	ds_bpermute_b32 v109, v167, v82
	v_cndmask_b32_e64 v83, v84, v80, s[6:7]
	v_cndmask_b32_e64 v82, v87, v91, s[6:7]
	ds_bpermute_b32 v83, v167, v83
	ds_bpermute_b32 v82, v167, v82
	s_waitcnt lgkmcnt(0)
	v_cndmask_b32_e64 v100, v109, v86, s[6:7]
	v_cndmask_b32_e64 v86, v85, v81, s[6:7]
	ds_bpermute_b32 v104, v167, v86
	v_cndmask_b32_e64 v102, v83, v84, s[6:7]
	v_cndmask_b32_e64 v101, v82, v87, s[6:7]
	v_cndmask_b32_e64 v103, v80, v83, s[6:7]
	v_cndmask_b32_e64 v80, v100, v102, s[10:11]
	s_waitcnt lgkmcnt(0)
	v_cndmask_b32_e64 v107, v104, v85, s[6:7]
	ds_bpermute_b32 v84, v168, v80
	v_cndmask_b32_e64 v80, v101, v107, s[10:11]
	ds_bpermute_b32 v80, v168, v80
	v_cndmask_b32_e64 v105, v90, v109, s[6:7]
	v_cndmask_b32_e64 v91, v91, v82, s[6:7]
	v_mov_b64_e32 v[92:93], 1
	v_mov_b64_e32 v[82:83], 4
	v_cndmask_b32_e64 v106, v81, v104, s[6:7]
	v_mov_b32_e32 v93, v91
	v_mov_b64_e32 v[86:87], 1
	v_mov_b32_e32 v83, v105
	s_waitcnt lgkmcnt(0)
	v_mov_b32_e32 v108, v80
	s_and_saveexec_b64 s[0:1], s[10:11]
	v_mov_b64_e32 v[82:83], 6
	v_mov_b64_e32 v[86:87], 3
	v_mov_b32_e32 v93, v106
	v_mov_b32_e32 v83, v103
	v_mov_b32_e32 v107, v80
	v_mov_b32_e32 v108, v101
	s_or_b64 exec, exec, s[0:1]
	ds_bpermute_b32 v87, v168, v93
	ds_bpermute_b32 v83, v168, v83
	v_cndmask_b32_e64 v93, v102, v84, s[10:11]
	v_cndmask_b32_e64 v93, v93, v107, s[8:9]
	v_cndmask_b32_e64 v110, v84, v100, s[10:11]
	s_waitcnt lgkmcnt(0)
	v_cndmask_b32_e64 v113, v106, v87, s[10:11]
	ds_bpermute_b32 v106, v169, v93
	v_cndmask_b32_e64 v93, v88, v96, s[6:7]
	ds_bpermute_b32 v114, v167, v93
	v_cndmask_b32_e64 v112, v83, v105, s[10:11]
	v_cndmask_b32_e64 v115, v87, v91, s[10:11]
	v_cndmask_b32_e64 v111, v103, v83, s[10:11]
	v_cndmask_b32_e64 v93, v112, v115, s[8:9]
	ds_bpermute_b32 v107, v169, v93
	v_cndmask_b32_e64 v93, v111, v113, s[8:9]
	v_cndmask_b32_e64 v105, v110, v108, s[8:9]
	ds_bpermute_b32 v108, v169, v93
	v_cndmask_b32_e64 v93, v89, v97, s[6:7]
	s_waitcnt lgkmcnt(0)
	v_cndmask_b32_e64 v112, v96, v114, s[6:7]
	ds_bpermute_b32 v96, v167, v93
	v_cndmask_b32_e64 v93, v98, v94, s[6:7]
	ds_bpermute_b32 v93, v167, v93
	v_cndmask_b32_e64 v110, v99, v95, s[6:7]
	v_cndmask_b32_e64 v111, v114, v88, s[6:7]
	ds_bpermute_b32 v110, v167, v110
	s_waitcnt lgkmcnt(0)
	v_cndmask_b32_e64 v113, v96, v89, s[6:7]
	v_cndmask_b32_e64 v117, v93, v98, s[6:7]
	v_cndmask_b32_e64 v89, v111, v117, s[10:11]
	ds_bpermute_b32 v116, v168, v89
	ds_bpermute_b32 v105, v169, v105
	v_cndmask_b32_e64 v115, v110, v99, s[6:7]
	v_mov_b64_e32 v[98:99], 0
	v_cndmask_b32_e64 v118, v94, v93, s[6:7]
	v_mov_b32_e32 v94, v112
	v_mov_b32_e32 v99, v113
	v_mov_b32_e32 v89, v117
	s_waitcnt lgkmcnt(0)
	v_mov_b32_e32 v93, v116
	s_and_saveexec_b64 s[0:1], s[10:11]
	v_mov_b64_e32 v[98:99], 2
	v_mov_b64_e32 v[92:93], 3
	v_mov_b32_e32 v94, v118
	v_mov_b32_e32 v99, v115
	v_mov_b32_e32 v89, v116
	v_mov_b32_e32 v93, v111
	s_or_b64 exec, exec, s[0:1]
	v_cndmask_b32_e64 v96, v97, v96, s[6:7]
	v_cndmask_b32_e64 v97, v95, v110, s[6:7]
	ds_bpermute_b32 v110, v168, v94
	ds_bpermute_b32 v119, v168, v99
	v_mov_b64_e32 v[94:95], 4
	v_mov_b32_e32 v111, v96
	v_mov_b32_e32 v95, v118
	s_waitcnt lgkmcnt(0)
	v_mov_b32_e32 v99, v110
	s_and_saveexec_b64 s[0:1], s[10:11]
	v_mov_b64_e32 v[94:95], 6
	v_mov_b32_e32 v111, v97
	v_mov_b32_e32 v95, v110
	v_mov_b32_e32 v99, v112
	s_or_b64 exec, exec, s[0:1]
	v_cmp_eq_u32_e32 vcc, 3, v98
	v_cndmask_b32_e64 v90, v90, v109, s[6:7]
	v_cndmask_b32_e64 v88, v114, v88, s[6:7]
	v_cndmask_b32_e32 v109, v115, v116, vcc
	v_cmp_eq_u32_e32 vcc, 7, v98
	v_cndmask_b32_e64 v85, v104, v85, s[6:7]
	v_cndmask_b32_e64 v81, v81, v104, s[6:7]
	v_cndmask_b32_e32 v114, v97, v116, vcc
	v_cmp_eq_u32_e32 vcc, 6, v98
	v_cndmask_b32_e64 v115, v115, v119, s[10:11]
	v_cndmask_b32_e64 v89, v89, v115, s[8:9]
	v_cndmask_b32_e32 v118, v118, v116, vcc
	v_cmp_eq_u32_e32 vcc, 4, v98
	s_lshr_b32 s0, s2, 5
	ds_bpermute_b32 v89, v169, v89
	v_cndmask_b32_e32 v112, v112, v116, vcc
	v_cmp_eq_u32_e32 vcc, 2, v98
	s_and_b32 s0, s0, 0xfffc
	s_add_i32 s0, s0, s54
	v_cndmask_b32_e32 v117, v117, v116, vcc
	v_cmp_eq_u32_e32 vcc, 1, v98
	s_lshl_b32 s1, s4, 6
	s_lshl_b32 s0, s0, 16
	v_cndmask_b32_e32 v120, v113, v116, vcc
	v_cmp_eq_u32_e32 vcc, 0, v98
	v_cndmask_b32_e64 v113, v119, v113, s[10:11]
	v_cndmask_b32_e64 v93, v93, v113, s[8:9]
	v_cndmask_b32_e32 v88, v88, v116, vcc
	v_cmp_eq_u32_e32 vcc, 5, v98
	ds_bpermute_b32 v93, v169, v93
	s_and_b32 s1, s1, 0x1800
	v_cndmask_b32_e32 v98, v96, v116, vcc
	v_cmp_eq_u32_e32 vcc, 7, v92
	s_or_b32 s0, s0, s1
	v_or_b32_e32 v176, s0, v171
	v_cndmask_b32_e32 v114, v114, v119, vcc
	v_cmp_eq_u32_e32 vcc, 5, v92
	s_nop 1
	v_cndmask_b32_e32 v98, v98, v119, vcc
	v_cmp_eq_u32_e32 vcc, 0, v92
	s_nop 1
	v_cndmask_b32_e32 v88, v88, v119, vcc
	v_cmp_eq_u32_e32 vcc, 1, v92
	s_nop 1
	v_cndmask_b32_e32 v116, v120, v119, vcc
	v_cmp_eq_u32_e32 vcc, 2, v92
	s_nop 1
	v_cndmask_b32_e32 v117, v117, v119, vcc
	v_cmp_eq_u32_e32 vcc, 3, v92
	s_nop 1
	v_cndmask_b32_e32 v109, v109, v119, vcc
	v_cmp_eq_u32_e32 vcc, 4, v92
	s_nop 1
	v_cndmask_b32_e32 v112, v112, v119, vcc
	v_cmp_eq_u32_e32 vcc, 6, v92
	s_nop 1
	v_cndmask_b32_e32 v92, v118, v119, vcc
	v_cmp_eq_u32_e32 vcc, 3, v136
	s_nop 1
	v_cndmask_b32_e32 v85, v85, v84, vcc
	v_cmp_eq_u32_e32 vcc, 7, v136
	s_nop 1
	v_cndmask_b32_e32 v81, v81, v84, vcc
	v_cmp_eq_u32_e32 vcc, 6, v136
	s_nop 1
	v_cndmask_b32_e32 v103, v103, v84, vcc
	v_cmp_eq_u32_e32 vcc, 4, v136
	s_nop 1
	v_cndmask_b32_e32 v90, v90, v84, vcc
	v_cmp_eq_u32_e32 vcc, 2, v136
	s_nop 1
	v_cndmask_b32_e32 v102, v102, v84, vcc
	v_cmp_eq_u32_e32 vcc, 1, v136
	s_nop 1
	v_cndmask_b32_e32 v101, v101, v84, vcc
	v_cmp_eq_u32_e32 vcc, 0, v136
	s_nop 1
	v_cndmask_b32_e32 v100, v100, v84, vcc
	v_cmp_eq_u32_e32 vcc, 5, v136
	s_nop 1
	v_cndmask_b32_e32 v84, v91, v84, vcc
	v_cmp_eq_u32_e32 vcc, 7, v86
	s_nop 1
	v_cndmask_b32_e32 v81, v81, v80, vcc
	v_cmp_eq_u32_e32 vcc, 5, v86
	s_nop 1
	v_cndmask_b32_e32 v84, v84, v80, vcc
	v_cmp_eq_u32_e32 vcc, 0, v86
	s_nop 1
	v_cndmask_b32_e32 v91, v100, v80, vcc
	v_cmp_eq_u32_e32 vcc, 1, v86
	s_nop 1
	v_cndmask_b32_e32 v100, v101, v80, vcc
	v_cmp_eq_u32_e32 vcc, 2, v86
	s_nop 1
	v_cndmask_b32_e32 v101, v102, v80, vcc
	v_cmp_eq_u32_e32 vcc, 3, v86
	ds_bpermute_b32 v102, v168, v111
	s_waitcnt lgkmcnt(0)
; DI u32x4 pk8(const f32x4& v0, const f32x4& v1) { u32x4 w; w.x = cvt_pk_bf16(v0[0], v0[1]); w.y = cvt_pk_bf16(v0[2], v0[3]); w.z = cvt_pk_bf16(v1[0], v1[1]); w.w = cvt_pk_bf16(v1[2], v1[3]); return w; }
; DI void transpose8(float (&v)[8], int lane) { tstage8<4>(v, lane); tstage8<2>(v, lane); tstage8<1>(v, lane); }
;   DI void epi(const Acc& acc, const Unit& u, int wr, int wc, int fr, int fq, LAS unsigned char* lds) const {
;     ...
;           const int rl = u.pm * 256 + ai * 128 + wr * 64 + m * 16 + fr; const int pos = tok_pos(rb + rl);
;           const unsigned to = (unsigned)(pos * 128 + d0) * 4u; const f32x4 c0 = ldf4(cosR, to), c1 = ldf4(cosR, to + 16u);
;           const f32x4 s0 = ldf4(sinR, to), s1 = ldf4(sinR, to + 16u);
;           const f32x4 a0 = acc[ai][0][m][0], a1 = acc[ai][0][m][1], b0 = acc[ai][1][m][0], b1 = acc[ai][1][m][1];
;           const f32x4 x0 = (a0 * c0 - b0 * s0) * sc, x1 = (a1 * c1 - b1 * s1) * sc, y0 = (b0 * c0 + a0 * s0) * sc, y1 = (b1 * c1 + a1 * s1) * sc;
;           const unsigned ro = fo + (unsigned)(rl >> 7) * 262144u + (unsigned)((rl >> 5) & 3) * 16384u + (unsigned)(rl & 31) * 16u;
;           st16(base, ro, pk8(x0, x1));
;           st16(base, ro + 8192u, pk8(y0, y1));
;           if (!isq) {
;             float vx[8] = {x0[0], x0[1], x0[2], x0[3], x1[0], x1[1], x1[2], x1[3]}, vy[8] = {y0[0], y0[1], y0[2], y0[3], y1[0], y1[1], y1[2], y1[3]};
;             const int lane = fq * 16 + fr;
;             transpose8(vx, lane); transpose8(vy, lane);
;             const int tl = rl & ~7, dk = d0 + (fr & 7);
;             const unsigned kro = (unsigned)((tl >> 7) * 4 + hd) * 65536u + (unsigned)(dk >> 5) * 8192u + (unsigned)((tl & 127) >> 4) * 1024u + (unsigned)((tl >> 3) & 1) * 512u + (unsigned)(dk & 31) * 16u;
;             st16(kT, kro, pk8((f32x4){vx[0], vx[1], vx[2], vx[3]}, (f32x4){vx[4], vx[5], vx[6], vx[7]}));
;             st16(kT, kro + 4u * 8192u, pk8((f32x4){vy[0], vy[1], vy[2], vy[3]}, (f32x4){vy[4], vy[5], vy[6], vy[7]}));
	v_cndmask_b32_e64 v97, v97, v102, s[10:11]
	v_cndmask_b32_e32 v85, v85, v80, vcc
	v_cmp_eq_u32_e32 vcc, 4, v86
	v_cndmask_b32_e64 v96, v102, v96, s[10:11]
	v_cndmask_b32_e64 v96, v99, v96, s[8:9]
	v_cndmask_b32_e32 v90, v90, v80, vcc
	v_cmp_eq_u32_e32 vcc, 6, v86
	v_cndmask_b32_e64 v95, v95, v97, s[8:9]
	ds_bpermute_b32 v96, v169, v96
	v_cndmask_b32_e32 v80, v103, v80, vcc
	v_cmp_eq_u32_e32 vcc, 6, v82
	ds_bpermute_b32 v95, v169, v95
	s_nop 0
	v_cndmask_b32_e32 v80, v80, v83, vcc
	v_cmp_eq_u32_e32 vcc, 4, v82
	s_nop 1
	v_cndmask_b32_e32 v86, v90, v83, vcc
	v_cmp_eq_u32_e32 vcc, 3, v82
	v_cndmask_b32_e64 v86, v107, v86, s[8:9]
	s_nop 0
	v_cndmask_b32_e32 v85, v85, v83, vcc
	v_cmp_eq_u32_e32 vcc, 2, v82
	v_cndmask_b32_e64 v85, v85, v106, s[8:9]
	s_nop 0
	v_cndmask_b32_e32 v90, v101, v83, vcc
	v_cmp_eq_u32_e32 vcc, 1, v82
	s_nop 1
	v_cndmask_b32_e32 v100, v100, v83, vcc
	v_cmp_eq_u32_e32 vcc, 0, v82
	s_nop 1
	v_cndmask_b32_e32 v91, v91, v83, vcc
	v_cmp_eq_u32_e32 vcc, 5, v82
	s_nop 1
	v_cndmask_b32_e32 v84, v84, v83, vcc
	v_cmp_eq_u32_e32 vcc, 7, v82
	v_cndmask_b32_e64 v82, v87, v84, s[10:11]
	v_cndmask_b32_e64 v84, v100, v105, s[8:9]
	v_cndmask_b32_e32 v81, v81, v83, vcc
	v_cmp_eq_u32_e32 vcc, 6, v94
	v_cndmask_b32_e64 v81, v81, v87, s[10:11]
	v_cndmask_b32_e64 v87, v106, v90, s[8:9]
	v_cndmask_b32_e64 v90, v108, v80, s[8:9]
	v_cndmask_b32_e32 v80, v92, v110, vcc
	v_cmp_eq_u32_e32 vcc, 4, v94
	v_cndmask_b32_e64 v83, v105, v91, s[8:9]
	v_cndmask_b32_e64 v91, v81, v108, s[8:9]
	v_cndmask_b32_e32 v81, v112, v110, vcc
	v_cmp_eq_u32_e32 vcc, 3, v94
	v_cndmask_b32_e64 v82, v82, v107, s[8:9]
	s_nop 0
	v_cndmask_b32_e32 v92, v109, v110, vcc
	v_cmp_eq_u32_e32 vcc, 2, v94
	s_nop 1
	v_cndmask_b32_e32 v100, v117, v110, vcc
	v_cmp_eq_u32_e32 vcc, 1, v94
	v_cndmask_b32_e64 v97, v89, v100, s[8:9]
	v_cndmask_b32_e64 v89, v92, v89, s[8:9]
	v_cndmask_b32_e32 v101, v116, v110, vcc
	v_cmp_eq_u32_e32 vcc, 0, v94
	s_waitcnt lgkmcnt(0)
	v_cndmask_b32_e64 v92, v96, v81, s[8:9]
	v_cndmask_b32_e32 v88, v88, v110, vcc
	v_cmp_eq_u32_e32 vcc, 5, v94
	v_cndmask_b32_e64 v88, v93, v88, s[8:9]
	v_cndmask_b32_e64 v93, v101, v93, s[8:9]
	v_cndmask_b32_e32 v98, v98, v110, vcc
	v_cmp_eq_u32_e32 vcc, 7, v94
	v_cndmask_b32_e64 v98, v102, v98, s[10:11]
	v_cndmask_b32_e64 v96, v98, v96, s[8:9]
	v_cndmask_b32_e32 v94, v114, v110, vcc
	v_cndmask_b32_e64 v98, v95, v80, s[8:9]
	v_cvt_pk_bf16_f32 v80, v83, v84
	v_cvt_pk_bf16_f32 v81, v87, v85
	v_lshl_add_u64 v[84:85], s[24:25], 0, v[176:177]
	v_or_b32_e32 v176, 0x8000, v176
	v_cndmask_b32_e64 v94, v94, v102, s[10:11]
	v_cvt_pk_bf16_f32 v82, v86, v82
	v_cvt_pk_bf16_f32 v83, v90, v91
	global_store_dwordx4 v[84:85], v[80:83], off
	v_lshl_add_u64 v[84:85], s[24:25], 0, v[176:177]
	v_cndmask_b32_e64 v94, v94, v95, s[8:9]
	v_cvt_pk_bf16_f32 v80, v88, v93
	v_cvt_pk_bf16_f32 v81, v97, v89
	v_cvt_pk_bf16_f32 v82, v92, v96
	v_cvt_pk_bf16_f32 v83, v98, v94
	global_store_dwordx4 v[84:85], v[80:83], off
.LBB0_164:
	s_or_b32 s4, s2, 48
	v_or_b32_e32 v98, s4, v137
	v_add_u32_e32 v80, s34, v98
	v_cmp_gt_i32_e32 vcc, s55, v80
	v_mov_b32_e32 v81, 0xfff
	v_mov_b32_e32 v82, 0x7ff
	v_cndmask_b32_e32 v81, v81, v82, vcc
	v_and_b32_e32 v80, v81, v80
	v_lshl_or_b32 v176, v80, 9, v166
	v_lshl_add_u64 v[80:81], s[30:31], 0, v[176:177]
	global_load_dwordx4 v[82:85], v[80:81], off
	v_lshl_add_u64 v[80:81], s[28:29], 0, v[176:177]
	global_load_dwordx4 v[86:89], v[80:81], off
	v_or_b32_e32 v80, 16, v176
	v_mov_b32_e32 v81, v177
	v_lshl_add_u64 v[90:91], s[30:31], 0, v[80:81]
	global_load_dwordx4 v[90:93], v[90:91], off
	v_lshl_add_u64 v[80:81], s[28:29], 0, v[80:81]
	global_load_dwordx4 v[94:97], v[80:81], off
	s_lshl_b32 s0, s4, 9
	v_lshlrev_b32_e32 v98, 4, v98
	s_and_b32 s0, s0, 0xc000
	v_and_b32_e32 v98, 0x1f0, v98
	v_or3_b32 v176, s0, v98, v126
	v_mov_b32_e32 v80, v142
	v_mov_b32_e32 v81, v142
	v_lshl_add_u64 v[98:99], s[26:27], 0, v[176:177]
	v_or_b32_e32 v176, 0x2000, v176
	v_lshl_add_u64 v[100:101], s[26:27], 0, v[176:177]
	s_and_b64 vcc, exec, s[12:13]
	s_waitcnt vmcnt(0) lgkmcnt(0)
	v_pk_mul_f32 v[102:103], v[70:71], v[84:85]
	v_pk_mul_f32 v[104:105], v[68:69], v[82:83]
	v_pk_mul_f32 v[84:85], v[78:79], v[84:85]
	v_pk_mul_f32 v[82:83], v[76:77], v[82:83]
	v_pk_fma_f32 v[78:79], v[78:79], v[88:89], v[102:103] neg_lo:[0,0,1] neg_hi:[0,0,1]
	v_pk_fma_f32 v[76:77], v[76:77], v[86:87], v[104:105] neg_lo:[0,0,1] neg_hi:[0,0,1]
	v_pk_mul_f32 v[102:103], v[66:67], v[92:93]
	v_pk_mul_f32 v[104:105], v[64:65], v[90:91]
	v_pk_fma_f32 v[84:85], v[70:71], v[88:89], v[84:85]
	v_pk_fma_f32 v[82:83], v[68:69], v[86:87], v[82:83]
	v_pk_mul_f32 v[86:87], v[74:75], v[92:93]
	v_pk_mul_f32 v[88:89], v[72:73], v[90:91]
	v_pk_mul_f32 v[70:71], v[142:143], v[76:77]
	v_pk_fma_f32 v[74:75], v[74:75], v[96:97], v[102:103] neg_lo:[0,0,1] neg_hi:[0,0,1]
	v_pk_fma_f32 v[76:77], v[72:73], v[94:95], v[104:105] neg_lo:[0,0,1] neg_hi:[0,0,1]
	v_pk_mul_f32 v[72:73], v[142:143], v[82:83]
	v_pk_fma_f32 v[66:67], v[66:67], v[96:97], v[86:87]
	v_pk_fma_f32 v[82:83], v[64:65], v[94:95], v[88:89]
	v_pk_mul_f32 v[68:69], v[80:81], v[78:79]
	v_pk_mul_f32 v[84:85], v[80:81], v[84:85]
	v_pk_mul_f32 v[64:65], v[80:81], v[74:75]
	v_pk_mul_f32 v[74:75], v[142:143], v[76:77]
	v_pk_mul_f32 v[78:79], v[80:81], v[66:67]
	v_pk_mul_f32 v[82:83], v[142:143], v[82:83]
	v_cvt_pk_bf16_f32 v86, v70, v71
	v_cvt_pk_bf16_f32 v87, v68, v69
	v_cvt_pk_bf16_f32 v88, v74, v75
	v_cvt_pk_bf16_f32 v89, v64, v65
	global_store_dwordx4 v[98:99], v[86:89], off
	s_nop 1
	v_cvt_pk_bf16_f32 v86, v72, v73
	v_cvt_pk_bf16_f32 v87, v84, v85
	v_cvt_pk_bf16_f32 v88, v82, v83
	v_cvt_pk_bf16_f32 v89, v78, v79
	global_store_dwordx4 v[100:101], v[86:89], off
	s_cbranch_vccnz .LBB0_172
; DI float shx(float v, int lane, int mask) { return __int_as_float(__builtin_amdgcn_ds_bpermute((lane ^ mask) << 2, __float_as_int(v))); }
; DI u32x4 pk8(const f32x4& v0, const f32x4& v1) { u32x4 w; w.x = cvt_pk_bf16(v0[0], v0[1]); w.y = cvt_pk_bf16(v0[2], v0[3]); w.z = cvt_pk_bf16(v1[0], v1[1]); w.w = cvt_pk_bf16(v1[2], v1[3]); return w; }
; DI void transpose8(float (&v)[8], int lane) { tstage8<4>(v, lane); tstage8<2>(v, lane); tstage8<1>(v, lane); }
; template <int K> DI void tstage8(float (&v)[8], int lane) {
;   const bool up = (lane & K) != 0;
; #pragma unroll
;   for (int j = 0; j < 8; ++j) {
;     if ((j & K) == 0) {
;       const float send = up ? v[j] : v[j | K];
;       const float recv = shx(send, lane, K);
;       if (up) v[j] = recv; else v[j | K] = recv;
;     }
;   }
; }
;   DI void epi(const Acc& acc, const Unit& u, int wr, int wc, int fr, int fq, LAS unsigned char* lds) const {
;     ...
;             float vx[8] = {x0[0], x0[1], x0[2], x0[3], x1[0], x1[1], x1[2], x1[3]}, vy[8] = {y0[0], y0[1], y0[2], y0[3], y1[0], y1[1], y1[2], y1[3]};
;             const int lane = fq * 16 + fr;
;             transpose8(vx, lane); transpose8(vy, lane);
;             const int tl = rl & ~7, dk = d0 + (fr & 7);
;             const unsigned kro = (unsigned)((tl >> 7) * 4 + hd) * 65536u + (unsigned)(dk >> 5) * 8192u + (unsigned)((tl & 127) >> 4) * 1024u + (unsigned)((tl >> 3) & 1) * 512u + (unsigned)(dk & 31) * 16u;
;             st16(kT, kro, pk8((f32x4){vx[0], vx[1], vx[2], vx[3]}, (f32x4){vx[4], vx[5], vx[6], vx[7]}));
;             st16(kT, kro + 4u * 8192u, pk8((f32x4){vy[0], vy[1], vy[2], vy[3]}, (f32x4){vy[4], vy[5], vy[6], vy[7]}));
	v_cndmask_b32_e64 v66, v70, v74, s[6:7]
	ds_bpermute_b32 v95, v167, v66
	v_cndmask_b32_e64 v67, v68, v64, s[6:7]
	v_cndmask_b32_e64 v66, v71, v75, s[6:7]
	ds_bpermute_b32 v67, v167, v67
	ds_bpermute_b32 v66, v167, v66
	s_waitcnt lgkmcnt(0)
	v_cndmask_b32_e64 v86, v95, v70, s[6:7]
	v_cndmask_b32_e64 v70, v69, v65, s[6:7]
	ds_bpermute_b32 v90, v167, v70
	v_cndmask_b32_e64 v88, v67, v68, s[6:7]
	v_cndmask_b32_e64 v87, v66, v71, s[6:7]
	v_cndmask_b32_e64 v89, v64, v67, s[6:7]
	v_cndmask_b32_e64 v64, v86, v88, s[10:11]
	s_waitcnt lgkmcnt(0)
	v_cndmask_b32_e64 v93, v90, v69, s[6:7]
	ds_bpermute_b32 v68, v168, v64
	v_cndmask_b32_e64 v64, v87, v93, s[10:11]
	ds_bpermute_b32 v64, v168, v64
	v_cndmask_b32_e64 v91, v74, v95, s[6:7]
	v_cndmask_b32_e64 v75, v75, v66, s[6:7]
	v_mov_b64_e32 v[76:77], 1
	v_mov_b64_e32 v[66:67], 4
	v_cndmask_b32_e64 v92, v65, v90, s[6:7]
	v_mov_b32_e32 v77, v75
	v_mov_b64_e32 v[70:71], 1
	v_mov_b32_e32 v67, v91
	s_waitcnt lgkmcnt(0)
	v_mov_b32_e32 v94, v64
	s_and_saveexec_b64 s[0:1], s[10:11]
	v_mov_b64_e32 v[66:67], 6
	v_mov_b64_e32 v[70:71], 3
	v_mov_b32_e32 v77, v92
	v_mov_b32_e32 v67, v89
	v_mov_b32_e32 v93, v64
	v_mov_b32_e32 v94, v87
	s_or_b64 exec, exec, s[0:1]
	ds_bpermute_b32 v71, v168, v77
	ds_bpermute_b32 v67, v168, v67
	v_cndmask_b32_e64 v77, v88, v68, s[10:11]
	v_cndmask_b32_e64 v77, v77, v93, s[8:9]
	v_cndmask_b32_e64 v96, v68, v86, s[10:11]
	s_waitcnt lgkmcnt(0)
	v_cndmask_b32_e64 v99, v92, v71, s[10:11]
	ds_bpermute_b32 v92, v169, v77
	v_cndmask_b32_e64 v77, v72, v82, s[6:7]
	ds_bpermute_b32 v100, v167, v77
	v_cndmask_b32_e64 v98, v67, v91, s[10:11]
	v_cndmask_b32_e64 v101, v71, v75, s[10:11]
	v_cndmask_b32_e64 v97, v89, v67, s[10:11]
	v_cndmask_b32_e64 v77, v98, v101, s[8:9]
	ds_bpermute_b32 v93, v169, v77
	v_cndmask_b32_e64 v77, v97, v99, s[8:9]
	v_cndmask_b32_e64 v91, v96, v94, s[8:9]
	ds_bpermute_b32 v94, v169, v77
	v_cndmask_b32_e64 v77, v73, v83, s[6:7]
	s_waitcnt lgkmcnt(0)
	v_cndmask_b32_e64 v98, v82, v100, s[6:7]
	ds_bpermute_b32 v82, v167, v77
	v_cndmask_b32_e64 v77, v84, v78, s[6:7]
	ds_bpermute_b32 v77, v167, v77
	v_cndmask_b32_e64 v96, v85, v79, s[6:7]
	v_cndmask_b32_e64 v97, v100, v72, s[6:7]
	ds_bpermute_b32 v96, v167, v96
	s_waitcnt lgkmcnt(0)
	v_cndmask_b32_e64 v99, v82, v73, s[6:7]
	v_cndmask_b32_e64 v103, v77, v84, s[6:7]
	v_cndmask_b32_e64 v73, v97, v103, s[10:11]
	ds_bpermute_b32 v102, v168, v73
	ds_bpermute_b32 v91, v169, v91
	v_cndmask_b32_e64 v101, v96, v85, s[6:7]
	v_mov_b64_e32 v[84:85], 0
	v_cndmask_b32_e64 v104, v78, v77, s[6:7]
	v_mov_b32_e32 v78, v98
	v_mov_b32_e32 v85, v99
	v_mov_b32_e32 v73, v103
	s_waitcnt lgkmcnt(0)
	v_mov_b32_e32 v77, v102
	s_and_saveexec_b64 s[0:1], s[10:11]
	v_mov_b64_e32 v[84:85], 2
	v_mov_b64_e32 v[76:77], 3
	v_mov_b32_e32 v78, v104
	v_mov_b32_e32 v85, v101
	v_mov_b32_e32 v73, v102
	v_mov_b32_e32 v77, v97
	s_or_b64 exec, exec, s[0:1]
	v_cndmask_b32_e64 v82, v83, v82, s[6:7]
	v_cndmask_b32_e64 v83, v79, v96, s[6:7]
	ds_bpermute_b32 v96, v168, v78
	ds_bpermute_b32 v105, v168, v85
	v_mov_b64_e32 v[78:79], 4
	v_mov_b32_e32 v97, v82
	v_mov_b32_e32 v79, v104
	s_waitcnt lgkmcnt(0)
	v_mov_b32_e32 v85, v96
	s_and_saveexec_b64 s[0:1], s[10:11]
	v_mov_b64_e32 v[78:79], 6
	v_mov_b32_e32 v97, v83
	v_mov_b32_e32 v79, v96
	v_mov_b32_e32 v85, v98
	s_or_b64 exec, exec, s[0:1]
	v_cmp_eq_u32_e32 vcc, 3, v84
	v_cndmask_b32_e64 v74, v74, v95, s[6:7]
	v_cndmask_b32_e64 v72, v100, v72, s[6:7]
	v_cndmask_b32_e32 v95, v101, v102, vcc
	v_cmp_eq_u32_e32 vcc, 7, v84
	v_cndmask_b32_e64 v69, v90, v69, s[6:7]
	v_cndmask_b32_e64 v65, v65, v90, s[6:7]
	v_cndmask_b32_e32 v100, v83, v102, vcc
	v_cmp_eq_u32_e32 vcc, 6, v84
	v_cndmask_b32_e64 v101, v101, v105, s[10:11]
	v_cndmask_b32_e64 v73, v73, v101, s[8:9]
	v_cndmask_b32_e32 v104, v104, v102, vcc
	v_cmp_eq_u32_e32 vcc, 4, v84
	s_lshr_b32 s0, s2, 5
	ds_bpermute_b32 v73, v169, v73
	v_cndmask_b32_e32 v98, v98, v102, vcc
	v_cmp_eq_u32_e32 vcc, 2, v84
	s_and_b32 s0, s0, 0xfffc
	s_add_i32 s0, s0, s54
	v_cndmask_b32_e32 v103, v103, v102, vcc
	v_cmp_eq_u32_e32 vcc, 1, v84
	s_lshl_b32 s1, s4, 6
	s_lshl_b32 s0, s0, 16
	v_cndmask_b32_e32 v106, v99, v102, vcc
	v_cmp_eq_u32_e32 vcc, 0, v84
	v_cndmask_b32_e64 v99, v105, v99, s[10:11]
	v_cndmask_b32_e64 v77, v77, v99, s[8:9]
	v_cndmask_b32_e32 v72, v72, v102, vcc
	v_cmp_eq_u32_e32 vcc, 5, v84
	ds_bpermute_b32 v77, v169, v77
	s_and_b32 s1, s1, 0x1c00
	v_cndmask_b32_e32 v84, v82, v102, vcc
	v_cmp_eq_u32_e32 vcc, 7, v76
	s_or_b32 s0, s0, s1
	v_or_b32_e32 v176, s0, v171
	v_cndmask_b32_e32 v100, v100, v105, vcc
	v_cmp_eq_u32_e32 vcc, 5, v76
	s_nop 1
	v_cndmask_b32_e32 v84, v84, v105, vcc
	v_cmp_eq_u32_e32 vcc, 0, v76
	s_nop 1
	v_cndmask_b32_e32 v72, v72, v105, vcc
	v_cmp_eq_u32_e32 vcc, 1, v76
	s_nop 1
	v_cndmask_b32_e32 v102, v106, v105, vcc
	v_cmp_eq_u32_e32 vcc, 2, v76
	s_nop 1
	v_cndmask_b32_e32 v103, v103, v105, vcc
	v_cmp_eq_u32_e32 vcc, 3, v76
	s_nop 1
	v_cndmask_b32_e32 v95, v95, v105, vcc
	v_cmp_eq_u32_e32 vcc, 4, v76
	s_nop 1
	v_cndmask_b32_e32 v98, v98, v105, vcc
	v_cmp_eq_u32_e32 vcc, 6, v76
	s_nop 1
	v_cndmask_b32_e32 v76, v104, v105, vcc
	v_cmp_eq_u32_e32 vcc, 3, v136
	s_nop 1
	v_cndmask_b32_e32 v69, v69, v68, vcc
	v_cmp_eq_u32_e32 vcc, 7, v136
	s_nop 1
	v_cndmask_b32_e32 v65, v65, v68, vcc
	v_cmp_eq_u32_e32 vcc, 6, v136
	s_nop 1
	v_cndmask_b32_e32 v89, v89, v68, vcc
	v_cmp_eq_u32_e32 vcc, 4, v136
	s_nop 1
	v_cndmask_b32_e32 v74, v74, v68, vcc
	v_cmp_eq_u32_e32 vcc, 2, v136
	s_nop 1
	v_cndmask_b32_e32 v88, v88, v68, vcc
	v_cmp_eq_u32_e32 vcc, 1, v136
	s_nop 1
	v_cndmask_b32_e32 v87, v87, v68, vcc
	v_cmp_eq_u32_e32 vcc, 0, v136
	s_nop 1
	v_cndmask_b32_e32 v86, v86, v68, vcc
	v_cmp_eq_u32_e32 vcc, 5, v136
	s_nop 1
	v_cndmask_b32_e32 v68, v75, v68, vcc
	v_cmp_eq_u32_e32 vcc, 7, v70
	s_nop 1
	v_cndmask_b32_e32 v65, v65, v64, vcc
	v_cmp_eq_u32_e32 vcc, 5, v70
	s_nop 1
	v_cndmask_b32_e32 v68, v68, v64, vcc
	v_cmp_eq_u32_e32 vcc, 0, v70
	s_nop 1
	v_cndmask_b32_e32 v75, v86, v64, vcc
	v_cmp_eq_u32_e32 vcc, 1, v70
	s_nop 1
	v_cndmask_b32_e32 v86, v87, v64, vcc
	v_cmp_eq_u32_e32 vcc, 2, v70
	s_nop 1
	v_cndmask_b32_e32 v87, v88, v64, vcc
	v_cmp_eq_u32_e32 vcc, 3, v70
	ds_bpermute_b32 v88, v168, v97
	s_waitcnt lgkmcnt(0)
; DI u32x4 pk8(const f32x4& v0, const f32x4& v1) { u32x4 w; w.x = cvt_pk_bf16(v0[0], v0[1]); w.y = cvt_pk_bf16(v0[2], v0[3]); w.z = cvt_pk_bf16(v1[0], v1[1]); w.w = cvt_pk_bf16(v1[2], v1[3]); return w; }
; DI void transpose8(float (&v)[8], int lane) { tstage8<4>(v, lane); tstage8<2>(v, lane); tstage8<1>(v, lane); }
;   DI void epi(const Acc& acc, const Unit& u, int wr, int wc, int fr, int fq, LAS unsigned char* lds) const {
;     ...
;           const int rl = u.pm * 256 + ai * 128 + wr * 64 + m * 16 + fr; const int pos = tok_pos(rb + rl);
;           const unsigned to = (unsigned)(pos * 128 + d0) * 4u; const f32x4 c0 = ldf4(cosR, to), c1 = ldf4(cosR, to + 16u);
;           const f32x4 s0 = ldf4(sinR, to), s1 = ldf4(sinR, to + 16u);
;           const f32x4 a0 = acc[ai][0][m][0], a1 = acc[ai][0][m][1], b0 = acc[ai][1][m][0], b1 = acc[ai][1][m][1];
;           const f32x4 x0 = (a0 * c0 - b0 * s0) * sc, x1 = (a1 * c1 - b1 * s1) * sc, y0 = (b0 * c0 + a0 * s0) * sc, y1 = (b1 * c1 + a1 * s1) * sc;
;           const unsigned ro = fo + (unsigned)(rl >> 7) * 262144u + (unsigned)((rl >> 5) & 3) * 16384u + (unsigned)(rl & 31) * 16u;
;           st16(base, ro, pk8(x0, x1));
;           st16(base, ro + 8192u, pk8(y0, y1));
;           if (!isq) {
;             float vx[8] = {x0[0], x0[1], x0[2], x0[3], x1[0], x1[1], x1[2], x1[3]}, vy[8] = {y0[0], y0[1], y0[2], y0[3], y1[0], y1[1], y1[2], y1[3]};
;             const int lane = fq * 16 + fr;
;             transpose8(vx, lane); transpose8(vy, lane);
;             const int tl = rl & ~7, dk = d0 + (fr & 7);
;             const unsigned kro = (unsigned)((tl >> 7) * 4 + hd) * 65536u + (unsigned)(dk >> 5) * 8192u + (unsigned)((tl & 127) >> 4) * 1024u + (unsigned)((tl >> 3) & 1) * 512u + (unsigned)(dk & 31) * 16u;
;             st16(kT, kro, pk8((f32x4){vx[0], vx[1], vx[2], vx[3]}, (f32x4){vx[4], vx[5], vx[6], vx[7]}));
;             st16(kT, kro + 4u * 8192u, pk8((f32x4){vy[0], vy[1], vy[2], vy[3]}, (f32x4){vy[4], vy[5], vy[6], vy[7]}));
	v_cndmask_b32_e64 v83, v83, v88, s[10:11]
	v_cndmask_b32_e32 v69, v69, v64, vcc
	v_cmp_eq_u32_e32 vcc, 4, v70
	v_cndmask_b32_e64 v82, v88, v82, s[10:11]
	v_cndmask_b32_e64 v82, v85, v82, s[8:9]
	v_cndmask_b32_e32 v74, v74, v64, vcc
	v_cmp_eq_u32_e32 vcc, 6, v70
	v_cndmask_b32_e64 v79, v79, v83, s[8:9]
	ds_bpermute_b32 v82, v169, v82
	v_cndmask_b32_e32 v64, v89, v64, vcc
	v_cmp_eq_u32_e32 vcc, 6, v66
	ds_bpermute_b32 v79, v169, v79
	s_nop 0
	v_cndmask_b32_e32 v64, v64, v67, vcc
	v_cmp_eq_u32_e32 vcc, 4, v66
	s_nop 1
	v_cndmask_b32_e32 v70, v74, v67, vcc
	v_cmp_eq_u32_e32 vcc, 3, v66
	v_cndmask_b32_e64 v70, v93, v70, s[8:9]
	s_nop 0
	v_cndmask_b32_e32 v69, v69, v67, vcc
	v_cmp_eq_u32_e32 vcc, 2, v66
	v_cndmask_b32_e64 v69, v69, v92, s[8:9]
	s_nop 0
	v_cndmask_b32_e32 v74, v87, v67, vcc
	v_cmp_eq_u32_e32 vcc, 1, v66
	s_nop 1
	v_cndmask_b32_e32 v86, v86, v67, vcc
	v_cmp_eq_u32_e32 vcc, 0, v66
	s_nop 1
	v_cndmask_b32_e32 v75, v75, v67, vcc
	v_cmp_eq_u32_e32 vcc, 5, v66
	s_nop 1
	v_cndmask_b32_e32 v68, v68, v67, vcc
	v_cmp_eq_u32_e32 vcc, 7, v66
	v_cndmask_b32_e64 v66, v71, v68, s[10:11]
	v_cndmask_b32_e64 v68, v86, v91, s[8:9]
	v_cndmask_b32_e32 v65, v65, v67, vcc
	v_cmp_eq_u32_e32 vcc, 6, v78
	v_cndmask_b32_e64 v65, v65, v71, s[10:11]
	v_cndmask_b32_e64 v71, v92, v74, s[8:9]
	v_cndmask_b32_e64 v74, v94, v64, s[8:9]
	v_cndmask_b32_e32 v64, v76, v96, vcc
	v_cmp_eq_u32_e32 vcc, 4, v78
	v_cndmask_b32_e64 v67, v91, v75, s[8:9]
	v_cndmask_b32_e64 v75, v65, v94, s[8:9]
	v_cndmask_b32_e32 v65, v98, v96, vcc
	v_cmp_eq_u32_e32 vcc, 3, v78
	v_cndmask_b32_e64 v66, v66, v93, s[8:9]
	s_nop 0
	v_cndmask_b32_e32 v76, v95, v96, vcc
	v_cmp_eq_u32_e32 vcc, 2, v78
	s_nop 1
	v_cndmask_b32_e32 v86, v103, v96, vcc
	v_cmp_eq_u32_e32 vcc, 1, v78
	v_cndmask_b32_e64 v83, v73, v86, s[8:9]
	v_cndmask_b32_e64 v73, v76, v73, s[8:9]
	v_cndmask_b32_e32 v87, v102, v96, vcc
	v_cmp_eq_u32_e32 vcc, 0, v78
	s_waitcnt lgkmcnt(0)
	v_cndmask_b32_e64 v76, v82, v65, s[8:9]
	v_cndmask_b32_e32 v72, v72, v96, vcc
	v_cmp_eq_u32_e32 vcc, 5, v78
	v_cndmask_b32_e64 v72, v77, v72, s[8:9]
	v_cndmask_b32_e64 v77, v87, v77, s[8:9]
	v_cndmask_b32_e32 v84, v84, v96, vcc
	v_cmp_eq_u32_e32 vcc, 7, v78
	v_cndmask_b32_e64 v84, v88, v84, s[10:11]
	v_cndmask_b32_e64 v82, v84, v82, s[8:9]
	v_cndmask_b32_e32 v78, v100, v96, vcc
	v_cndmask_b32_e64 v84, v79, v64, s[8:9]
	v_cvt_pk_bf16_f32 v64, v67, v68
	v_cvt_pk_bf16_f32 v65, v71, v69
	v_lshl_add_u64 v[68:69], s[24:25], 0, v[176:177]
	v_or_b32_e32 v176, 0x8000, v176
	v_cndmask_b32_e64 v78, v78, v88, s[10:11]
	v_cvt_pk_bf16_f32 v66, v70, v66
	v_cvt_pk_bf16_f32 v67, v74, v75
	global_store_dwordx4 v[68:69], v[64:67], off
	v_lshl_add_u64 v[68:69], s[24:25], 0, v[176:177]
	v_cndmask_b32_e64 v78, v78, v79, s[8:9]
	v_cvt_pk_bf16_f32 v64, v72, v77
	v_cvt_pk_bf16_f32 v65, v83, v73
	v_cvt_pk_bf16_f32 v66, v76, v82
	v_cvt_pk_bf16_f32 v67, v84, v78
	global_store_dwordx4 v[68:69], v[64:67], off
.LBB0_172:
	s_addk_i32 s2, 0x80
	s_nop 0
	v_or_b32_e32 v64, s2, v137
	v_add_u32_e32 v64, s34, v64
	v_cmp_gt_i32_e32 vcc, s55, v64
	v_mov_b32_e32 v65, 0xfcf
	v_mov_b32_e32 v66, 0x7cf
	v_cndmask_b32_e32 v65, v65, v66, vcc
	v_and_b32_e32 v64, v65, v64
	v_lshl_or_b32 v176, v64, 9, v166
	v_lshl_add_u64 v[64:65], s[28:29], 0, v[176:177]
	global_load_dwordx4 v[72:75], v[64:65], off
	v_or_b32_e32 v64, 16, v176
	v_mov_b32_e32 v65, v177
	v_lshl_add_u64 v[66:67], s[28:29], 0, v[64:65]
	v_lshl_add_u64 v[64:65], s[30:31], 0, v[64:65]
	global_load_dwordx4 v[76:79], v[66:67], off
	global_load_dwordx4 v[86:89], v[64:65], off
	v_lshl_add_u64 v[66:67], s[30:31], 0, v[176:177]
	global_load_dwordx4 v[82:85], v[66:67], off
	s_lshl_b32 s0, s2, 11
	s_and_b32 s0, s0, 0xfffc0000
	s_and_b64 vcc, exec, s[12:13]
	s_waitcnt vmcnt(0) lgkmcnt(0)
	v_pk_mul_f32 v[68:69], v[48:49], v[86:87]
	s_nop 0
	v_pk_fma_f32 v[68:69], v[56:57], v[76:77], v[68:69] neg_lo:[0,0,1] neg_hi:[0,0,1]
	v_pk_mul_f32 v[64:65], v[54:55], v[84:85]
	v_pk_mul_f32 v[66:67], v[52:53], v[82:83]
	v_pk_fma_f32 v[64:65], v[62:63], v[74:75], v[64:65] neg_lo:[0,0,1] neg_hi:[0,0,1]
	v_pk_mul_f32 v[62:63], v[62:63], v[84:85]
	v_pk_fma_f32 v[66:67], v[60:61], v[72:73], v[66:67] neg_lo:[0,0,1] neg_hi:[0,0,1]
	v_pk_fma_f32 v[54:55], v[54:55], v[74:75], v[62:63]
	v_add_u32_e32 v62, s0, v174
	v_pk_mul_f32 v[70:71], v[142:143], v[66:67]
	v_pk_mul_f32 v[66:67], v[50:51], v[88:89]
	v_or_b32_e32 v63, s46, v62
	v_pk_fma_f32 v[66:67], v[58:59], v[78:79], v[66:67] neg_lo:[0,0,1] neg_hi:[0,0,1]
	v_pk_mul_f32 v[60:61], v[60:61], v[82:83]
	v_pk_mul_f32 v[58:59], v[58:59], v[88:89]
	v_pk_mul_f32 v[56:57], v[56:57], v[86:87]
	v_or_b32_e32 v176, v63, v154
	v_pk_fma_f32 v[52:53], v[52:53], v[72:73], v[60:61]
	v_pk_fma_f32 v[50:51], v[50:51], v[78:79], v[58:59]
	v_pk_fma_f32 v[56:57], v[48:49], v[76:77], v[56:57]
	v_lshl_add_u64 v[60:61], s[26:27], 0, v[176:177]
	v_or_b32_e32 v176, 0x2000, v176
	v_pk_mul_f32 v[64:65], v[80:81], v[64:65]
	v_pk_mul_f32 v[66:67], v[80:81], v[66:67]
	v_pk_mul_f32 v[68:69], v[142:143], v[68:69]
	v_pk_mul_f32 v[54:55], v[80:81], v[54:55]
	v_pk_mul_f32 v[52:53], v[142:143], v[52:53]
	v_pk_mul_f32 v[48:49], v[80:81], v[50:51]
	v_pk_mul_f32 v[50:51], v[142:143], v[56:57]
	v_cvt_pk_bf16_f32 v56, v70, v71
	v_cvt_pk_bf16_f32 v57, v64, v65
	v_cvt_pk_bf16_f32 v58, v68, v69
	v_cvt_pk_bf16_f32 v59, v66, v67
	global_store_dwordx4 v[60:61], v[56:59], off
	v_lshl_add_u64 v[60:61], s[26:27], 0, v[176:177]
	s_nop 0
	v_cvt_pk_bf16_f32 v56, v52, v53
	v_cvt_pk_bf16_f32 v57, v54, v55
	v_cvt_pk_bf16_f32 v58, v50, v51
	v_cvt_pk_bf16_f32 v59, v48, v49
	global_store_dwordx4 v[60:61], v[56:59], off
	s_cbranch_vccnz .LBB0_180
; DI float shx(float v, int lane, int mask) { return __int_as_float(__builtin_amdgcn_ds_bpermute((lane ^ mask) << 2, __float_as_int(v))); }
; DI u32x4 pk8(const f32x4& v0, const f32x4& v1) { u32x4 w; w.x = cvt_pk_bf16(v0[0], v0[1]); w.y = cvt_pk_bf16(v0[2], v0[3]); w.z = cvt_pk_bf16(v1[0], v1[1]); w.w = cvt_pk_bf16(v1[2], v1[3]); return w; }
; DI void transpose8(float (&v)[8], int lane) { tstage8<4>(v, lane); tstage8<2>(v, lane); tstage8<1>(v, lane); }
; template <int K> DI void tstage8(float (&v)[8], int lane) {
;   const bool up = (lane & K) != 0;
; #pragma unroll
;   for (int j = 0; j < 8; ++j) {
;     if ((j & K) == 0) {
;       const float send = up ? v[j] : v[j | K];
;       const float recv = shx(send, lane, K);
;       if (up) v[j] = recv; else v[j | K] = recv;
;     }
;   }
; }
;   DI void epi(const Acc& acc, const Unit& u, int wr, int wc, int fr, int fq, LAS unsigned char* lds) const {
;     ...
;             float vx[8] = {x0[0], x0[1], x0[2], x0[3], x1[0], x1[1], x1[2], x1[3]}, vy[8] = {y0[0], y0[1], y0[2], y0[3], y1[0], y1[1], y1[2], y1[3]};
;             const int lane = fq * 16 + fr;
;             transpose8(vx, lane); transpose8(vy, lane);
;             const int tl = rl & ~7, dk = d0 + (fr & 7);
;             const unsigned kro = (unsigned)((tl >> 7) * 4 + hd) * 65536u + (unsigned)(dk >> 5) * 8192u + (unsigned)((tl & 127) >> 4) * 1024u + (unsigned)((tl >> 3) & 1) * 512u + (unsigned)(dk & 31) * 16u;
;             st16(kT, kro, pk8((f32x4){vx[0], vx[1], vx[2], vx[3]}, (f32x4){vx[4], vx[5], vx[6], vx[7]}));
;             st16(kT, kro + 4u * 8192u, pk8((f32x4){vy[0], vy[1], vy[2], vy[3]}, (f32x4){vy[4], vy[5], vy[6], vy[7]}));
	s_nop 0
	v_cndmask_b32_e64 v56, v70, v68, s[6:7]
	v_cndmask_b32_e64 v57, v64, v66, s[6:7]
	ds_bpermute_b32 v79, v167, v56
	v_cndmask_b32_e64 v56, v71, v69, s[6:7]
	ds_bpermute_b32 v57, v167, v57
	v_cndmask_b32_e64 v58, v65, v67, s[6:7]
	ds_bpermute_b32 v56, v167, v56
	ds_bpermute_b32 v74, v167, v58
	s_waitcnt lgkmcnt(0)
	v_cndmask_b32_e64 v70, v79, v70, s[6:7]
	v_cndmask_b32_e64 v72, v57, v64, s[6:7]
	v_cndmask_b32_e64 v73, v66, v57, s[6:7]
	v_cndmask_b32_e64 v69, v69, v56, s[6:7]
	v_cndmask_b32_e64 v71, v56, v71, s[6:7]
	v_cndmask_b32_e64 v77, v74, v65, s[6:7]
	v_cndmask_b32_e64 v56, v70, v72, s[10:11]
	ds_bpermute_b32 v66, v168, v56
	v_cndmask_b32_e64 v56, v71, v77, s[10:11]
	ds_bpermute_b32 v64, v168, v56
	v_cndmask_b32_e64 v75, v68, v79, s[6:7]
	v_mov_b64_e32 v[60:61], 1
	v_mov_b64_e32 v[56:57], 4
	v_cndmask_b32_e64 v76, v67, v74, s[6:7]
	v_mov_b32_e32 v61, v69
	v_mov_b64_e32 v[58:59], 1
	v_mov_b32_e32 v57, v75
	s_waitcnt lgkmcnt(0)
	v_mov_b32_e32 v78, v64
	s_and_saveexec_b64 s[0:1], s[10:11]
	v_mov_b64_e32 v[56:57], 6
	v_mov_b64_e32 v[58:59], 3
	v_mov_b32_e32 v61, v76
	v_mov_b32_e32 v57, v73
	v_mov_b32_e32 v77, v64
	v_mov_b32_e32 v78, v71
	s_or_b64 exec, exec, s[0:1]
	ds_bpermute_b32 v59, v168, v61
	v_cndmask_b32_e64 v61, v72, v66, s[10:11]
	v_cndmask_b32_e64 v61, v61, v77, s[8:9]
	ds_bpermute_b32 v57, v168, v57
	v_cndmask_b32_e64 v80, v66, v70, s[10:11]
	s_waitcnt lgkmcnt(0)
	v_cndmask_b32_e64 v83, v76, v59, s[10:11]
	ds_bpermute_b32 v76, v169, v61
	v_cndmask_b32_e64 v61, v52, v50, s[6:7]
	ds_bpermute_b32 v84, v167, v61
	v_cndmask_b32_e64 v82, v57, v75, s[10:11]
	v_cndmask_b32_e64 v85, v59, v69, s[10:11]
	v_cndmask_b32_e64 v61, v82, v85, s[8:9]
	v_cndmask_b32_e64 v75, v80, v78, s[8:9]
	s_waitcnt lgkmcnt(0)
	v_cndmask_b32_e64 v82, v50, v84, s[6:7]
	v_cndmask_b32_e64 v50, v53, v51, s[6:7]
	ds_bpermute_b32 v80, v167, v50
	v_cndmask_b32_e64 v50, v54, v48, s[6:7]
	ds_bpermute_b32 v50, v167, v50
	v_cndmask_b32_e64 v81, v73, v57, s[10:11]
	ds_bpermute_b32 v77, v169, v61
	v_cndmask_b32_e64 v61, v81, v83, s[8:9]
	v_cndmask_b32_e64 v89, v84, v52, s[6:7]
	s_waitcnt lgkmcnt(0)
	v_cndmask_b32_e64 v87, v50, v54, s[6:7]
	ds_bpermute_b32 v78, v169, v61
	v_cndmask_b32_e64 v61, v55, v49, s[6:7]
	v_cndmask_b32_e64 v88, v48, v50, s[6:7]
	v_cndmask_b32_e64 v48, v89, v87, s[10:11]
	ds_bpermute_b32 v81, v167, v61
	ds_bpermute_b32 v86, v168, v48
	ds_bpermute_b32 v75, v169, v75
	v_cndmask_b32_e64 v83, v80, v53, s[6:7]
	v_mov_b32_e32 v48, v82
	s_waitcnt lgkmcnt(0)
	v_cndmask_b32_e64 v85, v81, v55, s[6:7]
	v_mov_b64_e32 v[54:55], 0
	v_mov_b32_e32 v61, v83
	v_mov_b32_e32 v50, v87
	v_mov_b32_e32 v53, v86
	s_and_saveexec_b64 s[0:1], s[10:11]
	v_mov_b64_e32 v[60:61], 3
	v_mov_b64_e32 v[54:55], 2
	v_mov_b32_e32 v48, v88
	v_mov_b32_e32 v61, v85
	v_mov_b32_e32 v50, v86
	v_mov_b32_e32 v53, v89
	s_or_b64 exec, exec, s[0:1]
	v_cndmask_b32_e64 v51, v51, v80, s[6:7]
	ds_bpermute_b32 v80, v168, v48
	ds_bpermute_b32 v89, v168, v61
	v_cndmask_b32_e64 v55, v49, v81, s[6:7]
	v_mov_b64_e32 v[48:49], 4
	v_mov_b32_e32 v81, v51
	v_mov_b32_e32 v49, v88
	s_waitcnt lgkmcnt(0)
	v_mov_b32_e32 v61, v80
	s_and_saveexec_b64 s[0:1], s[10:11]
	v_mov_b64_e32 v[48:49], 6
	v_mov_b32_e32 v81, v55
	v_mov_b32_e32 v49, v80
	v_mov_b32_e32 v61, v82
	s_or_b64 exec, exec, s[0:1]
	v_cmp_eq_u32_e32 vcc, 3, v54
	v_cndmask_b32_e64 v68, v68, v79, s[6:7]
	v_cndmask_b32_e64 v52, v84, v52, s[6:7]
	v_cndmask_b32_e32 v79, v85, v86, vcc
	v_cmp_eq_u32_e32 vcc, 7, v54
	v_cndmask_b32_e64 v65, v74, v65, s[6:7]
	v_cndmask_b32_e64 v67, v67, v74, s[6:7]
	v_cndmask_b32_e32 v84, v55, v86, vcc
	v_cmp_eq_u32_e32 vcc, 6, v54
	v_cndmask_b32_e64 v85, v85, v89, s[10:11]
	v_cndmask_b32_e64 v50, v50, v85, s[8:9]
	v_cndmask_b32_e32 v88, v88, v86, vcc
	v_cmp_eq_u32_e32 vcc, 4, v54
	ds_bpermute_b32 v50, v169, v50
	s_lshr_b32 s0, s2, 5
	v_cndmask_b32_e32 v82, v82, v86, vcc
	v_cmp_eq_u32_e32 vcc, 2, v54
	s_and_b32 s0, s0, 0xfffc
	s_add_i32 s0, s0, s54
	v_cndmask_b32_e32 v87, v87, v86, vcc
	v_cmp_eq_u32_e32 vcc, 1, v54
	v_lshl_or_b32 v176, s0, 16, v172
	s_nop 0
	v_cndmask_b32_e32 v90, v83, v86, vcc
	v_cmp_eq_u32_e32 vcc, 0, v54
	v_cndmask_b32_e64 v83, v89, v83, s[10:11]
	v_cndmask_b32_e64 v53, v53, v83, s[8:9]
	v_cndmask_b32_e32 v52, v52, v86, vcc
	v_cmp_eq_u32_e32 vcc, 5, v54
	ds_bpermute_b32 v53, v169, v53
	s_nop 0
	v_cndmask_b32_e32 v54, v51, v86, vcc
	v_cmp_eq_u32_e32 vcc, 7, v60
	s_nop 1
	v_cndmask_b32_e32 v84, v84, v89, vcc
	v_cmp_eq_u32_e32 vcc, 5, v60
	s_nop 1
	v_cndmask_b32_e32 v54, v54, v89, vcc
	v_cmp_eq_u32_e32 vcc, 0, v60
	s_nop 1
	v_cndmask_b32_e32 v52, v52, v89, vcc
	v_cmp_eq_u32_e32 vcc, 1, v60
	s_nop 1
	v_cndmask_b32_e32 v86, v90, v89, vcc
	v_cmp_eq_u32_e32 vcc, 2, v60
	s_nop 1
	v_cndmask_b32_e32 v87, v87, v89, vcc
	v_cmp_eq_u32_e32 vcc, 3, v60
	s_nop 1
	v_cndmask_b32_e32 v79, v79, v89, vcc
	v_cmp_eq_u32_e32 vcc, 4, v60
	s_nop 1
	v_cndmask_b32_e32 v82, v82, v89, vcc
	v_cmp_eq_u32_e32 vcc, 6, v60
	s_nop 1
	v_cndmask_b32_e32 v60, v88, v89, vcc
	v_cmp_eq_u32_e32 vcc, 3, v136
	s_nop 1
	v_cndmask_b32_e32 v65, v65, v66, vcc
	v_cmp_eq_u32_e32 vcc, 7, v136
	s_nop 1
	v_cndmask_b32_e32 v67, v67, v66, vcc
	v_cmp_eq_u32_e32 vcc, 6, v136
	s_nop 1
	v_cndmask_b32_e32 v73, v73, v66, vcc
	v_cmp_eq_u32_e32 vcc, 4, v136
	s_nop 1
	v_cndmask_b32_e32 v68, v68, v66, vcc
	v_cmp_eq_u32_e32 vcc, 2, v136
	s_nop 1
	v_cndmask_b32_e32 v72, v72, v66, vcc
	v_cmp_eq_u32_e32 vcc, 1, v136
	s_nop 1
	v_cndmask_b32_e32 v71, v71, v66, vcc
	v_cmp_eq_u32_e32 vcc, 0, v136
	s_nop 1
	v_cndmask_b32_e32 v70, v70, v66, vcc
	v_cmp_eq_u32_e32 vcc, 5, v136
	s_nop 1
	v_cndmask_b32_e32 v66, v69, v66, vcc
	v_cmp_eq_u32_e32 vcc, 7, v58
	s_nop 1
	v_cndmask_b32_e32 v67, v67, v64, vcc
	v_cmp_eq_u32_e32 vcc, 5, v58
	s_nop 1
	v_cndmask_b32_e32 v66, v66, v64, vcc
	v_cmp_eq_u32_e32 vcc, 0, v58
	s_nop 1
	v_cndmask_b32_e32 v69, v70, v64, vcc
	v_cmp_eq_u32_e32 vcc, 1, v58
	s_nop 1
	v_cndmask_b32_e32 v70, v71, v64, vcc
	v_cmp_eq_u32_e32 vcc, 2, v58
	s_nop 1
	v_cndmask_b32_e32 v71, v72, v64, vcc
	v_cmp_eq_u32_e32 vcc, 3, v58
	ds_bpermute_b32 v72, v168, v81
	s_waitcnt lgkmcnt(0)
; DI u32x4 pk8(const f32x4& v0, const f32x4& v1) { u32x4 w; w.x = cvt_pk_bf16(v0[0], v0[1]); w.y = cvt_pk_bf16(v0[2], v0[3]); w.z = cvt_pk_bf16(v1[0], v1[1]); w.w = cvt_pk_bf16(v1[2], v1[3]); return w; }
; DI void transpose8(float (&v)[8], int lane) { tstage8<4>(v, lane); tstage8<2>(v, lane); tstage8<1>(v, lane); }
;   DI void epi(const Acc& acc, const Unit& u, int wr, int wc, int fr, int fq, LAS unsigned char* lds) const {
;     ...
;           const int rl = u.pm * 256 + ai * 128 + wr * 64 + m * 16 + fr; const int pos = tok_pos(rb + rl);
;           const unsigned to = (unsigned)(pos * 128 + d0) * 4u; const f32x4 c0 = ldf4(cosR, to), c1 = ldf4(cosR, to + 16u);
;           const f32x4 s0 = ldf4(sinR, to), s1 = ldf4(sinR, to + 16u);
;           const f32x4 a0 = acc[ai][0][m][0], a1 = acc[ai][0][m][1], b0 = acc[ai][1][m][0], b1 = acc[ai][1][m][1];
;           const f32x4 x0 = (a0 * c0 - b0 * s0) * sc, x1 = (a1 * c1 - b1 * s1) * sc, y0 = (b0 * c0 + a0 * s0) * sc, y1 = (b1 * c1 + a1 * s1) * sc;
;           const unsigned ro = fo + (unsigned)(rl >> 7) * 262144u + (unsigned)((rl >> 5) & 3) * 16384u + (unsigned)(rl & 31) * 16u;
;           st16(base, ro, pk8(x0, x1));
;           st16(base, ro + 8192u, pk8(y0, y1));
;           if (!isq) {
;             float vx[8] = {x0[0], x0[1], x0[2], x0[3], x1[0], x1[1], x1[2], x1[3]}, vy[8] = {y0[0], y0[1], y0[2], y0[3], y1[0], y1[1], y1[2], y1[3]};
;             const int lane = fq * 16 + fr;
;             transpose8(vx, lane); transpose8(vy, lane);
;             const int tl = rl & ~7, dk = d0 + (fr & 7);
;             const unsigned kro = (unsigned)((tl >> 7) * 4 + hd) * 65536u + (unsigned)(dk >> 5) * 8192u + (unsigned)((tl & 127) >> 4) * 1024u + (unsigned)((tl >> 3) & 1) * 512u + (unsigned)(dk & 31) * 16u;
;             st16(kT, kro, pk8((f32x4){vx[0], vx[1], vx[2], vx[3]}, (f32x4){vx[4], vx[5], vx[6], vx[7]}));
;             st16(kT, kro + 4u * 8192u, pk8((f32x4){vy[0], vy[1], vy[2], vy[3]}, (f32x4){vy[4], vy[5], vy[6], vy[7]}));
	v_cndmask_b32_e64 v55, v55, v72, s[10:11]
	v_cndmask_b32_e32 v65, v65, v64, vcc
	v_cmp_eq_u32_e32 vcc, 4, v58
	v_cndmask_b32_e64 v51, v72, v51, s[10:11]
	v_cndmask_b32_e64 v51, v61, v51, s[8:9]
	v_cndmask_b32_e32 v68, v68, v64, vcc
	v_cmp_eq_u32_e32 vcc, 6, v58
	v_cndmask_b32_e64 v49, v49, v55, s[8:9]
	ds_bpermute_b32 v51, v169, v51
	v_cndmask_b32_e32 v58, v73, v64, vcc
	v_cmp_eq_u32_e32 vcc, 6, v56
	ds_bpermute_b32 v49, v169, v49
	s_nop 0
	v_cndmask_b32_e32 v58, v58, v57, vcc
	v_cmp_eq_u32_e32 vcc, 4, v56
	v_cndmask_b32_e64 v58, v78, v58, s[8:9]
	s_nop 0
	v_cndmask_b32_e32 v64, v68, v57, vcc
	v_cmp_eq_u32_e32 vcc, 3, v56
	v_cndmask_b32_e64 v64, v77, v64, s[8:9]
	s_nop 0
	v_cndmask_b32_e32 v65, v65, v57, vcc
	v_cmp_eq_u32_e32 vcc, 2, v56
	v_cndmask_b32_e64 v65, v65, v76, s[8:9]
	s_nop 0
	v_cndmask_b32_e32 v68, v71, v57, vcc
	v_cmp_eq_u32_e32 vcc, 1, v56
	s_nop 1
	v_cndmask_b32_e32 v70, v70, v57, vcc
	v_cmp_eq_u32_e32 vcc, 0, v56
	s_nop 1
	v_cndmask_b32_e32 v69, v69, v57, vcc
	v_cmp_eq_u32_e32 vcc, 5, v56
	s_nop 1
	v_cndmask_b32_e32 v66, v66, v57, vcc
	v_cmp_eq_u32_e32 vcc, 7, v56
	s_nop 1
	v_cndmask_b32_e32 v56, v67, v57, vcc
	v_cmp_eq_u32_e32 vcc, 6, v48
	v_cndmask_b32_e64 v67, v76, v68, s[8:9]
	v_cndmask_b32_e64 v56, v56, v59, s[10:11]
	v_cndmask_b32_e32 v60, v60, v80, vcc
	v_cmp_eq_u32_e32 vcc, 4, v48
	v_cndmask_b32_e64 v57, v59, v66, s[10:11]
	v_cndmask_b32_e64 v59, v75, v69, s[8:9]
	v_cndmask_b32_e32 v68, v82, v80, vcc
	v_cmp_eq_u32_e32 vcc, 3, v48
	v_cndmask_b32_e64 v66, v70, v75, s[8:9]
	v_cndmask_b32_e64 v57, v57, v77, s[8:9]
	v_cndmask_b32_e32 v69, v79, v80, vcc
	v_cmp_eq_u32_e32 vcc, 2, v48
	v_cndmask_b32_e64 v56, v56, v78, s[8:9]
	v_cndmask_b32_e64 v61, v69, v50, s[8:9]
	v_cndmask_b32_e32 v70, v87, v80, vcc
	v_cmp_eq_u32_e32 vcc, 1, v48
	v_cndmask_b32_e64 v55, v50, v70, s[8:9]
	s_waitcnt lgkmcnt(0)
	v_cndmask_b32_e64 v68, v51, v68, s[8:9]
	v_cndmask_b32_e32 v71, v86, v80, vcc
	v_cmp_eq_u32_e32 vcc, 0, v48
	v_cndmask_b32_e64 v71, v71, v53, s[8:9]
	v_cndmask_b32_e64 v60, v49, v60, s[8:9]
	v_cndmask_b32_e32 v52, v52, v80, vcc
	v_cmp_eq_u32_e32 vcc, 5, v48
	s_nop 1
	v_cndmask_b32_e32 v54, v54, v80, vcc
	v_cmp_eq_u32_e32 vcc, 7, v48
	v_cndmask_b32_e64 v54, v72, v54, s[10:11]
	v_cndmask_b32_e64 v54, v54, v51, s[8:9]
	v_cndmask_b32_e32 v48, v84, v80, vcc
	v_cndmask_b32_e64 v48, v48, v72, s[10:11]
	v_cndmask_b32_e64 v72, v53, v52, s[8:9]
	v_lshl_add_u64 v[52:53], s[24:25], 0, v[176:177]
	v_or_b32_e32 v176, 0x8000, v176
	v_cndmask_b32_e64 v69, v48, v49, s[8:9]
	v_cvt_pk_bf16_f32 v48, v59, v66
	v_cvt_pk_bf16_f32 v49, v67, v65
	v_cvt_pk_bf16_f32 v50, v64, v57
	v_cvt_pk_bf16_f32 v51, v58, v56
	global_store_dwordx4 v[52:53], v[48:51], off
	v_lshl_add_u64 v[52:53], s[24:25], 0, v[176:177]
	s_nop 0
	v_cvt_pk_bf16_f32 v48, v72, v71
	v_cvt_pk_bf16_f32 v49, v55, v61
	v_cvt_pk_bf16_f32 v50, v68, v54
	v_cvt_pk_bf16_f32 v51, v60, v69
	global_store_dwordx4 v[52:53], v[48:51], off
.LBB0_180:
	s_or_b32 s4, s2, 16
	v_or_b32_e32 v54, s4, v137
	v_add_u32_e32 v48, s34, v54
	v_cmp_gt_i32_e32 vcc, s55, v48
	v_mov_b32_e32 v49, 0xfff
	v_mov_b32_e32 v50, 0x7ff
	v_cndmask_b32_e32 v49, v49, v50, vcc
	v_and_b32_e32 v48, v49, v48
	v_lshl_or_b32 v176, v48, 9, v166
	v_lshl_add_u64 v[48:49], s[30:31], 0, v[176:177]
	global_load_dwordx4 v[50:53], v[48:49], off
	v_lshl_add_u64 v[48:49], s[28:29], 0, v[176:177]
	global_load_dwordx4 v[56:59], v[48:49], off
	v_or_b32_e32 v48, 16, v176
	v_mov_b32_e32 v49, v177
	v_lshl_add_u64 v[60:61], s[30:31], 0, v[48:49]
	global_load_dwordx4 v[64:67], v[60:61], off
	v_lshl_add_u64 v[48:49], s[28:29], 0, v[48:49]
	global_load_dwordx4 v[68:71], v[48:49], off
	v_lshlrev_b32_e32 v55, 4, v54
	s_movk_i32 s0, 0x1f0
	v_and_or_b32 v176, v55, s0, v63
	v_mov_b32_e32 v48, v142
	v_mov_b32_e32 v49, v142
	v_lshl_add_u64 v[60:61], s[26:27], 0, v[176:177]
	v_or_b32_e32 v176, 0x2000, v176
	v_lshl_add_u64 v[72:73], s[26:27], 0, v[176:177]
	s_and_b64 vcc, exec, s[12:13]
	s_waitcnt vmcnt(0) lgkmcnt(0)
	v_pk_mul_f32 v[74:75], v[38:39], v[52:53]
	v_pk_mul_f32 v[76:77], v[36:37], v[50:51]
	v_pk_mul_f32 v[52:53], v[46:47], v[52:53]
	v_pk_mul_f32 v[50:51], v[44:45], v[50:51]
	v_pk_fma_f32 v[46:47], v[46:47], v[58:59], v[74:75] neg_lo:[0,0,1] neg_hi:[0,0,1]
	v_pk_fma_f32 v[44:45], v[44:45], v[56:57], v[76:77] neg_lo:[0,0,1] neg_hi:[0,0,1]
	v_pk_mul_f32 v[74:75], v[34:35], v[66:67]
	v_pk_mul_f32 v[76:77], v[32:33], v[64:65]
	v_pk_fma_f32 v[52:53], v[38:39], v[58:59], v[52:53]
	v_pk_fma_f32 v[50:51], v[36:37], v[56:57], v[50:51]
	v_pk_mul_f32 v[56:57], v[42:43], v[66:67]
	v_pk_mul_f32 v[58:59], v[40:41], v[64:65]
	v_pk_mul_f32 v[38:39], v[142:143], v[44:45]
	v_pk_fma_f32 v[42:43], v[42:43], v[70:71], v[74:75] neg_lo:[0,0,1] neg_hi:[0,0,1]
	v_pk_fma_f32 v[44:45], v[40:41], v[68:69], v[76:77] neg_lo:[0,0,1] neg_hi:[0,0,1]
	v_pk_mul_f32 v[40:41], v[142:143], v[50:51]
	v_pk_fma_f32 v[34:35], v[34:35], v[70:71], v[56:57]
	v_pk_fma_f32 v[50:51], v[32:33], v[68:69], v[58:59]
	v_pk_mul_f32 v[36:37], v[48:49], v[46:47]
	v_pk_mul_f32 v[52:53], v[48:49], v[52:53]
	v_pk_mul_f32 v[32:33], v[48:49], v[42:43]
	v_pk_mul_f32 v[42:43], v[142:143], v[44:45]
	v_pk_mul_f32 v[46:47], v[48:49], v[34:35]
	v_pk_mul_f32 v[50:51], v[142:143], v[50:51]
	v_cvt_pk_bf16_f32 v56, v38, v39
	v_cvt_pk_bf16_f32 v57, v36, v37
	v_cvt_pk_bf16_f32 v58, v42, v43
	v_cvt_pk_bf16_f32 v59, v32, v33
	global_store_dwordx4 v[60:61], v[56:59], off
	s_nop 1
	v_cvt_pk_bf16_f32 v56, v40, v41
	v_cvt_pk_bf16_f32 v57, v52, v53
	v_cvt_pk_bf16_f32 v58, v50, v51
	v_cvt_pk_bf16_f32 v59, v46, v47
	global_store_dwordx4 v[72:73], v[56:59], off
	s_cbranch_vccnz .LBB0_188
; DI float shx(float v, int lane, int mask) { return __int_as_float(__builtin_amdgcn_ds_bpermute((lane ^ mask) << 2, __float_as_int(v))); }
; DI u32x4 pk8(const f32x4& v0, const f32x4& v1) { u32x4 w; w.x = cvt_pk_bf16(v0[0], v0[1]); w.y = cvt_pk_bf16(v0[2], v0[3]); w.z = cvt_pk_bf16(v1[0], v1[1]); w.w = cvt_pk_bf16(v1[2], v1[3]); return w; }
; DI void transpose8(float (&v)[8], int lane) { tstage8<4>(v, lane); tstage8<2>(v, lane); tstage8<1>(v, lane); }
; template <int K> DI void tstage8(float (&v)[8], int lane) {
;   const bool up = (lane & K) != 0;
; #pragma unroll
;   for (int j = 0; j < 8; ++j) {
;     if ((j & K) == 0) {
;       const float send = up ? v[j] : v[j | K];
;       const float recv = shx(send, lane, K);
;       if (up) v[j] = recv; else v[j | K] = recv;
;     }
;   }
; }
;   DI void epi(const Acc& acc, const Unit& u, int wr, int wc, int fr, int fq, LAS unsigned char* lds) const {
;     ...
;             float vx[8] = {x0[0], x0[1], x0[2], x0[3], x1[0], x1[1], x1[2], x1[3]}, vy[8] = {y0[0], y0[1], y0[2], y0[3], y1[0], y1[1], y1[2], y1[3]};
;             const int lane = fq * 16 + fr;
;             transpose8(vx, lane); transpose8(vy, lane);
;             const int tl = rl & ~7, dk = d0 + (fr & 7);
;             const unsigned kro = (unsigned)((tl >> 7) * 4 + hd) * 65536u + (unsigned)(dk >> 5) * 8192u + (unsigned)((tl & 127) >> 4) * 1024u + (unsigned)((tl >> 3) & 1) * 512u + (unsigned)(dk & 31) * 16u;
;             st16(kT, kro, pk8((f32x4){vx[0], vx[1], vx[2], vx[3]}, (f32x4){vx[4], vx[5], vx[6], vx[7]}));
;             st16(kT, kro + 4u * 8192u, pk8((f32x4){vy[0], vy[1], vy[2], vy[3]}, (f32x4){vy[4], vy[5], vy[6], vy[7]}));
	v_cndmask_b32_e64 v34, v38, v42, s[6:7]
	ds_bpermute_b32 v65, v167, v34
	v_cndmask_b32_e64 v35, v36, v32, s[6:7]
	v_cndmask_b32_e64 v34, v39, v43, s[6:7]
	ds_bpermute_b32 v35, v167, v35
	ds_bpermute_b32 v34, v167, v34
	s_waitcnt lgkmcnt(0)
	v_cndmask_b32_e64 v55, v65, v38, s[6:7]
	v_cndmask_b32_e64 v38, v37, v33, s[6:7]
	ds_bpermute_b32 v59, v167, v38
	v_cndmask_b32_e64 v57, v35, v36, s[6:7]
	v_cndmask_b32_e64 v56, v34, v39, s[6:7]
	v_cndmask_b32_e64 v58, v32, v35, s[6:7]
	v_cndmask_b32_e64 v32, v55, v57, s[10:11]
	s_waitcnt lgkmcnt(0)
	v_cndmask_b32_e64 v63, v59, v37, s[6:7]
	ds_bpermute_b32 v36, v168, v32
	v_cndmask_b32_e64 v32, v56, v63, s[10:11]
	ds_bpermute_b32 v32, v168, v32
	v_cndmask_b32_e64 v60, v42, v65, s[6:7]
	v_cndmask_b32_e64 v43, v43, v34, s[6:7]
	v_mov_b64_e32 v[44:45], 1
	v_mov_b64_e32 v[34:35], 4
	v_cndmask_b32_e64 v61, v33, v59, s[6:7]
	v_mov_b32_e32 v45, v43
	v_mov_b64_e32 v[38:39], 1
	v_mov_b32_e32 v35, v60
	s_waitcnt lgkmcnt(0)
	v_mov_b32_e32 v64, v32
	s_and_saveexec_b64 s[0:1], s[10:11]
	v_mov_b64_e32 v[34:35], 6
	v_mov_b64_e32 v[38:39], 3
	v_mov_b32_e32 v45, v61
	v_mov_b32_e32 v35, v58
	v_mov_b32_e32 v63, v32
	v_mov_b32_e32 v64, v56
	s_or_b64 exec, exec, s[0:1]
	ds_bpermute_b32 v39, v168, v45
	ds_bpermute_b32 v35, v168, v35
	v_cndmask_b32_e64 v45, v57, v36, s[10:11]
	v_cndmask_b32_e64 v45, v45, v63, s[8:9]
	v_cndmask_b32_e64 v66, v36, v55, s[10:11]
	s_waitcnt lgkmcnt(0)
	v_cndmask_b32_e64 v69, v61, v39, s[10:11]
	ds_bpermute_b32 v61, v169, v45
	v_cndmask_b32_e64 v45, v40, v50, s[6:7]
	ds_bpermute_b32 v70, v167, v45
	v_cndmask_b32_e64 v68, v35, v60, s[10:11]
	v_cndmask_b32_e64 v71, v39, v43, s[10:11]
	v_cndmask_b32_e64 v67, v58, v35, s[10:11]
	v_cndmask_b32_e64 v45, v68, v71, s[8:9]
	ds_bpermute_b32 v63, v169, v45
	v_cndmask_b32_e64 v45, v67, v69, s[8:9]
	v_cndmask_b32_e64 v60, v66, v64, s[8:9]
	ds_bpermute_b32 v64, v169, v45
	v_cndmask_b32_e64 v45, v41, v51, s[6:7]
	s_waitcnt lgkmcnt(0)
	v_cndmask_b32_e64 v68, v50, v70, s[6:7]
	ds_bpermute_b32 v50, v167, v45
	v_cndmask_b32_e64 v45, v52, v46, s[6:7]
	ds_bpermute_b32 v45, v167, v45
	v_cndmask_b32_e64 v66, v53, v47, s[6:7]
	v_cndmask_b32_e64 v67, v70, v40, s[6:7]
	ds_bpermute_b32 v66, v167, v66
	s_waitcnt lgkmcnt(0)
	v_cndmask_b32_e64 v69, v50, v41, s[6:7]
	v_cndmask_b32_e64 v73, v45, v52, s[6:7]
	v_cndmask_b32_e64 v41, v67, v73, s[10:11]
	ds_bpermute_b32 v72, v168, v41
	ds_bpermute_b32 v60, v169, v60
	v_cndmask_b32_e64 v71, v66, v53, s[6:7]
	v_mov_b64_e32 v[52:53], 0
	v_cndmask_b32_e64 v74, v46, v45, s[6:7]
	v_mov_b32_e32 v46, v68
	v_mov_b32_e32 v53, v69
	v_mov_b32_e32 v41, v73
	s_waitcnt lgkmcnt(0)
	v_mov_b32_e32 v45, v72
	s_and_saveexec_b64 s[0:1], s[10:11]
	v_mov_b64_e32 v[52:53], 2
	v_mov_b64_e32 v[44:45], 3
	v_mov_b32_e32 v46, v74
	v_mov_b32_e32 v53, v71
	v_mov_b32_e32 v41, v72
	v_mov_b32_e32 v45, v67
	s_or_b64 exec, exec, s[0:1]
	v_cndmask_b32_e64 v50, v51, v50, s[6:7]
	v_cndmask_b32_e64 v51, v47, v66, s[6:7]
	ds_bpermute_b32 v66, v168, v46
	ds_bpermute_b32 v75, v168, v53
	v_mov_b64_e32 v[46:47], 4
	v_mov_b32_e32 v67, v50
	v_mov_b32_e32 v47, v74
	s_waitcnt lgkmcnt(0)
	v_mov_b32_e32 v53, v66
	s_and_saveexec_b64 s[0:1], s[10:11]
	v_mov_b64_e32 v[46:47], 6
	v_mov_b32_e32 v67, v51
	v_mov_b32_e32 v47, v66
	v_mov_b32_e32 v53, v68
	s_or_b64 exec, exec, s[0:1]
	v_cmp_eq_u32_e32 vcc, 3, v52
	v_cndmask_b32_e64 v42, v42, v65, s[6:7]
	v_cndmask_b32_e64 v40, v70, v40, s[6:7]
	v_cndmask_b32_e32 v65, v71, v72, vcc
	v_cmp_eq_u32_e32 vcc, 7, v52
	v_cndmask_b32_e64 v37, v59, v37, s[6:7]
	v_cndmask_b32_e64 v33, v33, v59, s[6:7]
	v_cndmask_b32_e32 v70, v51, v72, vcc
	v_cmp_eq_u32_e32 vcc, 6, v52
	v_cndmask_b32_e64 v71, v71, v75, s[10:11]
	v_cndmask_b32_e64 v41, v41, v71, s[8:9]
	v_cndmask_b32_e32 v74, v74, v72, vcc
	v_cmp_eq_u32_e32 vcc, 4, v52
	ds_bpermute_b32 v41, v169, v41
	s_lshr_b32 s0, s2, 5
	v_cndmask_b32_e32 v68, v68, v72, vcc
	v_cmp_eq_u32_e32 vcc, 2, v52
	s_and_b32 s0, s0, 0xfffc
	s_add_i32 s0, s0, s54
	v_cndmask_b32_e32 v73, v73, v72, vcc
	v_cmp_eq_u32_e32 vcc, 1, v52
	s_lshl_b32 s1, s4, 6
	s_lshl_b32 s0, s0, 16
	v_cndmask_b32_e32 v76, v69, v72, vcc
	v_cmp_eq_u32_e32 vcc, 0, v52
	v_cndmask_b32_e64 v69, v75, v69, s[10:11]
	v_cndmask_b32_e64 v45, v45, v69, s[8:9]
	v_cndmask_b32_e32 v40, v40, v72, vcc
	v_cmp_eq_u32_e32 vcc, 5, v52
	ds_bpermute_b32 v45, v169, v45
	s_and_b32 s1, s1, 0x1400
	v_cndmask_b32_e32 v52, v50, v72, vcc
	v_cmp_eq_u32_e32 vcc, 7, v44
	s_or_b32 s0, s0, s1
	s_nop 0
	v_cndmask_b32_e32 v70, v70, v75, vcc
	v_cmp_eq_u32_e32 vcc, 5, v44
	s_nop 1
	v_cndmask_b32_e32 v52, v52, v75, vcc
	v_cmp_eq_u32_e32 vcc, 0, v44
	s_nop 1
	v_cndmask_b32_e32 v40, v40, v75, vcc
	v_cmp_eq_u32_e32 vcc, 1, v44
	s_nop 1
	v_cndmask_b32_e32 v72, v76, v75, vcc
	v_cmp_eq_u32_e32 vcc, 2, v44
	s_nop 1
	v_cndmask_b32_e32 v73, v73, v75, vcc
	v_cmp_eq_u32_e32 vcc, 3, v44
	s_nop 1
	v_cndmask_b32_e32 v65, v65, v75, vcc
	v_cmp_eq_u32_e32 vcc, 4, v44
	s_nop 1
	v_cndmask_b32_e32 v68, v68, v75, vcc
	v_cmp_eq_u32_e32 vcc, 6, v44
	s_nop 1
	v_cndmask_b32_e32 v44, v74, v75, vcc
	v_cmp_eq_u32_e32 vcc, 3, v136
	s_nop 1
	v_cndmask_b32_e32 v37, v37, v36, vcc
	v_cmp_eq_u32_e32 vcc, 7, v136
	s_nop 1
	v_cndmask_b32_e32 v33, v33, v36, vcc
	v_cmp_eq_u32_e32 vcc, 6, v136
	s_nop 1
	v_cndmask_b32_e32 v58, v58, v36, vcc
	v_cmp_eq_u32_e32 vcc, 4, v136
	s_nop 1
	v_cndmask_b32_e32 v42, v42, v36, vcc
	v_cmp_eq_u32_e32 vcc, 2, v136
	s_nop 1
	v_cndmask_b32_e32 v57, v57, v36, vcc
	v_cmp_eq_u32_e32 vcc, 1, v136
	s_nop 1
	v_cndmask_b32_e32 v56, v56, v36, vcc
	v_cmp_eq_u32_e32 vcc, 0, v136
	s_nop 1
	v_cndmask_b32_e32 v55, v55, v36, vcc
	v_cmp_eq_u32_e32 vcc, 5, v136
	s_nop 1
	v_cndmask_b32_e32 v36, v43, v36, vcc
	v_cmp_eq_u32_e32 vcc, 7, v38
	s_nop 1
	v_cndmask_b32_e32 v33, v33, v32, vcc
	v_cmp_eq_u32_e32 vcc, 5, v38
	s_nop 1
	v_cndmask_b32_e32 v36, v36, v32, vcc
	v_cmp_eq_u32_e32 vcc, 0, v38
	s_nop 1
	v_cndmask_b32_e32 v43, v55, v32, vcc
	v_cmp_eq_u32_e32 vcc, 1, v38
	s_nop 1
	v_cndmask_b32_e32 v55, v56, v32, vcc
	v_cmp_eq_u32_e32 vcc, 2, v38
	s_nop 1
	v_cndmask_b32_e32 v56, v57, v32, vcc
	v_cmp_eq_u32_e32 vcc, 3, v38
	ds_bpermute_b32 v57, v168, v67
	s_waitcnt lgkmcnt(0)
; DI u32x4 pk8(const f32x4& v0, const f32x4& v1) { u32x4 w; w.x = cvt_pk_bf16(v0[0], v0[1]); w.y = cvt_pk_bf16(v0[2], v0[3]); w.z = cvt_pk_bf16(v1[0], v1[1]); w.w = cvt_pk_bf16(v1[2], v1[3]); return w; }
; DI void transpose8(float (&v)[8], int lane) { tstage8<4>(v, lane); tstage8<2>(v, lane); tstage8<1>(v, lane); }
;   DI void epi(const Acc& acc, const Unit& u, int wr, int wc, int fr, int fq, LAS unsigned char* lds) const {
;     ...
;           const int rl = u.pm * 256 + ai * 128 + wr * 64 + m * 16 + fr; const int pos = tok_pos(rb + rl);
;           const unsigned to = (unsigned)(pos * 128 + d0) * 4u; const f32x4 c0 = ldf4(cosR, to), c1 = ldf4(cosR, to + 16u);
;           const f32x4 s0 = ldf4(sinR, to), s1 = ldf4(sinR, to + 16u);
;           const f32x4 a0 = acc[ai][0][m][0], a1 = acc[ai][0][m][1], b0 = acc[ai][1][m][0], b1 = acc[ai][1][m][1];
;           const f32x4 x0 = (a0 * c0 - b0 * s0) * sc, x1 = (a1 * c1 - b1 * s1) * sc, y0 = (b0 * c0 + a0 * s0) * sc, y1 = (b1 * c1 + a1 * s1) * sc;
;           const unsigned ro = fo + (unsigned)(rl >> 7) * 262144u + (unsigned)((rl >> 5) & 3) * 16384u + (unsigned)(rl & 31) * 16u;
;           st16(base, ro, pk8(x0, x1));
;           st16(base, ro + 8192u, pk8(y0, y1));
;           if (!isq) {
;             float vx[8] = {x0[0], x0[1], x0[2], x0[3], x1[0], x1[1], x1[2], x1[3]}, vy[8] = {y0[0], y0[1], y0[2], y0[3], y1[0], y1[1], y1[2], y1[3]};
;             const int lane = fq * 16 + fr;
;             transpose8(vx, lane); transpose8(vy, lane);
;             const int tl = rl & ~7, dk = d0 + (fr & 7);
;             const unsigned kro = (unsigned)((tl >> 7) * 4 + hd) * 65536u + (unsigned)(dk >> 5) * 8192u + (unsigned)((tl & 127) >> 4) * 1024u + (unsigned)((tl >> 3) & 1) * 512u + (unsigned)(dk & 31) * 16u;
;             st16(kT, kro, pk8((f32x4){vx[0], vx[1], vx[2], vx[3]}, (f32x4){vx[4], vx[5], vx[6], vx[7]}));
;             st16(kT, kro + 4u * 8192u, pk8((f32x4){vy[0], vy[1], vy[2], vy[3]}, (f32x4){vy[4], vy[5], vy[6], vy[7]}));
	v_cndmask_b32_e64 v51, v51, v57, s[10:11]
	v_cndmask_b32_e32 v37, v37, v32, vcc
	v_cmp_eq_u32_e32 vcc, 4, v38
	v_cndmask_b32_e64 v50, v57, v50, s[10:11]
	v_cndmask_b32_e64 v50, v53, v50, s[8:9]
	v_cndmask_b32_e32 v42, v42, v32, vcc
	v_cmp_eq_u32_e32 vcc, 6, v38
	v_cndmask_b32_e64 v47, v47, v51, s[8:9]
	ds_bpermute_b32 v50, v169, v50
	v_cndmask_b32_e32 v32, v58, v32, vcc
	v_cmp_eq_u32_e32 vcc, 6, v34
	ds_bpermute_b32 v47, v169, v47
	s_nop 0
	v_cndmask_b32_e32 v32, v32, v35, vcc
	v_cmp_eq_u32_e32 vcc, 4, v34
	s_nop 1
	v_cndmask_b32_e32 v38, v42, v35, vcc
	v_cmp_eq_u32_e32 vcc, 3, v34
	v_cndmask_b32_e64 v38, v63, v38, s[8:9]
	s_nop 0
	v_cndmask_b32_e32 v37, v37, v35, vcc
	v_cmp_eq_u32_e32 vcc, 2, v34
	v_cndmask_b32_e64 v37, v37, v61, s[8:9]
	s_nop 0
	v_cndmask_b32_e32 v42, v56, v35, vcc
	v_cmp_eq_u32_e32 vcc, 1, v34
	s_nop 1
	v_cndmask_b32_e32 v55, v55, v35, vcc
	v_cmp_eq_u32_e32 vcc, 0, v34
	s_nop 1
	v_cndmask_b32_e32 v43, v43, v35, vcc
	v_cmp_eq_u32_e32 vcc, 5, v34
	s_nop 1
	v_cndmask_b32_e32 v36, v36, v35, vcc
	v_cmp_eq_u32_e32 vcc, 7, v34
	v_cndmask_b32_e64 v34, v39, v36, s[10:11]
	v_cndmask_b32_e64 v36, v55, v60, s[8:9]
	v_cndmask_b32_e32 v33, v33, v35, vcc
	v_cmp_eq_u32_e32 vcc, 6, v46
	v_cndmask_b32_e64 v33, v33, v39, s[10:11]
	v_cndmask_b32_e64 v39, v61, v42, s[8:9]
	v_cndmask_b32_e64 v42, v64, v32, s[8:9]
	v_cndmask_b32_e32 v32, v44, v66, vcc
	v_cmp_eq_u32_e32 vcc, 4, v46
	v_cndmask_b32_e64 v35, v60, v43, s[8:9]
	v_cndmask_b32_e64 v43, v33, v64, s[8:9]
	v_cndmask_b32_e32 v33, v68, v66, vcc
	v_cmp_eq_u32_e32 vcc, 3, v46
	v_cndmask_b32_e64 v34, v34, v63, s[8:9]
	s_nop 0
	v_cndmask_b32_e32 v44, v65, v66, vcc
	v_cmp_eq_u32_e32 vcc, 2, v46
	s_nop 1
	v_cndmask_b32_e32 v55, v73, v66, vcc
	v_cmp_eq_u32_e32 vcc, 1, v46
	v_cndmask_b32_e64 v51, v41, v55, s[8:9]
	v_cndmask_b32_e64 v41, v44, v41, s[8:9]
	v_cndmask_b32_e32 v56, v72, v66, vcc
	v_cmp_eq_u32_e32 vcc, 0, v46
	s_waitcnt lgkmcnt(0)
	v_cndmask_b32_e64 v44, v50, v33, s[8:9]
	v_cndmask_b32_e32 v40, v40, v66, vcc
	v_cmp_eq_u32_e32 vcc, 5, v46
	v_cndmask_b32_e64 v40, v45, v40, s[8:9]
	v_cndmask_b32_e64 v45, v56, v45, s[8:9]
	v_cndmask_b32_e32 v52, v52, v66, vcc
	v_cndmask_b32_e64 v52, v57, v52, s[10:11]
	v_cndmask_b32_e64 v50, v52, v50, s[8:9]
	v_cndmask_b32_e64 v52, v47, v32, s[8:9]
	v_lshlrev_b32_e32 v32, 6, v54
	v_and_b32_e32 v32, 0x200, v32
	v_cmp_eq_u32_e32 vcc, 7, v46
	v_or3_b32 v176, s0, v32, v170
	v_cvt_pk_bf16_f32 v32, v35, v36
	v_cvt_pk_bf16_f32 v33, v39, v37
	v_lshl_add_u64 v[36:37], s[24:25], 0, v[176:177]
	v_cndmask_b32_e32 v46, v70, v66, vcc
	v_or_b32_e32 v176, 0x8000, v176
	v_cndmask_b32_e64 v46, v46, v57, s[10:11]
	v_cvt_pk_bf16_f32 v34, v38, v34
	v_cvt_pk_bf16_f32 v35, v42, v43
	global_store_dwordx4 v[36:37], v[32:35], off
	v_lshl_add_u64 v[36:37], s[24:25], 0, v[176:177]
	v_cndmask_b32_e64 v46, v46, v47, s[8:9]
	v_cvt_pk_bf16_f32 v32, v40, v45
	v_cvt_pk_bf16_f32 v33, v51, v41
	v_cvt_pk_bf16_f32 v34, v44, v50
	v_cvt_pk_bf16_f32 v35, v52, v46
	global_store_dwordx4 v[36:37], v[32:35], off
.LBB0_188:
	s_or_b32 s4, s2, 32
	v_or_b32_e32 v36, s4, v137
	v_add_u32_e32 v32, s34, v36
	v_cmp_gt_i32_e32 vcc, s55, v32
	v_mov_b32_e32 v33, 0xfff
	v_mov_b32_e32 v34, 0x7ff
	v_cndmask_b32_e32 v33, v33, v34, vcc
	v_and_b32_e32 v32, v33, v32
	v_lshl_or_b32 v176, v32, 9, v166
	v_lshl_add_u64 v[32:33], s[30:31], 0, v[176:177]
	v_or_b32_e32 v46, 16, v176
	v_mov_b32_e32 v47, v177
	global_load_dwordx4 v[32:35], v[32:33], off
	v_lshl_add_u64 v[38:39], s[28:29], 0, v[176:177]
	v_lshl_add_u64 v[42:43], s[30:31], 0, v[46:47]
	global_load_dwordx4 v[38:41], v[38:39], off
	v_lshl_add_u64 v[46:47], s[28:29], 0, v[46:47]
	global_load_dwordx4 v[42:45], v[42:43], off
	s_lshl_b32 s0, s4, 9
	global_load_dwordx4 v[50:53], v[46:47], off
	v_lshlrev_b32_e32 v37, 4, v36
	s_and_b32 s0, s0, 0xc000
	v_and_b32_e32 v37, 0x1f0, v37
	v_or3_b32 v176, s0, v37, v62
	v_lshl_add_u64 v[46:47], s[26:27], 0, v[176:177]
	v_or_b32_e32 v176, 0x2000, v176
	v_lshl_add_u64 v[54:55], s[26:27], 0, v[176:177]
	s_and_b64 vcc, exec, s[12:13]
	s_waitcnt vmcnt(0) lgkmcnt(0)
	v_pk_mul_f32 v[56:57], v[22:23], v[34:35]
	v_pk_mul_f32 v[58:59], v[20:21], v[32:33]
	v_pk_mul_f32 v[34:35], v[30:31], v[34:35]
	v_pk_mul_f32 v[32:33], v[28:29], v[32:33]
	v_pk_fma_f32 v[30:31], v[30:31], v[40:41], v[56:57] neg_lo:[0,0,1] neg_hi:[0,0,1]
	v_pk_fma_f32 v[28:29], v[28:29], v[38:39], v[58:59] neg_lo:[0,0,1] neg_hi:[0,0,1]
	v_pk_mul_f32 v[56:57], v[18:19], v[44:45]
	v_pk_mul_f32 v[58:59], v[16:17], v[42:43]
	v_pk_fma_f32 v[34:35], v[22:23], v[40:41], v[34:35]
	v_pk_fma_f32 v[32:33], v[20:21], v[38:39], v[32:33]
	v_pk_mul_f32 v[38:39], v[26:27], v[44:45]
	v_pk_mul_f32 v[40:41], v[24:25], v[42:43]
	v_pk_mul_f32 v[22:23], v[142:143], v[28:29]
	v_pk_fma_f32 v[26:27], v[26:27], v[52:53], v[56:57] neg_lo:[0,0,1] neg_hi:[0,0,1]
	v_pk_fma_f32 v[28:29], v[24:25], v[50:51], v[58:59] neg_lo:[0,0,1] neg_hi:[0,0,1]
	v_pk_mul_f32 v[24:25], v[142:143], v[32:33]
	v_pk_fma_f32 v[18:19], v[18:19], v[52:53], v[38:39]
	v_pk_fma_f32 v[32:33], v[16:17], v[50:51], v[40:41]
	v_pk_mul_f32 v[20:21], v[48:49], v[30:31]
	v_pk_mul_f32 v[34:35], v[48:49], v[34:35]
	v_pk_mul_f32 v[16:17], v[48:49], v[26:27]
	v_pk_mul_f32 v[26:27], v[142:143], v[28:29]
	v_pk_mul_f32 v[30:31], v[48:49], v[18:19]
	v_pk_mul_f32 v[32:33], v[142:143], v[32:33]
	v_cvt_pk_bf16_f32 v38, v22, v23
	v_cvt_pk_bf16_f32 v39, v20, v21
	v_cvt_pk_bf16_f32 v40, v26, v27
	v_cvt_pk_bf16_f32 v41, v16, v17
	global_store_dwordx4 v[46:47], v[38:41], off
	s_nop 1
	v_cvt_pk_bf16_f32 v38, v24, v25
	v_cvt_pk_bf16_f32 v39, v34, v35
	v_cvt_pk_bf16_f32 v40, v32, v33
	v_cvt_pk_bf16_f32 v41, v30, v31
	global_store_dwordx4 v[54:55], v[38:41], off
	s_cbranch_vccnz .LBB0_196
; DI float shx(float v, int lane, int mask) { return __int_as_float(__builtin_amdgcn_ds_bpermute((lane ^ mask) << 2, __float_as_int(v))); }
; DI u32x4 pk8(const f32x4& v0, const f32x4& v1) { u32x4 w; w.x = cvt_pk_bf16(v0[0], v0[1]); w.y = cvt_pk_bf16(v0[2], v0[3]); w.z = cvt_pk_bf16(v1[0], v1[1]); w.w = cvt_pk_bf16(v1[2], v1[3]); return w; }
; DI void transpose8(float (&v)[8], int lane) { tstage8<4>(v, lane); tstage8<2>(v, lane); tstage8<1>(v, lane); }
; template <int K> DI void tstage8(float (&v)[8], int lane) {
;   const bool up = (lane & K) != 0;
; #pragma unroll
;   for (int j = 0; j < 8; ++j) {
;     if ((j & K) == 0) {
;       const float send = up ? v[j] : v[j | K];
;       const float recv = shx(send, lane, K);
;       if (up) v[j] = recv; else v[j | K] = recv;
;     }
;   }
; }
;   DI void epi(const Acc& acc, const Unit& u, int wr, int wc, int fr, int fq, LAS unsigned char* lds) const {
;     ...
;             float vx[8] = {x0[0], x0[1], x0[2], x0[3], x1[0], x1[1], x1[2], x1[3]}, vy[8] = {y0[0], y0[1], y0[2], y0[3], y1[0], y1[1], y1[2], y1[3]};
;             const int lane = fq * 16 + fr;
;             transpose8(vx, lane); transpose8(vy, lane);
;             const int tl = rl & ~7, dk = d0 + (fr & 7);
;             const unsigned kro = (unsigned)((tl >> 7) * 4 + hd) * 65536u + (unsigned)(dk >> 5) * 8192u + (unsigned)((tl & 127) >> 4) * 1024u + (unsigned)((tl >> 3) & 1) * 512u + (unsigned)(dk & 31) * 16u;
;             st16(kT, kro, pk8((f32x4){vx[0], vx[1], vx[2], vx[3]}, (f32x4){vx[4], vx[5], vx[6], vx[7]}));
;             st16(kT, kro + 4u * 8192u, pk8((f32x4){vy[0], vy[1], vy[2], vy[3]}, (f32x4){vy[4], vy[5], vy[6], vy[7]}));
	v_cndmask_b32_e64 v18, v22, v26, s[6:7]
	ds_bpermute_b32 v46, v167, v18
	v_cndmask_b32_e64 v19, v20, v16, s[6:7]
	v_cndmask_b32_e64 v18, v23, v27, s[6:7]
	ds_bpermute_b32 v19, v167, v19
	ds_bpermute_b32 v18, v167, v18
	s_waitcnt lgkmcnt(0)
	v_cndmask_b32_e64 v37, v46, v22, s[6:7]
	v_cndmask_b32_e64 v22, v21, v17, s[6:7]
	ds_bpermute_b32 v41, v167, v22
	v_cndmask_b32_e64 v39, v19, v20, s[6:7]
	v_cndmask_b32_e64 v38, v18, v23, s[6:7]
	v_cndmask_b32_e64 v40, v16, v19, s[6:7]
	v_cndmask_b32_e64 v16, v37, v39, s[10:11]
	s_waitcnt lgkmcnt(0)
	v_cndmask_b32_e64 v44, v41, v21, s[6:7]
	ds_bpermute_b32 v20, v168, v16
	v_cndmask_b32_e64 v16, v38, v44, s[10:11]
	ds_bpermute_b32 v16, v168, v16
	v_cndmask_b32_e64 v42, v26, v46, s[6:7]
	v_cndmask_b32_e64 v27, v27, v18, s[6:7]
	v_mov_b64_e32 v[28:29], 1
	v_mov_b64_e32 v[18:19], 4
	v_cndmask_b32_e64 v43, v17, v41, s[6:7]
	v_mov_b32_e32 v29, v27
	v_mov_b64_e32 v[22:23], 1
	v_mov_b32_e32 v19, v42
	s_waitcnt lgkmcnt(0)
	v_mov_b32_e32 v45, v16
	s_and_saveexec_b64 s[0:1], s[10:11]
	v_mov_b64_e32 v[18:19], 6
	v_mov_b64_e32 v[22:23], 3
	v_mov_b32_e32 v29, v43
	v_mov_b32_e32 v19, v40
	v_mov_b32_e32 v44, v16
	v_mov_b32_e32 v45, v38
	s_or_b64 exec, exec, s[0:1]
	ds_bpermute_b32 v23, v168, v29
	ds_bpermute_b32 v19, v168, v19
	v_cndmask_b32_e64 v29, v39, v20, s[10:11]
	v_cndmask_b32_e64 v29, v29, v44, s[8:9]
	v_cndmask_b32_e64 v47, v20, v37, s[10:11]
	s_waitcnt lgkmcnt(0)
	v_cndmask_b32_e64 v50, v43, v23, s[10:11]
	ds_bpermute_b32 v43, v169, v29
	v_cndmask_b32_e64 v29, v24, v32, s[6:7]
	ds_bpermute_b32 v51, v167, v29
	v_cndmask_b32_e64 v49, v19, v42, s[10:11]
	v_cndmask_b32_e64 v52, v23, v27, s[10:11]
	v_cndmask_b32_e64 v48, v40, v19, s[10:11]
	v_cndmask_b32_e64 v29, v49, v52, s[8:9]
	ds_bpermute_b32 v44, v169, v29
	v_cndmask_b32_e64 v29, v48, v50, s[8:9]
	v_cndmask_b32_e64 v42, v47, v45, s[8:9]
	ds_bpermute_b32 v45, v169, v29
	v_cndmask_b32_e64 v29, v25, v33, s[6:7]
	s_waitcnt lgkmcnt(0)
	v_cndmask_b32_e64 v49, v32, v51, s[6:7]
	ds_bpermute_b32 v32, v167, v29
	v_cndmask_b32_e64 v29, v34, v30, s[6:7]
	ds_bpermute_b32 v29, v167, v29
	v_cndmask_b32_e64 v47, v35, v31, s[6:7]
	v_cndmask_b32_e64 v48, v51, v24, s[6:7]
	ds_bpermute_b32 v47, v167, v47
	s_waitcnt lgkmcnt(0)
	v_cndmask_b32_e64 v50, v32, v25, s[6:7]
	v_cndmask_b32_e64 v54, v29, v34, s[6:7]
	v_cndmask_b32_e64 v25, v48, v54, s[10:11]
	ds_bpermute_b32 v53, v168, v25
	ds_bpermute_b32 v42, v169, v42
	v_cndmask_b32_e64 v52, v47, v35, s[6:7]
	v_mov_b64_e32 v[34:35], 0
	v_cndmask_b32_e64 v55, v30, v29, s[6:7]
	v_mov_b32_e32 v30, v49
	v_mov_b32_e32 v35, v50
	v_mov_b32_e32 v25, v54
	s_waitcnt lgkmcnt(0)
	v_mov_b32_e32 v29, v53
	s_and_saveexec_b64 s[0:1], s[10:11]
	v_mov_b64_e32 v[34:35], 2
	v_mov_b64_e32 v[28:29], 3
	v_mov_b32_e32 v30, v55
	v_mov_b32_e32 v35, v52
	v_mov_b32_e32 v25, v53
	v_mov_b32_e32 v29, v48
	s_or_b64 exec, exec, s[0:1]
	v_cndmask_b32_e64 v32, v33, v32, s[6:7]
	v_cndmask_b32_e64 v33, v31, v47, s[6:7]
	ds_bpermute_b32 v47, v168, v30
	ds_bpermute_b32 v56, v168, v35
	v_mov_b64_e32 v[30:31], 4
	v_mov_b32_e32 v48, v32
	v_mov_b32_e32 v31, v55
	s_waitcnt lgkmcnt(0)
	v_mov_b32_e32 v35, v47
	s_and_saveexec_b64 s[0:1], s[10:11]
	v_mov_b64_e32 v[30:31], 6
	v_mov_b32_e32 v48, v33
	v_mov_b32_e32 v31, v47
	v_mov_b32_e32 v35, v49
	s_or_b64 exec, exec, s[0:1]
	v_cmp_eq_u32_e32 vcc, 3, v34
	v_cndmask_b32_e64 v26, v26, v46, s[6:7]
	v_cndmask_b32_e64 v24, v51, v24, s[6:7]
	v_cndmask_b32_e32 v46, v52, v53, vcc
	v_cmp_eq_u32_e32 vcc, 7, v34
	v_cndmask_b32_e64 v21, v41, v21, s[6:7]
	v_cndmask_b32_e64 v17, v17, v41, s[6:7]
	v_cndmask_b32_e32 v51, v33, v53, vcc
	v_cmp_eq_u32_e32 vcc, 6, v34
	v_cndmask_b32_e64 v52, v52, v56, s[10:11]
	v_cndmask_b32_e64 v25, v25, v52, s[8:9]
	v_cndmask_b32_e32 v55, v55, v53, vcc
	v_cmp_eq_u32_e32 vcc, 4, v34
	ds_bpermute_b32 v25, v169, v25
	s_lshr_b32 s0, s2, 5
	v_cndmask_b32_e32 v49, v49, v53, vcc
	v_cmp_eq_u32_e32 vcc, 2, v34
	s_and_b32 s0, s0, 0xfffc
	s_add_i32 s0, s0, s54
	v_cndmask_b32_e32 v54, v54, v53, vcc
	v_cmp_eq_u32_e32 vcc, 1, v34
	s_lshl_b32 s1, s4, 6
	s_lshl_b32 s0, s0, 16
	v_cndmask_b32_e32 v57, v50, v53, vcc
	v_cmp_eq_u32_e32 vcc, 0, v34
	v_cndmask_b32_e64 v50, v56, v50, s[10:11]
	v_cndmask_b32_e64 v29, v29, v50, s[8:9]
	v_cndmask_b32_e32 v24, v24, v53, vcc
	v_cmp_eq_u32_e32 vcc, 5, v34
	ds_bpermute_b32 v29, v169, v29
	s_and_b32 s1, s1, 0x1800
	v_cndmask_b32_e32 v34, v32, v53, vcc
	v_cmp_eq_u32_e32 vcc, 7, v28
	s_or_b32 s0, s0, s1
	s_nop 0
	v_cndmask_b32_e32 v51, v51, v56, vcc
	v_cmp_eq_u32_e32 vcc, 5, v28
	s_nop 1
	v_cndmask_b32_e32 v34, v34, v56, vcc
	v_cmp_eq_u32_e32 vcc, 0, v28
	s_nop 1
	v_cndmask_b32_e32 v24, v24, v56, vcc
	v_cmp_eq_u32_e32 vcc, 1, v28
	s_nop 1
	v_cndmask_b32_e32 v53, v57, v56, vcc
	v_cmp_eq_u32_e32 vcc, 2, v28
	s_nop 1
	v_cndmask_b32_e32 v54, v54, v56, vcc
	v_cmp_eq_u32_e32 vcc, 3, v28
	s_nop 1
	v_cndmask_b32_e32 v46, v46, v56, vcc
	v_cmp_eq_u32_e32 vcc, 4, v28
	s_nop 1
	v_cndmask_b32_e32 v49, v49, v56, vcc
	v_cmp_eq_u32_e32 vcc, 6, v28
	s_nop 1
	v_cndmask_b32_e32 v28, v55, v56, vcc
	v_cmp_eq_u32_e32 vcc, 3, v136
	s_nop 1
	v_cndmask_b32_e32 v21, v21, v20, vcc
	v_cmp_eq_u32_e32 vcc, 7, v136
	s_nop 1
	v_cndmask_b32_e32 v17, v17, v20, vcc
	v_cmp_eq_u32_e32 vcc, 6, v136
	s_nop 1
	v_cndmask_b32_e32 v40, v40, v20, vcc
	v_cmp_eq_u32_e32 vcc, 4, v136
	s_nop 1
	v_cndmask_b32_e32 v26, v26, v20, vcc
	v_cmp_eq_u32_e32 vcc, 2, v136
	s_nop 1
	v_cndmask_b32_e32 v39, v39, v20, vcc
	v_cmp_eq_u32_e32 vcc, 1, v136
	s_nop 1
	v_cndmask_b32_e32 v38, v38, v20, vcc
	v_cmp_eq_u32_e32 vcc, 0, v136
	s_nop 1
	v_cndmask_b32_e32 v37, v37, v20, vcc
	v_cmp_eq_u32_e32 vcc, 5, v136
	s_nop 1
	v_cndmask_b32_e32 v20, v27, v20, vcc
	v_cmp_eq_u32_e32 vcc, 7, v22
	s_nop 1
	v_cndmask_b32_e32 v17, v17, v16, vcc
	v_cmp_eq_u32_e32 vcc, 5, v22
	s_nop 1
	v_cndmask_b32_e32 v20, v20, v16, vcc
	v_cmp_eq_u32_e32 vcc, 0, v22
	s_nop 1
	v_cndmask_b32_e32 v27, v37, v16, vcc
	v_cmp_eq_u32_e32 vcc, 1, v22
	s_nop 1
	v_cndmask_b32_e32 v37, v38, v16, vcc
	v_cmp_eq_u32_e32 vcc, 2, v22
	s_nop 1
	v_cndmask_b32_e32 v38, v39, v16, vcc
	v_cmp_eq_u32_e32 vcc, 3, v22
	ds_bpermute_b32 v39, v168, v48
	s_waitcnt lgkmcnt(0)
; DI u32x4 pk8(const f32x4& v0, const f32x4& v1) { u32x4 w; w.x = cvt_pk_bf16(v0[0], v0[1]); w.y = cvt_pk_bf16(v0[2], v0[3]); w.z = cvt_pk_bf16(v1[0], v1[1]); w.w = cvt_pk_bf16(v1[2], v1[3]); return w; }
; DI void transpose8(float (&v)[8], int lane) { tstage8<4>(v, lane); tstage8<2>(v, lane); tstage8<1>(v, lane); }
;   DI void epi(const Acc& acc, const Unit& u, int wr, int wc, int fr, int fq, LAS unsigned char* lds) const {
;     ...
;           const int rl = u.pm * 256 + ai * 128 + wr * 64 + m * 16 + fr; const int pos = tok_pos(rb + rl);
;           const unsigned to = (unsigned)(pos * 128 + d0) * 4u; const f32x4 c0 = ldf4(cosR, to), c1 = ldf4(cosR, to + 16u);
;           const f32x4 s0 = ldf4(sinR, to), s1 = ldf4(sinR, to + 16u);
;           const f32x4 a0 = acc[ai][0][m][0], a1 = acc[ai][0][m][1], b0 = acc[ai][1][m][0], b1 = acc[ai][1][m][1];
;           const f32x4 x0 = (a0 * c0 - b0 * s0) * sc, x1 = (a1 * c1 - b1 * s1) * sc, y0 = (b0 * c0 + a0 * s0) * sc, y1 = (b1 * c1 + a1 * s1) * sc;
;           const unsigned ro = fo + (unsigned)(rl >> 7) * 262144u + (unsigned)((rl >> 5) & 3) * 16384u + (unsigned)(rl & 31) * 16u;
;           st16(base, ro, pk8(x0, x1));
;           st16(base, ro + 8192u, pk8(y0, y1));
;           if (!isq) {
;             float vx[8] = {x0[0], x0[1], x0[2], x0[3], x1[0], x1[1], x1[2], x1[3]}, vy[8] = {y0[0], y0[1], y0[2], y0[3], y1[0], y1[1], y1[2], y1[3]};
;             const int lane = fq * 16 + fr;
;             transpose8(vx, lane); transpose8(vy, lane);
;             const int tl = rl & ~7, dk = d0 + (fr & 7);
;             const unsigned kro = (unsigned)((tl >> 7) * 4 + hd) * 65536u + (unsigned)(dk >> 5) * 8192u + (unsigned)((tl & 127) >> 4) * 1024u + (unsigned)((tl >> 3) & 1) * 512u + (unsigned)(dk & 31) * 16u;
;             st16(kT, kro, pk8((f32x4){vx[0], vx[1], vx[2], vx[3]}, (f32x4){vx[4], vx[5], vx[6], vx[7]}));
;             st16(kT, kro + 4u * 8192u, pk8((f32x4){vy[0], vy[1], vy[2], vy[3]}, (f32x4){vy[4], vy[5], vy[6], vy[7]}));
	v_cndmask_b32_e64 v33, v33, v39, s[10:11]
	v_cndmask_b32_e32 v21, v21, v16, vcc
	v_cmp_eq_u32_e32 vcc, 4, v22
	v_cndmask_b32_e64 v32, v39, v32, s[10:11]
	v_cndmask_b32_e64 v32, v35, v32, s[8:9]
	v_cndmask_b32_e32 v26, v26, v16, vcc
	v_cmp_eq_u32_e32 vcc, 6, v22
	v_cndmask_b32_e64 v31, v31, v33, s[8:9]
	ds_bpermute_b32 v32, v169, v32
	v_cndmask_b32_e32 v16, v40, v16, vcc
	v_cmp_eq_u32_e32 vcc, 6, v18
	ds_bpermute_b32 v31, v169, v31
	s_nop 0
	v_cndmask_b32_e32 v16, v16, v19, vcc
	v_cmp_eq_u32_e32 vcc, 4, v18
	s_nop 1
	v_cndmask_b32_e32 v22, v26, v19, vcc
	v_cmp_eq_u32_e32 vcc, 3, v18
	v_cndmask_b32_e64 v22, v44, v22, s[8:9]
	s_nop 0
	v_cndmask_b32_e32 v21, v21, v19, vcc
	v_cmp_eq_u32_e32 vcc, 2, v18
	v_cndmask_b32_e64 v21, v21, v43, s[8:9]
	s_nop 0
	v_cndmask_b32_e32 v26, v38, v19, vcc
	v_cmp_eq_u32_e32 vcc, 1, v18
	s_nop 1
	v_cndmask_b32_e32 v37, v37, v19, vcc
	v_cmp_eq_u32_e32 vcc, 0, v18
	s_nop 1
	v_cndmask_b32_e32 v27, v27, v19, vcc
	v_cmp_eq_u32_e32 vcc, 5, v18
	s_nop 1
	v_cndmask_b32_e32 v20, v20, v19, vcc
	v_cmp_eq_u32_e32 vcc, 7, v18
	v_cndmask_b32_e64 v18, v23, v20, s[10:11]
	v_cndmask_b32_e64 v20, v37, v42, s[8:9]
	v_cndmask_b32_e32 v17, v17, v19, vcc
	v_cmp_eq_u32_e32 vcc, 6, v30
	v_cndmask_b32_e64 v17, v17, v23, s[10:11]
	v_cndmask_b32_e64 v23, v43, v26, s[8:9]
	v_cndmask_b32_e64 v26, v45, v16, s[8:9]
	v_cndmask_b32_e32 v16, v28, v47, vcc
	v_cmp_eq_u32_e32 vcc, 4, v30
	v_cndmask_b32_e64 v19, v42, v27, s[8:9]
	v_cndmask_b32_e64 v27, v17, v45, s[8:9]
	v_cndmask_b32_e32 v17, v49, v47, vcc
	v_cmp_eq_u32_e32 vcc, 3, v30
	v_cndmask_b32_e64 v18, v18, v44, s[8:9]
	s_nop 0
	v_cndmask_b32_e32 v28, v46, v47, vcc
	v_cmp_eq_u32_e32 vcc, 2, v30
	s_nop 1
	v_cndmask_b32_e32 v37, v54, v47, vcc
	v_cmp_eq_u32_e32 vcc, 1, v30
	v_cndmask_b32_e64 v33, v25, v37, s[8:9]
	v_cndmask_b32_e64 v25, v28, v25, s[8:9]
	v_cndmask_b32_e32 v38, v53, v47, vcc
	v_cmp_eq_u32_e32 vcc, 0, v30
	s_waitcnt lgkmcnt(0)
	v_cndmask_b32_e64 v28, v32, v17, s[8:9]
	v_cndmask_b32_e32 v24, v24, v47, vcc
	v_cmp_eq_u32_e32 vcc, 5, v30
	v_cndmask_b32_e64 v24, v29, v24, s[8:9]
	v_cndmask_b32_e64 v29, v38, v29, s[8:9]
	v_cndmask_b32_e32 v34, v34, v47, vcc
	v_cndmask_b32_e64 v34, v39, v34, s[10:11]
	v_cndmask_b32_e64 v32, v34, v32, s[8:9]
	v_cndmask_b32_e64 v34, v31, v16, s[8:9]
	v_lshlrev_b32_e32 v16, 6, v36
	v_and_b32_e32 v16, 0x200, v16
	v_cmp_eq_u32_e32 vcc, 7, v30
	v_or3_b32 v176, s0, v16, v170
	v_cvt_pk_bf16_f32 v16, v19, v20
	v_cvt_pk_bf16_f32 v17, v23, v21
	v_lshl_add_u64 v[20:21], s[24:25], 0, v[176:177]
	v_cndmask_b32_e32 v30, v51, v47, vcc
	v_or_b32_e32 v176, 0x8000, v176
	v_cndmask_b32_e64 v30, v30, v39, s[10:11]
	v_cvt_pk_bf16_f32 v18, v22, v18
	v_cvt_pk_bf16_f32 v19, v26, v27
	global_store_dwordx4 v[20:21], v[16:19], off
	v_lshl_add_u64 v[20:21], s[24:25], 0, v[176:177]
	v_cndmask_b32_e64 v30, v30, v31, s[8:9]
	v_cvt_pk_bf16_f32 v16, v24, v29
	v_cvt_pk_bf16_f32 v17, v33, v25
	v_cvt_pk_bf16_f32 v18, v28, v32
	v_cvt_pk_bf16_f32 v19, v34, v30
	global_store_dwordx4 v[20:21], v[16:19], off
.LBB0_196:
	s_or_b32 s4, s2, 48
	v_or_b32_e32 v20, s4, v137
	v_add_u32_e32 v16, s34, v20
	v_cmp_gt_i32_e32 vcc, s55, v16
	v_mov_b32_e32 v17, 0xfff
	v_mov_b32_e32 v18, 0x7ff
	v_cndmask_b32_e32 v17, v17, v18, vcc
	v_and_b32_e32 v16, v17, v16
	v_lshl_or_b32 v176, v16, 9, v166
	v_lshl_add_u64 v[16:17], s[30:31], 0, v[176:177]
	v_or_b32_e32 v30, 16, v176
	v_mov_b32_e32 v31, v177
	global_load_dwordx4 v[16:19], v[16:17], off
	v_lshl_add_u64 v[22:23], s[28:29], 0, v[176:177]
	v_lshl_add_u64 v[26:27], s[30:31], 0, v[30:31]
	global_load_dwordx4 v[22:25], v[22:23], off
	v_lshl_add_u64 v[30:31], s[28:29], 0, v[30:31]
	global_load_dwordx4 v[26:29], v[26:27], off
	s_lshl_b32 s0, s4, 9
	global_load_dwordx4 v[30:33], v[30:31], off
	v_lshlrev_b32_e32 v21, 4, v20
	s_and_b32 s0, s0, 0xc000
	v_and_b32_e32 v21, 0x1f0, v21
	v_or3_b32 v176, s0, v21, v62
	v_mov_b32_e32 v34, v142
	v_mov_b32_e32 v35, v142
	v_lshl_add_u64 v[36:37], s[26:27], 0, v[176:177]
	v_or_b32_e32 v176, 0x2000, v176
	v_lshl_add_u64 v[38:39], s[26:27], 0, v[176:177]
	s_and_b64 vcc, exec, s[12:13]
	s_waitcnt vmcnt(0) lgkmcnt(0)
	v_pk_mul_f32 v[40:41], v[6:7], v[18:19]
	v_pk_mul_f32 v[42:43], v[4:5], v[16:17]
	v_pk_mul_f32 v[18:19], v[14:15], v[18:19]
	v_pk_mul_f32 v[16:17], v[12:13], v[16:17]
	v_pk_fma_f32 v[14:15], v[14:15], v[24:25], v[40:41] neg_lo:[0,0,1] neg_hi:[0,0,1]
	v_pk_fma_f32 v[12:13], v[12:13], v[22:23], v[42:43] neg_lo:[0,0,1] neg_hi:[0,0,1]
	v_pk_mul_f32 v[40:41], v[2:3], v[28:29]
	v_pk_mul_f32 v[42:43], v[0:1], v[26:27]
	v_pk_fma_f32 v[18:19], v[6:7], v[24:25], v[18:19]
	v_pk_fma_f32 v[16:17], v[4:5], v[22:23], v[16:17]
	v_pk_mul_f32 v[22:23], v[10:11], v[28:29]
	v_pk_mul_f32 v[24:25], v[8:9], v[26:27]
	v_pk_mul_f32 v[6:7], v[142:143], v[12:13]
	v_pk_fma_f32 v[10:11], v[10:11], v[32:33], v[40:41] neg_lo:[0,0,1] neg_hi:[0,0,1]
	v_pk_fma_f32 v[12:13], v[8:9], v[30:31], v[42:43] neg_lo:[0,0,1] neg_hi:[0,0,1]
	v_pk_mul_f32 v[8:9], v[142:143], v[16:17]
	v_pk_fma_f32 v[2:3], v[2:3], v[32:33], v[22:23]
	v_pk_fma_f32 v[16:17], v[0:1], v[30:31], v[24:25]
	v_pk_mul_f32 v[4:5], v[34:35], v[14:15]
	v_pk_mul_f32 v[18:19], v[34:35], v[18:19]
	v_pk_mul_f32 v[0:1], v[34:35], v[10:11]
	v_pk_mul_f32 v[10:11], v[142:143], v[12:13]
	v_pk_mul_f32 v[14:15], v[34:35], v[2:3]
	v_pk_mul_f32 v[16:17], v[142:143], v[16:17]
	v_cvt_pk_bf16_f32 v22, v6, v7
	v_cvt_pk_bf16_f32 v23, v4, v5
	v_cvt_pk_bf16_f32 v24, v10, v11
	v_cvt_pk_bf16_f32 v25, v0, v1
	global_store_dwordx4 v[36:37], v[22:25], off
	s_nop 1
	v_cvt_pk_bf16_f32 v22, v8, v9
	v_cvt_pk_bf16_f32 v23, v18, v19
	v_cvt_pk_bf16_f32 v24, v16, v17
	v_cvt_pk_bf16_f32 v25, v14, v15
	global_store_dwordx4 v[38:39], v[22:25], off
	s_cbranch_vccnz .LBB0_204
; DI float shx(float v, int lane, int mask) { return __int_as_float(__builtin_amdgcn_ds_bpermute((lane ^ mask) << 2, __float_as_int(v))); }
; DI void transpose8(float (&v)[8], int lane) { tstage8<4>(v, lane); tstage8<2>(v, lane); tstage8<1>(v, lane); }
; template <int K> DI void tstage8(float (&v)[8], int lane) {
;   const bool up = (lane & K) != 0;
; #pragma unroll
;   for (int j = 0; j < 8; ++j) {
;     if ((j & K) == 0) {
;       const float send = up ? v[j] : v[j | K];
;       const float recv = shx(send, lane, K);
;       if (up) v[j] = recv; else v[j | K] = recv;
;     }
;   }
; }
;   DI void epi(const Acc& acc, const Unit& u, int wr, int wc, int fr, int fq, LAS unsigned char* lds) const {
;     ...
;             float vx[8] = {x0[0], x0[1], x0[2], x0[3], x1[0], x1[1], x1[2], x1[3]}, vy[8] = {y0[0], y0[1], y0[2], y0[3], y1[0], y1[1], y1[2], y1[3]};
;             const int lane = fq * 16 + fr;
;             transpose8(vx, lane); transpose8(vy, lane);
	v_cndmask_b32_e64 v2, v6, v10, s[6:7]
	ds_bpermute_b32 v30, v167, v2
	v_cndmask_b32_e64 v3, v4, v0, s[6:7]
	v_cndmask_b32_e64 v2, v7, v11, s[6:7]
	ds_bpermute_b32 v3, v167, v3
	ds_bpermute_b32 v2, v167, v2
	s_waitcnt lgkmcnt(0)
	v_cndmask_b32_e64 v21, v30, v6, s[6:7]
	v_cndmask_b32_e64 v6, v5, v1, s[6:7]
	ds_bpermute_b32 v25, v167, v6
	v_cndmask_b32_e64 v23, v3, v4, s[6:7]
	v_cndmask_b32_e64 v22, v2, v7, s[6:7]
	v_cndmask_b32_e64 v24, v0, v3, s[6:7]
	v_cndmask_b32_e64 v0, v21, v23, s[10:11]
	s_waitcnt lgkmcnt(0)
	v_cndmask_b32_e64 v28, v25, v5, s[6:7]
	ds_bpermute_b32 v4, v168, v0
	v_cndmask_b32_e64 v0, v22, v28, s[10:11]
	ds_bpermute_b32 v0, v168, v0
	v_cndmask_b32_e64 v26, v10, v30, s[6:7]
	v_cndmask_b32_e64 v11, v11, v2, s[6:7]
	v_mov_b64_e32 v[12:13], 1
	v_mov_b64_e32 v[2:3], 4
	v_cndmask_b32_e64 v27, v1, v25, s[6:7]
	v_mov_b32_e32 v13, v11
	v_mov_b64_e32 v[6:7], 1
	v_mov_b32_e32 v3, v26
	s_waitcnt lgkmcnt(0)
	v_mov_b32_e32 v29, v0
	s_and_saveexec_b64 s[0:1], s[10:11]
	v_mov_b64_e32 v[2:3], 6
	v_mov_b64_e32 v[6:7], 3
	v_mov_b32_e32 v13, v27
	v_mov_b32_e32 v3, v24
	v_mov_b32_e32 v28, v0
	v_mov_b32_e32 v29, v22
	s_or_b64 exec, exec, s[0:1]
	ds_bpermute_b32 v7, v168, v13
	ds_bpermute_b32 v3, v168, v3
	v_cndmask_b32_e64 v13, v23, v4, s[10:11]
	v_cndmask_b32_e64 v13, v13, v28, s[8:9]
	v_cndmask_b32_e64 v31, v4, v21, s[10:11]
	s_waitcnt lgkmcnt(0)
	v_cndmask_b32_e64 v34, v27, v7, s[10:11]
	ds_bpermute_b32 v27, v169, v13
	v_cndmask_b32_e64 v13, v8, v16, s[6:7]
	ds_bpermute_b32 v35, v167, v13
	v_cndmask_b32_e64 v33, v3, v26, s[10:11]
	v_cndmask_b32_e64 v36, v7, v11, s[10:11]
	v_cndmask_b32_e64 v32, v24, v3, s[10:11]
	v_cndmask_b32_e64 v13, v33, v36, s[8:9]
	ds_bpermute_b32 v28, v169, v13
	v_cndmask_b32_e64 v13, v32, v34, s[8:9]
	v_cndmask_b32_e64 v26, v31, v29, s[8:9]
	ds_bpermute_b32 v29, v169, v13
	v_cndmask_b32_e64 v13, v9, v17, s[6:7]
	s_waitcnt lgkmcnt(0)
	v_cndmask_b32_e64 v33, v16, v35, s[6:7]
	ds_bpermute_b32 v16, v167, v13
	v_cndmask_b32_e64 v13, v18, v14, s[6:7]
	ds_bpermute_b32 v13, v167, v13
	v_cndmask_b32_e64 v31, v19, v15, s[6:7]
	v_cndmask_b32_e64 v32, v35, v8, s[6:7]
	ds_bpermute_b32 v31, v167, v31
	s_waitcnt lgkmcnt(0)
	v_cndmask_b32_e64 v34, v16, v9, s[6:7]
	v_cndmask_b32_e64 v38, v13, v18, s[6:7]
	v_cndmask_b32_e64 v9, v32, v38, s[10:11]
	ds_bpermute_b32 v37, v168, v9
	ds_bpermute_b32 v26, v169, v26
	v_cndmask_b32_e64 v36, v31, v19, s[6:7]
	v_mov_b64_e32 v[18:19], 0
	v_cndmask_b32_e64 v39, v14, v13, s[6:7]
	v_mov_b32_e32 v14, v33
	v_mov_b32_e32 v19, v34
	v_mov_b32_e32 v9, v38
	s_waitcnt lgkmcnt(0)
	v_mov_b32_e32 v13, v37
	s_and_saveexec_b64 s[0:1], s[10:11]
	v_mov_b64_e32 v[18:19], 2
	v_mov_b64_e32 v[12:13], 3
	v_mov_b32_e32 v14, v39
	v_mov_b32_e32 v19, v36
	v_mov_b32_e32 v9, v37
	v_mov_b32_e32 v13, v32
	s_or_b64 exec, exec, s[0:1]
	v_cndmask_b32_e64 v16, v17, v16, s[6:7]
	v_cndmask_b32_e64 v17, v15, v31, s[6:7]
	ds_bpermute_b32 v31, v168, v14
	ds_bpermute_b32 v40, v168, v19
	v_mov_b64_e32 v[14:15], 4
	v_mov_b32_e32 v32, v16
	v_mov_b32_e32 v15, v39
	s_waitcnt lgkmcnt(0)
; DI float shx(float v, int lane, int mask) { return __int_as_float(__builtin_amdgcn_ds_bpermute((lane ^ mask) << 2, __float_as_int(v))); }
; DI u32x4 pk8(const f32x4& v0, const f32x4& v1) { u32x4 w; w.x = cvt_pk_bf16(v0[0], v0[1]); w.y = cvt_pk_bf16(v0[2], v0[3]); w.z = cvt_pk_bf16(v1[0], v1[1]); w.w = cvt_pk_bf16(v1[2], v1[3]); return w; }
; DI void transpose8(float (&v)[8], int lane) { tstage8<4>(v, lane); tstage8<2>(v, lane); tstage8<1>(v, lane); }
; template <int K> DI void tstage8(float (&v)[8], int lane) {
;   const bool up = (lane & K) != 0;
; #pragma unroll
;   for (int j = 0; j < 8; ++j) {
;     if ((j & K) == 0) {
;       const float send = up ? v[j] : v[j | K];
;       const float recv = shx(send, lane, K);
;       if (up) v[j] = recv; else v[j | K] = recv;
;     }
;   }
; }
;   DI void epi(const Acc& acc, const Unit& u, int wr, int wc, int fr, int fq, LAS unsigned char* lds) const {
;     ...
;             float vx[8] = {x0[0], x0[1], x0[2], x0[3], x1[0], x1[1], x1[2], x1[3]}, vy[8] = {y0[0], y0[1], y0[2], y0[3], y1[0], y1[1], y1[2], y1[3]};
;             const int lane = fq * 16 + fr;
;             transpose8(vx, lane); transpose8(vy, lane);
;             const int tl = rl & ~7, dk = d0 + (fr & 7);
;             const unsigned kro = (unsigned)((tl >> 7) * 4 + hd) * 65536u + (unsigned)(dk >> 5) * 8192u + (unsigned)((tl & 127) >> 4) * 1024u + (unsigned)((tl >> 3) & 1) * 512u + (unsigned)(dk & 31) * 16u;
;             st16(kT, kro, pk8((f32x4){vx[0], vx[1], vx[2], vx[3]}, (f32x4){vx[4], vx[5], vx[6], vx[7]}));
;             st16(kT, kro + 4u * 8192u, pk8((f32x4){vy[0], vy[1], vy[2], vy[3]}, (f32x4){vy[4], vy[5], vy[6], vy[7]}));
	v_mov_b32_e32 v19, v31
	s_and_saveexec_b64 s[0:1], s[10:11]
	v_mov_b64_e32 v[14:15], 6
	v_mov_b32_e32 v32, v17
	v_mov_b32_e32 v15, v31
	v_mov_b32_e32 v19, v33
	s_or_b64 exec, exec, s[0:1]
	v_cmp_eq_u32_e32 vcc, 3, v18
	v_cndmask_b32_e64 v10, v10, v30, s[6:7]
	v_cndmask_b32_e64 v8, v35, v8, s[6:7]
	v_cndmask_b32_e32 v30, v36, v37, vcc
	v_cmp_eq_u32_e32 vcc, 7, v18
	v_cndmask_b32_e64 v5, v25, v5, s[6:7]
	v_cndmask_b32_e64 v1, v1, v25, s[6:7]
	v_cndmask_b32_e32 v35, v17, v37, vcc
	v_cmp_eq_u32_e32 vcc, 6, v18
	v_cndmask_b32_e64 v36, v36, v40, s[10:11]
	v_cndmask_b32_e64 v9, v9, v36, s[8:9]
	v_cndmask_b32_e32 v39, v39, v37, vcc
	v_cmp_eq_u32_e32 vcc, 4, v18
	ds_bpermute_b32 v9, v169, v9
	s_lshr_b32 s0, s2, 5
	v_cndmask_b32_e32 v33, v33, v37, vcc
	v_cmp_eq_u32_e32 vcc, 2, v18
	s_and_b32 s0, s0, 0xfffc
	s_add_i32 s0, s0, s54
	v_cndmask_b32_e32 v38, v38, v37, vcc
	v_cmp_eq_u32_e32 vcc, 1, v18
	s_lshl_b32 s1, s4, 6
	s_lshl_b32 s0, s0, 16
	v_cndmask_b32_e32 v41, v34, v37, vcc
	v_cmp_eq_u32_e32 vcc, 0, v18
	v_cndmask_b32_e64 v34, v40, v34, s[10:11]
	v_cndmask_b32_e64 v13, v13, v34, s[8:9]
	v_cndmask_b32_e32 v8, v8, v37, vcc
	v_cmp_eq_u32_e32 vcc, 5, v18
	ds_bpermute_b32 v13, v169, v13
	s_and_b32 s1, s1, 0x1c00
	v_cndmask_b32_e32 v18, v16, v37, vcc
	v_cmp_eq_u32_e32 vcc, 7, v12
	s_or_b32 s0, s0, s1
	s_nop 0
	v_cndmask_b32_e32 v35, v35, v40, vcc
	v_cmp_eq_u32_e32 vcc, 5, v12
	s_nop 1
	v_cndmask_b32_e32 v18, v18, v40, vcc
	v_cmp_eq_u32_e32 vcc, 0, v12
	s_nop 1
	v_cndmask_b32_e32 v8, v8, v40, vcc
	v_cmp_eq_u32_e32 vcc, 1, v12
	s_nop 1
	v_cndmask_b32_e32 v37, v41, v40, vcc
	v_cmp_eq_u32_e32 vcc, 2, v12
	s_nop 1
	v_cndmask_b32_e32 v38, v38, v40, vcc
	v_cmp_eq_u32_e32 vcc, 3, v12
	s_nop 1
	v_cndmask_b32_e32 v30, v30, v40, vcc
	v_cmp_eq_u32_e32 vcc, 4, v12
	s_nop 1
	v_cndmask_b32_e32 v33, v33, v40, vcc
	v_cmp_eq_u32_e32 vcc, 6, v12
	s_nop 1
	v_cndmask_b32_e32 v12, v39, v40, vcc
	v_cmp_eq_u32_e32 vcc, 3, v136
	s_nop 1
	v_cndmask_b32_e32 v5, v5, v4, vcc
	v_cmp_eq_u32_e32 vcc, 7, v136
	s_nop 1
	v_cndmask_b32_e32 v1, v1, v4, vcc
	v_cmp_eq_u32_e32 vcc, 6, v136
	s_nop 1
	v_cndmask_b32_e32 v24, v24, v4, vcc
	v_cmp_eq_u32_e32 vcc, 4, v136
	s_nop 1
	v_cndmask_b32_e32 v10, v10, v4, vcc
	v_cmp_eq_u32_e32 vcc, 2, v136
	s_nop 1
	v_cndmask_b32_e32 v23, v23, v4, vcc
	v_cmp_eq_u32_e32 vcc, 1, v136
	s_nop 1
	v_cndmask_b32_e32 v22, v22, v4, vcc
	v_cmp_eq_u32_e32 vcc, 0, v136
	s_nop 1
	v_cndmask_b32_e32 v21, v21, v4, vcc
	v_cmp_eq_u32_e32 vcc, 5, v136
	s_nop 1
	v_cndmask_b32_e32 v4, v11, v4, vcc
	v_cmp_eq_u32_e32 vcc, 7, v6
	s_nop 1
	v_cndmask_b32_e32 v1, v1, v0, vcc
	v_cmp_eq_u32_e32 vcc, 5, v6
	s_nop 1
	v_cndmask_b32_e32 v4, v4, v0, vcc
	v_cmp_eq_u32_e32 vcc, 0, v6
	s_nop 1
	v_cndmask_b32_e32 v11, v21, v0, vcc
	v_cmp_eq_u32_e32 vcc, 1, v6
	s_nop 1
	v_cndmask_b32_e32 v21, v22, v0, vcc
	v_cmp_eq_u32_e32 vcc, 2, v6
	s_nop 1
	v_cndmask_b32_e32 v22, v23, v0, vcc
	v_cmp_eq_u32_e32 vcc, 3, v6
	ds_bpermute_b32 v23, v168, v32
	s_waitcnt lgkmcnt(0)
	v_cndmask_b32_e64 v17, v17, v23, s[10:11]
	v_cndmask_b32_e32 v5, v5, v0, vcc
	v_cmp_eq_u32_e32 vcc, 4, v6
	v_cndmask_b32_e64 v16, v23, v16, s[10:11]
	v_cndmask_b32_e64 v16, v19, v16, s[8:9]
	v_cndmask_b32_e32 v10, v10, v0, vcc
	v_cmp_eq_u32_e32 vcc, 6, v6
	v_cndmask_b32_e64 v15, v15, v17, s[8:9]
	ds_bpermute_b32 v16, v169, v16
	v_cndmask_b32_e32 v0, v24, v0, vcc
	v_cmp_eq_u32_e32 vcc, 6, v2
	ds_bpermute_b32 v15, v169, v15
	s_nop 0
	v_cndmask_b32_e32 v0, v0, v3, vcc
	v_cmp_eq_u32_e32 vcc, 4, v2
	s_nop 1
	v_cndmask_b32_e32 v6, v10, v3, vcc
	v_cmp_eq_u32_e32 vcc, 3, v2
	v_cndmask_b32_e64 v6, v28, v6, s[8:9]
	s_nop 0
	v_cndmask_b32_e32 v5, v5, v3, vcc
	v_cmp_eq_u32_e32 vcc, 2, v2
	v_cndmask_b32_e64 v5, v5, v27, s[8:9]
	s_nop 0
	v_cndmask_b32_e32 v10, v22, v3, vcc
	v_cmp_eq_u32_e32 vcc, 1, v2
	s_nop 1
	v_cndmask_b32_e32 v21, v21, v3, vcc
	v_cmp_eq_u32_e32 vcc, 0, v2
	s_nop 1
	v_cndmask_b32_e32 v11, v11, v3, vcc
	v_cmp_eq_u32_e32 vcc, 5, v2
	s_nop 1
	v_cndmask_b32_e32 v4, v4, v3, vcc
	v_cmp_eq_u32_e32 vcc, 7, v2
	v_cndmask_b32_e64 v2, v7, v4, s[10:11]
	v_cndmask_b32_e64 v4, v21, v26, s[8:9]
	v_cndmask_b32_e32 v1, v1, v3, vcc
	v_cmp_eq_u32_e32 vcc, 6, v14
	v_cndmask_b32_e64 v1, v1, v7, s[10:11]
	v_cndmask_b32_e64 v7, v27, v10, s[8:9]
	v_cndmask_b32_e64 v10, v29, v0, s[8:9]
	v_cndmask_b32_e32 v0, v12, v31, vcc
	v_cmp_eq_u32_e32 vcc, 4, v14
	v_cndmask_b32_e64 v3, v26, v11, s[8:9]
	v_cndmask_b32_e64 v11, v1, v29, s[8:9]
	v_cndmask_b32_e32 v1, v33, v31, vcc
	v_cmp_eq_u32_e32 vcc, 3, v14
	v_cndmask_b32_e64 v2, v2, v28, s[8:9]
	s_nop 0
	v_cndmask_b32_e32 v12, v30, v31, vcc
	v_cmp_eq_u32_e32 vcc, 2, v14
	s_nop 1
	v_cndmask_b32_e32 v21, v38, v31, vcc
	v_cmp_eq_u32_e32 vcc, 1, v14
	v_cndmask_b32_e64 v17, v9, v21, s[8:9]
	v_cndmask_b32_e64 v9, v12, v9, s[8:9]
	v_cndmask_b32_e32 v22, v37, v31, vcc
	v_cmp_eq_u32_e32 vcc, 0, v14
	s_waitcnt lgkmcnt(0)
	v_cndmask_b32_e64 v12, v16, v1, s[8:9]
	v_cndmask_b32_e32 v8, v8, v31, vcc
	v_cmp_eq_u32_e32 vcc, 5, v14
	v_cndmask_b32_e64 v8, v13, v8, s[8:9]
	v_cndmask_b32_e64 v13, v22, v13, s[8:9]
	v_cndmask_b32_e32 v18, v18, v31, vcc
	v_cndmask_b32_e64 v18, v23, v18, s[10:11]
	v_cndmask_b32_e64 v16, v18, v16, s[8:9]
	v_cndmask_b32_e64 v18, v15, v0, s[8:9]
	v_lshlrev_b32_e32 v0, 6, v20
	v_and_b32_e32 v0, 0x200, v0
	v_cmp_eq_u32_e32 vcc, 7, v14
	v_or3_b32 v176, s0, v0, v170
	v_cvt_pk_bf16_f32 v0, v3, v4
	v_cvt_pk_bf16_f32 v1, v7, v5
	v_lshl_add_u64 v[4:5], s[24:25], 0, v[176:177]
	v_cndmask_b32_e32 v14, v35, v31, vcc
	v_or_b32_e32 v176, 0x8000, v176
	v_cndmask_b32_e64 v14, v14, v23, s[10:11]
	v_cvt_pk_bf16_f32 v2, v6, v2
	v_cvt_pk_bf16_f32 v3, v10, v11
	global_store_dwordx4 v[4:5], v[0:3], off
	v_lshl_add_u64 v[4:5], s[24:25], 0, v[176:177]
	v_cndmask_b32_e64 v14, v14, v15, s[8:9]
	v_cvt_pk_bf16_f32 v0, v8, v13
	v_cvt_pk_bf16_f32 v1, v17, v9
	v_cvt_pk_bf16_f32 v2, v12, v16
	v_cvt_pk_bf16_f32 v3, v18, v14
	global_store_dwordx4 v[4:5], v[0:3], off

; DI u32x4 pk8(const f32x4& v0, const f32x4& v1) { u32x4 w; w.x = cvt_pk_bf16(v0[0], v0[1]); w.y = cvt_pk_bf16(v0[2], v0[3]); w.z = cvt_pk_bf16(v1[0], v1[1]); w.w = cvt_pk_bf16(v1[2], v1[3]); return w; }
;   DI void epi(const Acc& acc, const Unit& u, int wr, int wc, int fr, int fq, LAS unsigned char* lds) const {
;     ...
; #pragma unroll
;       for (int ai = 0; ai < 2; ++ai)
; #pragma unroll
;         for (int m = 0; m < 4; ++m) {
;           const int row = ai * 128 + wr * 64 + m * 16 + fr;
; #pragma unroll
;           for (int bj = 0; bj < 2; ++bj)
;           {
;             const int tl = u.pn * 256 + bj * 128 + wc * 32 + 8 * fq, ko = tl & 31;
;             const unsigned bo = (unsigned)((((((row >> 6) * 1024 + (tl >> 5)) * 2 + ((row & 63) >> 5)) * 2 + (ko >> 4)) * 64 + (row & 31)) * 16 + ((ko >> 3) & 1) * 8);
;             const u32x4 w = pk8(acc[ai][bj][m][0], acc[ai][bj][m][1]);
;             *(u32x2*)((char*)vT + bo) = (u32x2){w.x, w.y};
;             *(u32x2*)((char*)vT + bo + 512u) = (u32x2){w.z, w.w}; }
;         }
.LBB0_269:
	s_mov_b64 s[0:1], s[86:87]
	s_cmp_eq_u32 s30, 0
	s_cbranch_scc1 .LBB0_336
	s_add_u32 s4, s0, 0xce00000
	s_addc_u32 s5, s1, 0
	s_lshl_b32 s10, s51, 8
	s_or_b32 s10, s10, s42
	s_lshr_b32 s10, s10, 3
	v_add_u32_e32 v140, s10, v158
	v_lshl_or_b32 v176, v140, 10, v166
	v_cvt_pk_bf16_f32 v140, v124, v125
	v_cvt_pk_bf16_f32 v141, v126, v127
	v_lshl_add_u64 v[144:145], s[4:5], 0, v[176:177]
	s_or_b32 s11, s10, 16
	v_cvt_pk_bf16_f32 v142, v120, v121
	v_cvt_pk_bf16_f32 v143, v122, v123
	global_store_dwordx2 v[144:145], v[140:141], off
	global_store_dwordx2 v[144:145], v[142:143], off offset:512
	v_add_u32_e32 v140, s11, v158
	v_lshl_or_b32 v140, v140, 10, v166
	v_mov_b32_e32 v141, v177
	v_cvt_pk_bf16_f32 v142, v116, v117
	v_cvt_pk_bf16_f32 v143, v118, v119
	v_cvt_pk_bf16_f32 v144, v112, v113
	v_cvt_pk_bf16_f32 v145, v114, v115
	v_lshl_add_u64 v[146:147], s[4:5], 0, v[140:141]
	v_or_b32_e32 v176, 0x100, v176
	global_store_dwordx2 v[146:147], v[142:143], off
	global_store_dwordx2 v[146:147], v[144:145], off offset:512
	v_cvt_pk_bf16_f32 v142, v108, v109
	v_cvt_pk_bf16_f32 v143, v110, v111
	v_cvt_pk_bf16_f32 v144, v104, v105
	v_cvt_pk_bf16_f32 v145, v106, v107
	v_lshl_add_u64 v[146:147], s[4:5], 0, v[176:177]
	v_or_b32_e32 v176, 0x100, v140
	global_store_dwordx2 v[146:147], v[142:143], off
	global_store_dwordx2 v[146:147], v[144:145], off offset:512
	v_cvt_pk_bf16_f32 v140, v100, v101
	v_cvt_pk_bf16_f32 v141, v102, v103
	v_lshl_add_u64 v[144:145], s[4:5], 0, v[176:177]
	v_cvt_pk_bf16_f32 v142, v96, v97
	v_cvt_pk_bf16_f32 v143, v98, v99
	global_store_dwordx2 v[144:145], v[140:141], off
	global_store_dwordx2 v[144:145], v[142:143], off offset:512
	v_add_u32_e32 v140, s10, v159
	v_lshl_or_b32 v176, v140, 10, v166
	v_cvt_pk_bf16_f32 v140, v92, v93
	v_cvt_pk_bf16_f32 v141, v94, v95
	v_lshl_add_u64 v[144:145], s[4:5], 0, v[176:177]
	v_cvt_pk_bf16_f32 v142, v88, v89
	v_cvt_pk_bf16_f32 v143, v90, v91
	global_store_dwordx2 v[144:145], v[140:141], off
	global_store_dwordx2 v[144:145], v[142:143], off offset:512
	v_add_u32_e32 v140, s11, v159
	v_lshl_or_b32 v140, v140, 10, v166
	v_mov_b32_e32 v141, v177
	v_cvt_pk_bf16_f32 v142, v84, v85
	v_cvt_pk_bf16_f32 v143, v86, v87
	v_cvt_pk_bf16_f32 v144, v80, v81
	v_cvt_pk_bf16_f32 v145, v82, v83
	v_lshl_add_u64 v[146:147], s[4:5], 0, v[140:141]
	v_or_b32_e32 v176, 0x100, v176
	global_store_dwordx2 v[146:147], v[142:143], off
	global_store_dwordx2 v[146:147], v[144:145], off offset:512
	v_cvt_pk_bf16_f32 v142, v76, v77
	v_cvt_pk_bf16_f32 v143, v78, v79
	v_cvt_pk_bf16_f32 v144, v72, v73
	v_cvt_pk_bf16_f32 v145, v74, v75
	v_lshl_add_u64 v[146:147], s[4:5], 0, v[176:177]
	v_or_b32_e32 v176, 0x100, v140
	global_store_dwordx2 v[146:147], v[142:143], off
	global_store_dwordx2 v[146:147], v[144:145], off offset:512
	v_cvt_pk_bf16_f32 v140, v68, v69
	v_cvt_pk_bf16_f32 v141, v70, v71
	v_lshl_add_u64 v[144:145], s[4:5], 0, v[176:177]
	v_cvt_pk_bf16_f32 v142, v64, v65
	v_cvt_pk_bf16_f32 v143, v66, v67
	global_store_dwordx2 v[144:145], v[140:141], off
	global_store_dwordx2 v[144:145], v[142:143], off offset:512
	v_add_u32_e32 v140, s10, v160
	v_lshl_or_b32 v176, v140, 10, v166
	v_cvt_pk_bf16_f32 v140, v60, v61
	v_cvt_pk_bf16_f32 v141, v62, v63
	v_lshl_add_u64 v[144:145], s[4:5], 0, v[176:177]
	v_cvt_pk_bf16_f32 v142, v56, v57
	v_cvt_pk_bf16_f32 v143, v58, v59
	global_store_dwordx2 v[144:145], v[140:141], off
	global_store_dwordx2 v[144:145], v[142:143], off offset:512
	v_add_u32_e32 v140, s11, v160
	v_lshl_or_b32 v140, v140, 10, v166
	v_mov_b32_e32 v141, v177
	v_cvt_pk_bf16_f32 v142, v52, v53
	v_cvt_pk_bf16_f32 v143, v54, v55
	v_cvt_pk_bf16_f32 v144, v48, v49
	v_cvt_pk_bf16_f32 v145, v50, v51
	v_lshl_add_u64 v[146:147], s[4:5], 0, v[140:141]
	v_or_b32_e32 v176, 0x100, v176
	global_store_dwordx2 v[146:147], v[142:143], off
	global_store_dwordx2 v[146:147], v[144:145], off offset:512
	v_cvt_pk_bf16_f32 v142, v44, v45
	v_cvt_pk_bf16_f32 v143, v46, v47
	v_cvt_pk_bf16_f32 v144, v40, v41
	v_cvt_pk_bf16_f32 v145, v42, v43
	v_lshl_add_u64 v[146:147], s[4:5], 0, v[176:177]
	v_or_b32_e32 v176, 0x100, v140
	global_store_dwordx2 v[146:147], v[142:143], off
	global_store_dwordx2 v[146:147], v[144:145], off offset:512
	v_cvt_pk_bf16_f32 v140, v36, v37
	v_cvt_pk_bf16_f32 v141, v38, v39
	v_lshl_add_u64 v[144:145], s[4:5], 0, v[176:177]
	v_cvt_pk_bf16_f32 v142, v32, v33
	v_cvt_pk_bf16_f32 v143, v34, v35
	global_store_dwordx2 v[144:145], v[140:141], off
	global_store_dwordx2 v[144:145], v[142:143], off offset:512
	v_add_u32_e32 v140, s10, v161
	v_lshl_or_b32 v176, v140, 10, v166
	v_cvt_pk_bf16_f32 v140, v28, v29
	v_cvt_pk_bf16_f32 v141, v30, v31
	v_lshl_add_u64 v[144:145], s[4:5], 0, v[176:177]
	v_cvt_pk_bf16_f32 v142, v24, v25
	v_cvt_pk_bf16_f32 v143, v26, v27
	global_store_dwordx2 v[144:145], v[140:141], off
	global_store_dwordx2 v[144:145], v[142:143], off offset:512
	v_add_u32_e32 v140, s11, v161
	v_lshl_or_b32 v140, v140, 10, v166
	v_mov_b32_e32 v141, v177
	v_cvt_pk_bf16_f32 v142, v20, v21
	v_cvt_pk_bf16_f32 v143, v22, v23
	v_cvt_pk_bf16_f32 v144, v16, v17
	v_cvt_pk_bf16_f32 v145, v18, v19
	v_lshl_add_u64 v[146:147], s[4:5], 0, v[140:141]
	v_or_b32_e32 v176, 0x100, v176
	global_store_dwordx2 v[146:147], v[142:143], off
	global_store_dwordx2 v[146:147], v[144:145], off offset:512
	v_cvt_pk_bf16_f32 v142, v12, v13
	v_cvt_pk_bf16_f32 v143, v14, v15
	v_cvt_pk_bf16_f32 v144, v8, v9
	v_cvt_pk_bf16_f32 v145, v10, v11
	v_lshl_add_u64 v[146:147], s[4:5], 0, v[176:177]
	v_or_b32_e32 v176, 0x100, v140
	global_store_dwordx2 v[146:147], v[142:143], off
	global_store_dwordx2 v[146:147], v[144:145], off offset:512
	v_cvt_pk_bf16_f32 v140, v4, v5
	v_cvt_pk_bf16_f32 v141, v6, v7
	v_lshl_add_u64 v[144:145], s[4:5], 0, v[176:177]
	v_cvt_pk_bf16_f32 v142, v0, v1
	v_cvt_pk_bf16_f32 v143, v2, v3
	global_store_dwordx2 v[144:145], v[140:141], off
	global_store_dwordx2 v[144:145], v[142:143], off offset:512
	s_cbranch_execnz .LBB0_337
; DI float shx(float v, int lane, int mask) { return __int_as_float(__builtin_amdgcn_ds_bpermute((lane ^ mask) << 2, __float_as_int(v))); }
;   DI void epi(const Acc& acc, const Unit& u, int wr, int wc, int fr, int fq, LAS unsigned char* lds) const {
;     ...
;       const bool isq = u.pn < 4; const float sc = isq ? 0.125f : 1.0f;
;       bf16_t* base = isq ? q + u.pn * 256 : k; const int ld = isq ? 1024 : 256;
;       const bool rot = (wc & 1) == 0;
; #pragma unroll
;       for (int ai = 0; ai < 2; ++ai)
; #pragma unroll
;         for (int m = 0; m < 4; ++m) {
;           const int row = u.pm * 256 + ai * 128 + wr * 64 + m * 16 + fr; const int pos = tok_pos(row);
; #pragma unroll
;           for (int bj = 0; bj < 2; ++bj) {
;             f32x4 v0 = acc[ai][bj][m][0], v1 = acc[ai][bj][m][1];
;             if (rot) {
;               f32x4 o0, o1;
; #pragma unroll
;               for (int j = 0; j < 4; ++j) { o0[j] = shx(v0[j], fq * 16 + fr, 16); o1[j] = shx(v1[j], fq * 16 + fr, 16); }
;               if (fq < 2) {
;                 const f32x4 c0 = ldf4(cosA, (unsigned)pos * 32u), c1 = ldf4(cosA, (unsigned)pos * 32u + 16u);
;                 f32x4 s0 = ldf4(sinA, (unsigned)pos * 32u), s1 = ldf4(sinA, (unsigned)pos * 32u + 16u);
;                 if (fq == 0) { s0 = -s0; s1 = -s1; }
;                 v0 = v0 * c0 + o0 * s0; v1 = v1 * c1 + o1 * s1;
;               }
;             }
.LBB0_271:
	s_add_u32 s4, s0, 0x3100000
	s_addc_u32 s5, s1, 0
	s_add_u32 s30, s0, 0x3120000
	s_addc_u32 s31, s1, 0
	s_lshl_b32 s52, s2, 8
	s_add_i32 s2, s52, s41
	v_or_b32_e32 v140, s2, v156
	v_cmp_gt_i32_e32 vcc, s56, v140
	v_mov_b32_e32 v140, 0xfcf
	v_mov_b32_e32 v141, 0x7cf
	v_cndmask_b32_e32 v140, v140, v141, vcc
	v_bitop3_b32 v140, v140, s2, v156 bitop3:0xe0
	v_lshlrev_b32_e32 v176, 5, v140
	v_or_b32_e32 v140, 16, v176
	v_mov_b32_e32 v141, v177
	v_cndmask_b32_e64 v148, 0, 1, s[16:17]
	v_lshl_add_u64 v[142:143], s[4:5], 0, v[176:177]
	v_lshl_add_u64 v[144:145], s[4:5], 0, v[140:141]
	v_lshl_add_u64 v[146:147], s[30:31], 0, v[176:177]
	v_cmp_ne_u32_e64 s[10:11], 1, v148
	s_andn2_b64 vcc, exec, s[16:17]
	v_lshl_add_u64 v[148:149], s[30:31], 0, v[140:141]
	s_cbranch_vccnz .LBB0_275
	ds_bpermute_b32 v154, v164, v124
	ds_bpermute_b32 v150, v164, v120
	ds_bpermute_b32 v155, v164, v125
	ds_bpermute_b32 v151, v164, v121
	ds_bpermute_b32 v152, v164, v126
	ds_bpermute_b32 v140, v164, v122
	ds_bpermute_b32 v153, v164, v127
	ds_bpermute_b32 v141, v164, v123
	s_and_saveexec_b64 s[34:35], s[6:7]
	s_cbranch_execz .LBB0_274
	global_load_dwordx4 v[168:171], v[146:147], off
	global_load_dwordx4 v[172:175], v[148:149], off
	global_load_dwordx4 v[178:181], v[142:143], off
	global_load_dwordx4 v[182:185], v[144:145], off
	s_waitcnt vmcnt(0) lgkmcnt(0)
	v_xor_b32_e32 v176, 0x80000000, v168
	v_xor_b32_e32 v186, 0x80000000, v169
	v_xor_b32_e32 v187, 0x80000000, v170
	v_xor_b32_e32 v188, 0x80000000, v171
	v_xor_b32_e32 v189, 0x80000000, v172
	v_xor_b32_e32 v190, 0x80000000, v173
	v_xor_b32_e32 v191, 0x80000000, v174
	v_xor_b32_e32 v192, 0x80000000, v175
	v_cndmask_b32_e64 v175, v175, v192, s[8:9]
	v_cndmask_b32_e64 v174, v174, v191, s[8:9]
	v_cndmask_b32_e64 v173, v173, v190, s[8:9]
	v_cndmask_b32_e64 v172, v172, v189, s[8:9]
	v_cndmask_b32_e64 v171, v171, v188, s[8:9]
	v_cndmask_b32_e64 v170, v170, v187, s[8:9]
	v_cndmask_b32_e64 v169, v169, v186, s[8:9]
	v_cndmask_b32_e64 v168, v168, v176, s[8:9]
	v_pk_mul_f32 v[154:155], v[168:169], v[154:155]
	v_pk_mul_f32 v[152:153], v[170:171], v[152:153]
	v_pk_mul_f32 v[150:151], v[172:173], v[150:151]
	v_pk_mul_f32 v[140:141], v[174:175], v[140:141]
	v_pk_fma_f32 v[126:127], v[126:127], v[180:181], v[152:153]
	v_pk_fma_f32 v[124:125], v[124:125], v[178:179], v[154:155]
	v_pk_fma_f32 v[122:123], v[122:123], v[184:185], v[140:141]
	v_pk_fma_f32 v[120:121], v[120:121], v[182:183], v[150:151]

; DI float shx(float v, int lane, int mask) { return __int_as_float(__builtin_amdgcn_ds_bpermute((lane ^ mask) << 2, __float_as_int(v))); }
; DI u32x4 pk8(const f32x4& v0, const f32x4& v1) { u32x4 w; w.x = cvt_pk_bf16(v0[0], v0[1]); w.y = cvt_pk_bf16(v0[2], v0[3]); w.z = cvt_pk_bf16(v1[0], v1[1]); w.w = cvt_pk_bf16(v1[2], v1[3]); return w; }
;   DI void epi(const Acc& acc, const Unit& u, int wr, int wc, int fr, int fq, LAS unsigned char* lds) const {
;     ...
;       const bool isq = u.pn < 4; const float sc = isq ? 0.125f : 1.0f;
;       bf16_t* base = isq ? q + u.pn * 256 : k; const int ld = isq ? 1024 : 256;
;       const bool rot = (wc & 1) == 0;
; #pragma unroll
;       for (int ai = 0; ai < 2; ++ai)
; #pragma unroll
;         for (int m = 0; m < 4; ++m) {
;           const int row = u.pm * 256 + ai * 128 + wr * 64 + m * 16 + fr; const int pos = tok_pos(row);
; #pragma unroll
;           for (int bj = 0; bj < 2; ++bj) {
;             f32x4 v0 = acc[ai][bj][m][0], v1 = acc[ai][bj][m][1];
;             if (rot) {
;               f32x4 o0, o1;
; #pragma unroll
;               for (int j = 0; j < 4; ++j) { o0[j] = shx(v0[j], fq * 16 + fr, 16); o1[j] = shx(v1[j], fq * 16 + fr, 16); }
;               if (fq < 2) {
;                 const f32x4 c0 = ldf4(cosA, (unsigned)pos * 32u), c1 = ldf4(cosA, (unsigned)pos * 32u + 16u);
;                 f32x4 s0 = ldf4(sinA, (unsigned)pos * 32u), s1 = ldf4(sinA, (unsigned)pos * 32u + 16u);
;                 if (fq == 0) { s0 = -s0; s1 = -s1; }
;                 v0 = v0 * c0 + o0 * s0; v1 = v1 * c1 + o1 * s1;
;               }
;             }
;             v0 *= sc; v1 *= sc;
;             {
;               const int hl = bj * 2 + (wc >> 1), head = isq ? u.pn * 4 + hl : hl, d0 = (wc & 1) * 32 + 8 * fq;
;               st16(isq ? q : k, (unsigned)((((head * 1024 + (row >> 5)) * 4 + (d0 >> 4)) * 64 + ((d0 >> 3) & 1) * 32 + (row & 31)) * 16), pk8(v0, v1)); }
.LBB0_275:
	s_lshl_b32 s23, s51, 2
	s_cmp_lt_i32 s51, 4
	s_cselect_b64 vcc, -1, 0
	s_and_b64 s[34:35], vcc, exec
	s_mov_b32 s34, 0xbe00000
	s_cselect_b32 s34, 0x7e00000, s34
	s_cselect_b32 s23, s23, 0
	s_add_u32 s0, s0, s34
	s_addc_u32 s1, s1, 0
	s_lshr_b32 s34, s2, 3
	s_and_b32 s34, s34, 0x3fffff8
	s_waitcnt lgkmcnt(0)
	v_mov_b32_e32 v140, 0x3e000000
	v_or_b32_e32 v141, s34, v162
	s_or_b32 s23, s23, s46
	v_cndmask_b32_e32 v140, 1.0, v140, vcc
	s_lshl_b32 s23, s23, 18
	v_lshlrev_b32_e32 v150, 6, v141
	v_pk_mul_f32 v[152:153], v[140:141], v[122:123] op_sel_hi:[0,1]
	v_pk_mul_f32 v[122:123], v[140:141], v[120:121] op_sel_hi:[0,1]
	v_add_u32_e32 v120, s23, v150
	v_or_b32_e32 v120, v120, v165
	v_pk_mul_f32 v[124:125], v[140:141], v[124:125] op_sel_hi:[0,1]
	v_lshlrev_b32_e32 v176, 4, v120
	v_cvt_pk_bf16_f32 v120, v124, v125
	v_lshl_add_u64 v[124:125], s[0:1], 0, v[176:177]
	v_pk_mul_f32 v[126:127], v[140:141], v[126:127] op_sel_hi:[0,1]
	v_cvt_pk_bf16_f32 v121, v126, v127
	v_cvt_pk_bf16_f32 v122, v122, v123
	v_cvt_pk_bf16_f32 v123, v152, v153
	global_store_dwordx4 v[124:125], v[120:123], off
	s_and_b64 vcc, exec, s[10:11]
	s_cbranch_vccnz .LBB0_279
	ds_bpermute_b32 v126, v164, v116
	ds_bpermute_b32 v122, v164, v112
	ds_bpermute_b32 v127, v164, v117
	ds_bpermute_b32 v123, v164, v113
	ds_bpermute_b32 v124, v164, v118
	ds_bpermute_b32 v120, v164, v114
	ds_bpermute_b32 v125, v164, v119
	ds_bpermute_b32 v121, v164, v115
	s_and_saveexec_b64 s[34:35], s[6:7]
	s_cbranch_execz .LBB0_278
	global_load_dwordx4 v[152:155], v[146:147], off
	s_nop 0
	global_load_dwordx4 v[146:149], v[148:149], off
	s_nop 0
	global_load_dwordx4 v[168:171], v[142:143], off
	s_nop 0
	global_load_dwordx4 v[142:145], v[144:145], off
	s_waitcnt vmcnt(0) lgkmcnt(0)
	v_xor_b32_e32 v141, 0x80000000, v152
	v_xor_b32_e32 v151, 0x80000000, v153
	v_xor_b32_e32 v172, 0x80000000, v154
	v_xor_b32_e32 v173, 0x80000000, v155
	v_xor_b32_e32 v174, 0x80000000, v146
	v_xor_b32_e32 v175, 0x80000000, v147
	v_xor_b32_e32 v176, 0x80000000, v148
	v_xor_b32_e32 v178, 0x80000000, v149
	v_cndmask_b32_e64 v149, v149, v178, s[8:9]
	v_cndmask_b32_e64 v148, v148, v176, s[8:9]
	v_cndmask_b32_e64 v147, v147, v175, s[8:9]
	v_cndmask_b32_e64 v146, v146, v174, s[8:9]
	v_cndmask_b32_e64 v155, v155, v173, s[8:9]
	v_cndmask_b32_e64 v154, v154, v172, s[8:9]
	v_cndmask_b32_e64 v153, v153, v151, s[8:9]
	v_cndmask_b32_e64 v152, v152, v141, s[8:9]
	v_pk_mul_f32 v[126:127], v[152:153], v[126:127]
	v_pk_mul_f32 v[124:125], v[154:155], v[124:125]
	v_pk_mul_f32 v[122:123], v[146:147], v[122:123]
	v_pk_mul_f32 v[120:121], v[148:149], v[120:121]
	v_pk_fma_f32 v[118:119], v[118:119], v[170:171], v[124:125]
	v_pk_fma_f32 v[116:117], v[116:117], v[168:169], v[126:127]
	v_pk_fma_f32 v[114:115], v[114:115], v[144:145], v[120:121]
	v_pk_fma_f32 v[112:113], v[112:113], v[142:143], v[122:123]

; DI float shx(float v, int lane, int mask) { return __int_as_float(__builtin_amdgcn_ds_bpermute((lane ^ mask) << 2, __float_as_int(v))); }
; DI u32x4 pk8(const f32x4& v0, const f32x4& v1) { u32x4 w; w.x = cvt_pk_bf16(v0[0], v0[1]); w.y = cvt_pk_bf16(v0[2], v0[3]); w.z = cvt_pk_bf16(v1[0], v1[1]); w.w = cvt_pk_bf16(v1[2], v1[3]); return w; }
;   DI void epi(const Acc& acc, const Unit& u, int wr, int wc, int fr, int fq, LAS unsigned char* lds) const {
;     ...
;           const int row = u.pm * 256 + ai * 128 + wr * 64 + m * 16 + fr; const int pos = tok_pos(row);
; #pragma unroll
;           for (int bj = 0; bj < 2; ++bj) {
;             f32x4 v0 = acc[ai][bj][m][0], v1 = acc[ai][bj][m][1];
;             if (rot) {
;               f32x4 o0, o1;
; #pragma unroll
;               for (int j = 0; j < 4; ++j) { o0[j] = shx(v0[j], fq * 16 + fr, 16); o1[j] = shx(v1[j], fq * 16 + fr, 16); }
;               if (fq < 2) {
;                 const f32x4 c0 = ldf4(cosA, (unsigned)pos * 32u), c1 = ldf4(cosA, (unsigned)pos * 32u + 16u);
;                 f32x4 s0 = ldf4(sinA, (unsigned)pos * 32u), s1 = ldf4(sinA, (unsigned)pos * 32u + 16u);
;                 if (fq == 0) { s0 = -s0; s1 = -s1; }
;                 v0 = v0 * c0 + o0 * s0; v1 = v1 * c1 + o1 * s1;
;               }
;             }
;             v0 *= sc; v1 *= sc;
;             {
;               const int hl = bj * 2 + (wc >> 1), head = isq ? u.pn * 4 + hl : hl, d0 = (wc & 1) * 32 + 8 * fq;
;               st16(isq ? q : k, (unsigned)((((head * 1024 + (row >> 5)) * 4 + (d0 >> 4)) * 64 + ((d0 >> 3) & 1) * 32 + (row & 31)) * 16), pk8(v0, v1)); }
.LBB0_279:
	v_mov_b32_e32 v141, v140
	s_waitcnt lgkmcnt(0)
	v_mov_b32_e32 v120, v140
	v_mov_b32_e32 v121, v140
	s_or_b32 s51, s23, 0x80000
	v_pk_mul_f32 v[122:123], v[120:121], v[114:115]
	v_pk_mul_f32 v[114:115], v[140:141], v[112:113]
	v_add_u32_e32 v112, s51, v150
	v_or_b32_e32 v112, v112, v165
	v_pk_mul_f32 v[116:117], v[140:141], v[116:117]
	v_lshlrev_b32_e32 v176, 4, v112
	v_pk_mul_f32 v[118:119], v[120:121], v[118:119]
	v_cvt_pk_bf16_f32 v112, v116, v117
	v_lshl_add_u64 v[116:117], s[0:1], 0, v[176:177]
	v_cvt_pk_bf16_f32 v113, v118, v119
	v_cvt_pk_bf16_f32 v114, v114, v115
	v_cvt_pk_bf16_f32 v115, v122, v123
	global_store_dwordx4 v[116:117], v[112:115], off
	s_add_i32 s53, s52, s47
	v_or_b32_e32 v144, s53, v156
	v_cmp_gt_i32_e32 vcc, s56, v144
	v_mov_b32_e32 v112, 0xfdf
	v_mov_b32_e32 v113, 0x7df
	v_cndmask_b32_e32 v112, v112, v113, vcc
	v_bitop3_b32 v112, v112, s53, v156 bitop3:0xe0
	v_lshlrev_b32_e32 v176, 5, v112
	v_or_b32_e32 v118, 16, v176
	v_mov_b32_e32 v119, v177
	v_lshl_add_u64 v[112:113], s[4:5], 0, v[176:177]
	v_lshl_add_u64 v[114:115], s[4:5], 0, v[118:119]
	v_lshl_add_u64 v[116:117], s[30:31], 0, v[176:177]
	s_and_b64 vcc, exec, s[10:11]
	v_lshl_add_u64 v[118:119], s[30:31], 0, v[118:119]
	s_cbranch_vccnz .LBB0_283
	ds_bpermute_b32 v142, v164, v108
	ds_bpermute_b32 v124, v164, v104
	ds_bpermute_b32 v143, v164, v109
	ds_bpermute_b32 v125, v164, v105
	ds_bpermute_b32 v126, v164, v110
	ds_bpermute_b32 v122, v164, v106
	ds_bpermute_b32 v127, v164, v111
	ds_bpermute_b32 v123, v164, v107
	s_and_saveexec_b64 s[34:35], s[6:7]
	s_cbranch_execz .LBB0_282
	global_load_dwordx4 v[146:149], v[116:117], off
	global_load_dwordx4 v[150:153], v[118:119], off
	global_load_dwordx4 v[168:171], v[112:113], off
	global_load_dwordx4 v[172:175], v[114:115], off
	s_waitcnt vmcnt(0) lgkmcnt(0)
	v_xor_b32_e32 v145, 0x80000000, v146
	v_xor_b32_e32 v154, 0x80000000, v147
	v_xor_b32_e32 v155, 0x80000000, v148
	v_xor_b32_e32 v176, 0x80000000, v149
	v_xor_b32_e32 v178, 0x80000000, v150
	v_xor_b32_e32 v179, 0x80000000, v151
	v_xor_b32_e32 v180, 0x80000000, v152
	v_xor_b32_e32 v181, 0x80000000, v153
	v_cndmask_b32_e64 v153, v153, v181, s[8:9]
	v_cndmask_b32_e64 v152, v152, v180, s[8:9]
	v_cndmask_b32_e64 v151, v151, v179, s[8:9]
	v_cndmask_b32_e64 v150, v150, v178, s[8:9]
	v_cndmask_b32_e64 v149, v149, v176, s[8:9]
	v_cndmask_b32_e64 v148, v148, v155, s[8:9]
	v_cndmask_b32_e64 v147, v147, v154, s[8:9]
	v_cndmask_b32_e64 v146, v146, v145, s[8:9]
	v_pk_mul_f32 v[142:143], v[146:147], v[142:143]
	v_pk_mul_f32 v[126:127], v[148:149], v[126:127]
	v_pk_mul_f32 v[124:125], v[150:151], v[124:125]
	v_pk_mul_f32 v[122:123], v[152:153], v[122:123]
	v_pk_fma_f32 v[110:111], v[110:111], v[170:171], v[126:127]
	v_pk_fma_f32 v[108:109], v[108:109], v[168:169], v[142:143]
	v_pk_fma_f32 v[106:107], v[106:107], v[174:175], v[122:123]
	v_pk_fma_f32 v[104:105], v[104:105], v[172:173], v[124:125]

; DI float shx(float v, int lane, int mask) { return __int_as_float(__builtin_amdgcn_ds_bpermute((lane ^ mask) << 2, __float_as_int(v))); }
; DI u32x4 pk8(const f32x4& v0, const f32x4& v1) { u32x4 w; w.x = cvt_pk_bf16(v0[0], v0[1]); w.y = cvt_pk_bf16(v0[2], v0[3]); w.z = cvt_pk_bf16(v1[0], v1[1]); w.w = cvt_pk_bf16(v1[2], v1[3]); return w; }
;   DI void epi(const Acc& acc, const Unit& u, int wr, int wc, int fr, int fq, LAS unsigned char* lds) const {
;     ...
;           const int row = u.pm * 256 + ai * 128 + wr * 64 + m * 16 + fr; const int pos = tok_pos(row);
; #pragma unroll
;           for (int bj = 0; bj < 2; ++bj) {
;             f32x4 v0 = acc[ai][bj][m][0], v1 = acc[ai][bj][m][1];
;             if (rot) {
;               f32x4 o0, o1;
; #pragma unroll
;               for (int j = 0; j < 4; ++j) { o0[j] = shx(v0[j], fq * 16 + fr, 16); o1[j] = shx(v1[j], fq * 16 + fr, 16); }
;               if (fq < 2) {
;                 const f32x4 c0 = ldf4(cosA, (unsigned)pos * 32u), c1 = ldf4(cosA, (unsigned)pos * 32u + 16u);
;                 f32x4 s0 = ldf4(sinA, (unsigned)pos * 32u), s1 = ldf4(sinA, (unsigned)pos * 32u + 16u);
;                 if (fq == 0) { s0 = -s0; s1 = -s1; }
;                 v0 = v0 * c0 + o0 * s0; v1 = v1 * c1 + o1 * s1;
;               }
;             }
;             v0 *= sc; v1 *= sc;
;             {
;               const int hl = bj * 2 + (wc >> 1), head = isq ? u.pn * 4 + hl : hl, d0 = (wc & 1) * 32 + 8 * fq;
;               st16(isq ? q : k, (unsigned)((((head * 1024 + (row >> 5)) * 4 + (d0 >> 4)) * 64 + ((d0 >> 3) & 1) * 32 + (row & 31)) * 16), pk8(v0, v1)); }
.LBB0_283:
	s_lshr_b32 s34, s53, 3
	s_and_b32 s34, s34, 0x3fffff8
	s_waitcnt lgkmcnt(0)
	v_or_b32_e32 v123, s34, v162
	v_pk_mul_f32 v[110:111], v[120:121], v[110:111]
	v_pk_mul_f32 v[124:125], v[120:121], v[106:107]
	v_lshlrev_b32_e32 v120, 6, v123
	v_and_or_b32 v122, v144, 31, v163
	v_pk_mul_f32 v[106:107], v[140:141], v[104:105]
	v_add_u32_e32 v104, s23, v120
	v_or_b32_e32 v104, v104, v122
	v_pk_mul_f32 v[108:109], v[140:141], v[108:109]
	v_lshlrev_b32_e32 v176, 4, v104
	v_cvt_pk_bf16_f32 v104, v108, v109
	v_lshl_add_u64 v[108:109], s[0:1], 0, v[176:177]
	v_cvt_pk_bf16_f32 v105, v110, v111
	v_cvt_pk_bf16_f32 v106, v106, v107
	v_cvt_pk_bf16_f32 v107, v124, v125
	global_store_dwordx4 v[108:109], v[104:107], off
	s_and_b64 vcc, exec, s[10:11]
	s_cbranch_vccnz .LBB0_287
	ds_bpermute_b32 v110, v164, v100
	ds_bpermute_b32 v106, v164, v96
	ds_bpermute_b32 v111, v164, v101
	ds_bpermute_b32 v107, v164, v97
	ds_bpermute_b32 v108, v164, v102
	ds_bpermute_b32 v104, v164, v98
	ds_bpermute_b32 v109, v164, v103
	ds_bpermute_b32 v105, v164, v99
	s_and_saveexec_b64 s[34:35], s[6:7]
	s_cbranch_execz .LBB0_286
	global_load_dwordx4 v[124:127], v[116:117], off
	s_nop 0
	global_load_dwordx4 v[116:119], v[118:119], off
	s_nop 0
	global_load_dwordx4 v[142:145], v[112:113], off
	s_nop 0
	global_load_dwordx4 v[112:115], v[114:115], off
	s_waitcnt vmcnt(0) lgkmcnt(0)
	v_xor_b32_e32 v121, 0x80000000, v124
	v_xor_b32_e32 v123, 0x80000000, v125
	v_xor_b32_e32 v146, 0x80000000, v126
	v_xor_b32_e32 v147, 0x80000000, v127
	v_xor_b32_e32 v148, 0x80000000, v116
	v_xor_b32_e32 v149, 0x80000000, v117
	v_xor_b32_e32 v150, 0x80000000, v118
	v_xor_b32_e32 v151, 0x80000000, v119
	v_cndmask_b32_e64 v119, v119, v151, s[8:9]
	v_cndmask_b32_e64 v118, v118, v150, s[8:9]
	v_cndmask_b32_e64 v117, v117, v149, s[8:9]
	v_cndmask_b32_e64 v116, v116, v148, s[8:9]
	v_cndmask_b32_e64 v127, v127, v147, s[8:9]
	v_cndmask_b32_e64 v126, v126, v146, s[8:9]
	v_cndmask_b32_e64 v125, v125, v123, s[8:9]
	v_cndmask_b32_e64 v124, v124, v121, s[8:9]
	v_pk_mul_f32 v[110:111], v[124:125], v[110:111]
	v_pk_mul_f32 v[108:109], v[126:127], v[108:109]
	v_pk_mul_f32 v[106:107], v[116:117], v[106:107]
	v_pk_mul_f32 v[104:105], v[118:119], v[104:105]
	v_pk_fma_f32 v[102:103], v[102:103], v[144:145], v[108:109]
	v_pk_fma_f32 v[100:101], v[100:101], v[142:143], v[110:111]
	v_pk_fma_f32 v[98:99], v[98:99], v[114:115], v[104:105]
	v_pk_fma_f32 v[96:97], v[96:97], v[112:113], v[106:107]

; DI float shx(float v, int lane, int mask) { return __int_as_float(__builtin_amdgcn_ds_bpermute((lane ^ mask) << 2, __float_as_int(v))); }
; DI u32x4 pk8(const f32x4& v0, const f32x4& v1) { u32x4 w; w.x = cvt_pk_bf16(v0[0], v0[1]); w.y = cvt_pk_bf16(v0[2], v0[3]); w.z = cvt_pk_bf16(v1[0], v1[1]); w.w = cvt_pk_bf16(v1[2], v1[3]); return w; }
;   DI void epi(const Acc& acc, const Unit& u, int wr, int wc, int fr, int fq, LAS unsigned char* lds) const {
;     ...
;           const int row = u.pm * 256 + ai * 128 + wr * 64 + m * 16 + fr; const int pos = tok_pos(row);
; #pragma unroll
;           for (int bj = 0; bj < 2; ++bj) {
;             f32x4 v0 = acc[ai][bj][m][0], v1 = acc[ai][bj][m][1];
;             if (rot) {
;               f32x4 o0, o1;
; #pragma unroll
;               for (int j = 0; j < 4; ++j) { o0[j] = shx(v0[j], fq * 16 + fr, 16); o1[j] = shx(v1[j], fq * 16 + fr, 16); }
;               if (fq < 2) {
;                 const f32x4 c0 = ldf4(cosA, (unsigned)pos * 32u), c1 = ldf4(cosA, (unsigned)pos * 32u + 16u);
;                 f32x4 s0 = ldf4(sinA, (unsigned)pos * 32u), s1 = ldf4(sinA, (unsigned)pos * 32u + 16u);
;                 if (fq == 0) { s0 = -s0; s1 = -s1; }
;                 v0 = v0 * c0 + o0 * s0; v1 = v1 * c1 + o1 * s1;
;               }
;             }
;             v0 *= sc; v1 *= sc;
;             {
;               const int hl = bj * 2 + (wc >> 1), head = isq ? u.pn * 4 + hl : hl, d0 = (wc & 1) * 32 + 8 * fq;
;               st16(isq ? q : k, (unsigned)((((head * 1024 + (row >> 5)) * 4 + (d0 >> 4)) * 64 + ((d0 >> 3) & 1) * 32 + (row & 31)) * 16), pk8(v0, v1)); }
.LBB0_287:
	s_waitcnt lgkmcnt(0)
	v_mov_b32_e32 v104, v140
	v_mov_b32_e32 v105, v140
	v_pk_mul_f32 v[106:107], v[104:105], v[98:99]
	v_pk_mul_f32 v[98:99], v[140:141], v[96:97]
	v_add_u32_e32 v96, s51, v120
	v_or_b32_e32 v96, v96, v122
	v_pk_mul_f32 v[100:101], v[140:141], v[100:101]
	v_lshlrev_b32_e32 v176, 4, v96
	v_pk_mul_f32 v[102:103], v[104:105], v[102:103]
	v_cvt_pk_bf16_f32 v96, v100, v101
	v_lshl_add_u64 v[100:101], s[0:1], 0, v[176:177]
	v_cvt_pk_bf16_f32 v97, v102, v103
	v_cvt_pk_bf16_f32 v98, v98, v99
	v_cvt_pk_bf16_f32 v99, v106, v107
	global_store_dwordx4 v[100:101], v[96:99], off
	s_add_i32 s53, s52, s48
	s_nop 0
	v_or_b32_e32 v96, s53, v156
	v_cmp_gt_i32_e32 vcc, s56, v96
	v_mov_b32_e32 v96, 0xfef
	v_mov_b32_e32 v97, 0x7ef
	v_cndmask_b32_e32 v96, v96, v97, vcc
	v_bitop3_b32 v96, v96, s53, v156 bitop3:0xe0
	v_lshlrev_b32_e32 v176, 5, v96
	v_or_b32_e32 v102, 16, v176
	v_mov_b32_e32 v103, v177
	v_lshl_add_u64 v[96:97], s[4:5], 0, v[176:177]
	v_lshl_add_u64 v[98:99], s[4:5], 0, v[102:103]
	v_lshl_add_u64 v[100:101], s[30:31], 0, v[176:177]
	s_and_b64 vcc, exec, s[10:11]
	v_lshl_add_u64 v[102:103], s[30:31], 0, v[102:103]
	s_cbranch_vccnz .LBB0_291
	ds_bpermute_b32 v112, v164, v92
	ds_bpermute_b32 v108, v164, v88
	ds_bpermute_b32 v113, v164, v93
	ds_bpermute_b32 v109, v164, v89
	ds_bpermute_b32 v110, v164, v94
	ds_bpermute_b32 v106, v164, v90
	ds_bpermute_b32 v111, v164, v95
	ds_bpermute_b32 v107, v164, v91
	s_and_saveexec_b64 s[34:35], s[6:7]
	s_cbranch_execz .LBB0_290
	global_load_dwordx4 v[114:117], v[100:101], off
	global_load_dwordx4 v[118:121], v[102:103], off
	global_load_dwordx4 v[122:125], v[96:97], off
	global_load_dwordx4 v[142:145], v[98:99], off
	s_waitcnt vmcnt(0) lgkmcnt(0)
	v_xor_b32_e32 v126, 0x80000000, v114
	v_xor_b32_e32 v127, 0x80000000, v115
	v_xor_b32_e32 v146, 0x80000000, v116
	v_xor_b32_e32 v147, 0x80000000, v117
	v_xor_b32_e32 v148, 0x80000000, v118
	v_xor_b32_e32 v149, 0x80000000, v119
	v_xor_b32_e32 v150, 0x80000000, v120
	v_xor_b32_e32 v151, 0x80000000, v121
	v_cndmask_b32_e64 v121, v121, v151, s[8:9]
	v_cndmask_b32_e64 v120, v120, v150, s[8:9]
	v_cndmask_b32_e64 v119, v119, v149, s[8:9]
	v_cndmask_b32_e64 v118, v118, v148, s[8:9]
	v_cndmask_b32_e64 v117, v117, v147, s[8:9]
	v_cndmask_b32_e64 v116, v116, v146, s[8:9]
	v_cndmask_b32_e64 v115, v115, v127, s[8:9]
	v_cndmask_b32_e64 v114, v114, v126, s[8:9]
	v_pk_mul_f32 v[112:113], v[114:115], v[112:113]
	v_pk_mul_f32 v[110:111], v[116:117], v[110:111]
	v_pk_mul_f32 v[108:109], v[118:119], v[108:109]
	v_pk_mul_f32 v[106:107], v[120:121], v[106:107]
	v_pk_fma_f32 v[94:95], v[94:95], v[124:125], v[110:111]
	v_pk_fma_f32 v[92:93], v[92:93], v[122:123], v[112:113]
	v_pk_fma_f32 v[90:91], v[90:91], v[144:145], v[106:107]
	v_pk_fma_f32 v[88:89], v[88:89], v[142:143], v[108:109]

; DI float shx(float v, int lane, int mask) { return __int_as_float(__builtin_amdgcn_ds_bpermute((lane ^ mask) << 2, __float_as_int(v))); }
; DI u32x4 pk8(const f32x4& v0, const f32x4& v1) { u32x4 w; w.x = cvt_pk_bf16(v0[0], v0[1]); w.y = cvt_pk_bf16(v0[2], v0[3]); w.z = cvt_pk_bf16(v1[0], v1[1]); w.w = cvt_pk_bf16(v1[2], v1[3]); return w; }
;   DI void epi(const Acc& acc, const Unit& u, int wr, int wc, int fr, int fq, LAS unsigned char* lds) const {
;     ...
;           const int row = u.pm * 256 + ai * 128 + wr * 64 + m * 16 + fr; const int pos = tok_pos(row);
; #pragma unroll
;           for (int bj = 0; bj < 2; ++bj) {
;             f32x4 v0 = acc[ai][bj][m][0], v1 = acc[ai][bj][m][1];
;             if (rot) {
;               f32x4 o0, o1;
; #pragma unroll
;               for (int j = 0; j < 4; ++j) { o0[j] = shx(v0[j], fq * 16 + fr, 16); o1[j] = shx(v1[j], fq * 16 + fr, 16); }
;               if (fq < 2) {
;                 const f32x4 c0 = ldf4(cosA, (unsigned)pos * 32u), c1 = ldf4(cosA, (unsigned)pos * 32u + 16u);
;                 f32x4 s0 = ldf4(sinA, (unsigned)pos * 32u), s1 = ldf4(sinA, (unsigned)pos * 32u + 16u);
;                 if (fq == 0) { s0 = -s0; s1 = -s1; }
;                 v0 = v0 * c0 + o0 * s0; v1 = v1 * c1 + o1 * s1;
;               }
;             }
;             v0 *= sc; v1 *= sc;
;             {
;               const int hl = bj * 2 + (wc >> 1), head = isq ? u.pn * 4 + hl : hl, d0 = (wc & 1) * 32 + 8 * fq;
;               st16(isq ? q : k, (unsigned)((((head * 1024 + (row >> 5)) * 4 + (d0 >> 4)) * 64 + ((d0 >> 3) & 1) * 32 + (row & 31)) * 16), pk8(v0, v1)); }
.LBB0_291:
	s_lshr_b32 s34, s53, 3
	s_and_b32 s34, s34, 0x3fffffc
	s_waitcnt lgkmcnt(0)
	v_or_b32_e32 v108, s34, v162
	v_pk_mul_f32 v[94:95], v[104:105], v[94:95]
	v_pk_mul_f32 v[106:107], v[104:105], v[90:91]
	v_lshlrev_b32_e32 v104, 6, v108
	v_pk_mul_f32 v[90:91], v[140:141], v[88:89]
	v_add_u32_e32 v88, s23, v104
	v_or_b32_e32 v88, v88, v165
	v_pk_mul_f32 v[92:93], v[140:141], v[92:93]
	v_lshlrev_b32_e32 v176, 4, v88
	v_cvt_pk_bf16_f32 v88, v92, v93
	v_lshl_add_u64 v[92:93], s[0:1], 0, v[176:177]
	v_cvt_pk_bf16_f32 v89, v94, v95
	v_cvt_pk_bf16_f32 v90, v90, v91
	v_cvt_pk_bf16_f32 v91, v106, v107
	global_store_dwordx4 v[92:93], v[88:91], off
	s_and_b64 vcc, exec, s[10:11]
	s_cbranch_vccnz .LBB0_295
	ds_bpermute_b32 v94, v164, v84
	ds_bpermute_b32 v90, v164, v80
	ds_bpermute_b32 v95, v164, v85
	ds_bpermute_b32 v91, v164, v81
	ds_bpermute_b32 v92, v164, v86
	ds_bpermute_b32 v88, v164, v82
	ds_bpermute_b32 v93, v164, v87
	ds_bpermute_b32 v89, v164, v83
	s_and_saveexec_b64 s[34:35], s[6:7]
	s_cbranch_execz .LBB0_294
	global_load_dwordx4 v[106:109], v[100:101], off
	s_nop 0
	global_load_dwordx4 v[100:103], v[102:103], off
	s_nop 0
	global_load_dwordx4 v[110:113], v[96:97], off
	s_nop 0
	global_load_dwordx4 v[96:99], v[98:99], off
	s_waitcnt vmcnt(0) lgkmcnt(0)
	v_xor_b32_e32 v105, 0x80000000, v106
	v_xor_b32_e32 v114, 0x80000000, v107
	v_xor_b32_e32 v115, 0x80000000, v108
	v_xor_b32_e32 v116, 0x80000000, v109
	v_xor_b32_e32 v117, 0x80000000, v100
	v_xor_b32_e32 v118, 0x80000000, v101
	v_xor_b32_e32 v119, 0x80000000, v102
	v_xor_b32_e32 v120, 0x80000000, v103
	v_cndmask_b32_e64 v103, v103, v120, s[8:9]
	v_cndmask_b32_e64 v102, v102, v119, s[8:9]
	v_cndmask_b32_e64 v101, v101, v118, s[8:9]
	v_cndmask_b32_e64 v100, v100, v117, s[8:9]
	v_cndmask_b32_e64 v109, v109, v116, s[8:9]
	v_cndmask_b32_e64 v108, v108, v115, s[8:9]
	v_cndmask_b32_e64 v107, v107, v114, s[8:9]
	v_cndmask_b32_e64 v106, v106, v105, s[8:9]
	v_pk_mul_f32 v[94:95], v[106:107], v[94:95]
	v_pk_mul_f32 v[92:93], v[108:109], v[92:93]
	v_pk_mul_f32 v[90:91], v[100:101], v[90:91]
	v_pk_mul_f32 v[88:89], v[102:103], v[88:89]
	v_pk_fma_f32 v[86:87], v[86:87], v[112:113], v[92:93]
	v_pk_fma_f32 v[84:85], v[84:85], v[110:111], v[94:95]
	v_pk_fma_f32 v[82:83], v[82:83], v[98:99], v[88:89]
	v_pk_fma_f32 v[80:81], v[80:81], v[96:97], v[90:91]

; DI float shx(float v, int lane, int mask) { return __int_as_float(__builtin_amdgcn_ds_bpermute((lane ^ mask) << 2, __float_as_int(v))); }
; DI u32x4 pk8(const f32x4& v0, const f32x4& v1) { u32x4 w; w.x = cvt_pk_bf16(v0[0], v0[1]); w.y = cvt_pk_bf16(v0[2], v0[3]); w.z = cvt_pk_bf16(v1[0], v1[1]); w.w = cvt_pk_bf16(v1[2], v1[3]); return w; }
;   DI void epi(const Acc& acc, const Unit& u, int wr, int wc, int fr, int fq, LAS unsigned char* lds) const {
;     ...
;           const int row = u.pm * 256 + ai * 128 + wr * 64 + m * 16 + fr; const int pos = tok_pos(row);
; #pragma unroll
;           for (int bj = 0; bj < 2; ++bj) {
;             f32x4 v0 = acc[ai][bj][m][0], v1 = acc[ai][bj][m][1];
;             if (rot) {
;               f32x4 o0, o1;
; #pragma unroll
;               for (int j = 0; j < 4; ++j) { o0[j] = shx(v0[j], fq * 16 + fr, 16); o1[j] = shx(v1[j], fq * 16 + fr, 16); }
;               if (fq < 2) {
;                 const f32x4 c0 = ldf4(cosA, (unsigned)pos * 32u), c1 = ldf4(cosA, (unsigned)pos * 32u + 16u);
;                 f32x4 s0 = ldf4(sinA, (unsigned)pos * 32u), s1 = ldf4(sinA, (unsigned)pos * 32u + 16u);
;                 if (fq == 0) { s0 = -s0; s1 = -s1; }
;                 v0 = v0 * c0 + o0 * s0; v1 = v1 * c1 + o1 * s1;
;               }
;             }
;             v0 *= sc; v1 *= sc;
;             {
;               const int hl = bj * 2 + (wc >> 1), head = isq ? u.pn * 4 + hl : hl, d0 = (wc & 1) * 32 + 8 * fq;
;               st16(isq ? q : k, (unsigned)((((head * 1024 + (row >> 5)) * 4 + (d0 >> 4)) * 64 + ((d0 >> 3) & 1) * 32 + (row & 31)) * 16), pk8(v0, v1)); }
.LBB0_295:
	s_waitcnt lgkmcnt(0)
	v_mov_b32_e32 v88, v140
	v_mov_b32_e32 v89, v140
	v_pk_mul_f32 v[90:91], v[88:89], v[82:83]
	v_pk_mul_f32 v[82:83], v[140:141], v[80:81]
	v_add_u32_e32 v80, s51, v104
	v_or_b32_e32 v80, v80, v165
	v_pk_mul_f32 v[84:85], v[140:141], v[84:85]
	v_lshlrev_b32_e32 v176, 4, v80
	v_pk_mul_f32 v[86:87], v[88:89], v[86:87]
	v_cvt_pk_bf16_f32 v80, v84, v85
	v_lshl_add_u64 v[84:85], s[0:1], 0, v[176:177]
	v_cvt_pk_bf16_f32 v81, v86, v87
	v_cvt_pk_bf16_f32 v82, v82, v83
	v_cvt_pk_bf16_f32 v83, v90, v91
	global_store_dwordx4 v[84:85], v[80:83], off
	s_add_i32 s52, s52, s49
	v_or_b32_e32 v98, s52, v156
	v_cmp_gt_i32_e32 vcc, s56, v98
	v_mov_b32_e32 v80, 0xfff
	v_mov_b32_e32 v81, 0x7ff
	v_cndmask_b32_e32 v80, v80, v81, vcc
	v_bitop3_b32 v80, v80, s52, v156 bitop3:0xe0
	v_lshlrev_b32_e32 v176, 5, v80
	v_or_b32_e32 v86, 16, v176
	v_mov_b32_e32 v87, v177
	v_lshl_add_u64 v[80:81], s[4:5], 0, v[176:177]
	v_lshl_add_u64 v[82:83], s[4:5], 0, v[86:87]
	v_lshl_add_u64 v[84:85], s[30:31], 0, v[176:177]
	s_and_b64 vcc, exec, s[10:11]
	v_lshl_add_u64 v[86:87], s[30:31], 0, v[86:87]
	s_cbranch_vccnz .LBB0_299
	ds_bpermute_b32 v96, v164, v76
	ds_bpermute_b32 v92, v164, v72
	ds_bpermute_b32 v97, v164, v77
	ds_bpermute_b32 v93, v164, v73
	ds_bpermute_b32 v94, v164, v78
	ds_bpermute_b32 v90, v164, v74
	ds_bpermute_b32 v95, v164, v79
	ds_bpermute_b32 v91, v164, v75
	s_and_saveexec_b64 s[34:35], s[6:7]
	s_cbranch_execz .LBB0_298
	global_load_dwordx4 v[100:103], v[84:85], off
	global_load_dwordx4 v[104:107], v[86:87], off
	global_load_dwordx4 v[108:111], v[80:81], off
	global_load_dwordx4 v[112:115], v[82:83], off
	s_waitcnt vmcnt(0) lgkmcnt(0)
	v_xor_b32_e32 v99, 0x80000000, v100
	v_xor_b32_e32 v116, 0x80000000, v101
	v_xor_b32_e32 v117, 0x80000000, v102
	v_xor_b32_e32 v118, 0x80000000, v103
	v_xor_b32_e32 v119, 0x80000000, v104
	v_xor_b32_e32 v120, 0x80000000, v105
	v_xor_b32_e32 v121, 0x80000000, v106
	v_xor_b32_e32 v122, 0x80000000, v107
	v_cndmask_b32_e64 v107, v107, v122, s[8:9]
	v_cndmask_b32_e64 v106, v106, v121, s[8:9]
	v_cndmask_b32_e64 v105, v105, v120, s[8:9]
	v_cndmask_b32_e64 v104, v104, v119, s[8:9]
	v_cndmask_b32_e64 v103, v103, v118, s[8:9]
	v_cndmask_b32_e64 v102, v102, v117, s[8:9]
	v_cndmask_b32_e64 v101, v101, v116, s[8:9]
	v_cndmask_b32_e64 v100, v100, v99, s[8:9]
	v_pk_mul_f32 v[96:97], v[100:101], v[96:97]
	v_pk_mul_f32 v[94:95], v[102:103], v[94:95]
	v_pk_mul_f32 v[92:93], v[104:105], v[92:93]
	v_pk_mul_f32 v[90:91], v[106:107], v[90:91]
	v_pk_fma_f32 v[78:79], v[78:79], v[110:111], v[94:95]
	v_pk_fma_f32 v[76:77], v[76:77], v[108:109], v[96:97]
	v_pk_fma_f32 v[74:75], v[74:75], v[114:115], v[90:91]
	v_pk_fma_f32 v[72:73], v[72:73], v[112:113], v[92:93]

; DI float shx(float v, int lane, int mask) { return __int_as_float(__builtin_amdgcn_ds_bpermute((lane ^ mask) << 2, __float_as_int(v))); }
; DI u32x4 pk8(const f32x4& v0, const f32x4& v1) { u32x4 w; w.x = cvt_pk_bf16(v0[0], v0[1]); w.y = cvt_pk_bf16(v0[2], v0[3]); w.z = cvt_pk_bf16(v1[0], v1[1]); w.w = cvt_pk_bf16(v1[2], v1[3]); return w; }
;   DI void epi(const Acc& acc, const Unit& u, int wr, int wc, int fr, int fq, LAS unsigned char* lds) const {
;     ...
;           const int row = u.pm * 256 + ai * 128 + wr * 64 + m * 16 + fr; const int pos = tok_pos(row);
; #pragma unroll
;           for (int bj = 0; bj < 2; ++bj) {
;             f32x4 v0 = acc[ai][bj][m][0], v1 = acc[ai][bj][m][1];
;             if (rot) {
;               f32x4 o0, o1;
; #pragma unroll
;               for (int j = 0; j < 4; ++j) { o0[j] = shx(v0[j], fq * 16 + fr, 16); o1[j] = shx(v1[j], fq * 16 + fr, 16); }
;               if (fq < 2) {
;                 const f32x4 c0 = ldf4(cosA, (unsigned)pos * 32u), c1 = ldf4(cosA, (unsigned)pos * 32u + 16u);
;                 f32x4 s0 = ldf4(sinA, (unsigned)pos * 32u), s1 = ldf4(sinA, (unsigned)pos * 32u + 16u);
;                 if (fq == 0) { s0 = -s0; s1 = -s1; }
;                 v0 = v0 * c0 + o0 * s0; v1 = v1 * c1 + o1 * s1;
;               }
;             }
;             v0 *= sc; v1 *= sc;
;             {
;               const int hl = bj * 2 + (wc >> 1), head = isq ? u.pn * 4 + hl : hl, d0 = (wc & 1) * 32 + 8 * fq;
;               st16(isq ? q : k, (unsigned)((((head * 1024 + (row >> 5)) * 4 + (d0 >> 4)) * 64 + ((d0 >> 3) & 1) * 32 + (row & 31)) * 16), pk8(v0, v1)); }
.LBB0_299:
	s_lshr_b32 s34, s52, 3
	s_and_b32 s34, s34, 0x3fffffc
	s_waitcnt lgkmcnt(0)
	v_or_b32_e32 v91, s34, v162
	v_pk_mul_f32 v[78:79], v[88:89], v[78:79]
	v_pk_mul_f32 v[92:93], v[88:89], v[74:75]
	v_lshlrev_b32_e32 v88, 6, v91
	v_and_or_b32 v90, v98, 31, v163
	v_pk_mul_f32 v[74:75], v[140:141], v[72:73]
	v_add_u32_e32 v72, s23, v88
	v_or_b32_e32 v72, v72, v90
	v_pk_mul_f32 v[76:77], v[140:141], v[76:77]
	v_lshlrev_b32_e32 v176, 4, v72
	v_cvt_pk_bf16_f32 v72, v76, v77
	v_lshl_add_u64 v[76:77], s[0:1], 0, v[176:177]
	v_cvt_pk_bf16_f32 v73, v78, v79
	v_cvt_pk_bf16_f32 v74, v74, v75
	v_cvt_pk_bf16_f32 v75, v92, v93
	global_store_dwordx4 v[76:77], v[72:75], off
	s_and_b64 vcc, exec, s[10:11]
	s_cbranch_vccnz .LBB0_303
	ds_bpermute_b32 v78, v164, v68
	ds_bpermute_b32 v74, v164, v64
	ds_bpermute_b32 v79, v164, v69
	ds_bpermute_b32 v75, v164, v65
	ds_bpermute_b32 v76, v164, v70
	ds_bpermute_b32 v72, v164, v66
	ds_bpermute_b32 v77, v164, v71
	ds_bpermute_b32 v73, v164, v67
	s_and_saveexec_b64 s[34:35], s[6:7]
	s_cbranch_execz .LBB0_302
	global_load_dwordx4 v[92:95], v[84:85], off
	s_nop 0
	global_load_dwordx4 v[84:87], v[86:87], off
	s_nop 0
	global_load_dwordx4 v[96:99], v[80:81], off
	s_nop 0
	global_load_dwordx4 v[80:83], v[82:83], off
	s_waitcnt vmcnt(0) lgkmcnt(0)
	v_xor_b32_e32 v89, 0x80000000, v92
	v_xor_b32_e32 v91, 0x80000000, v93
	v_xor_b32_e32 v100, 0x80000000, v94
	v_xor_b32_e32 v101, 0x80000000, v95
	v_xor_b32_e32 v102, 0x80000000, v84
	v_xor_b32_e32 v103, 0x80000000, v85
	v_xor_b32_e32 v104, 0x80000000, v86
	v_xor_b32_e32 v105, 0x80000000, v87
	v_cndmask_b32_e64 v87, v87, v105, s[8:9]
	v_cndmask_b32_e64 v86, v86, v104, s[8:9]
	v_cndmask_b32_e64 v85, v85, v103, s[8:9]
	v_cndmask_b32_e64 v84, v84, v102, s[8:9]
	v_cndmask_b32_e64 v95, v95, v101, s[8:9]
	v_cndmask_b32_e64 v94, v94, v100, s[8:9]
	v_cndmask_b32_e64 v93, v93, v91, s[8:9]
	v_cndmask_b32_e64 v92, v92, v89, s[8:9]
	v_pk_mul_f32 v[78:79], v[92:93], v[78:79]
	v_pk_mul_f32 v[76:77], v[94:95], v[76:77]
	v_pk_mul_f32 v[74:75], v[84:85], v[74:75]
	v_pk_mul_f32 v[72:73], v[86:87], v[72:73]
	v_pk_fma_f32 v[70:71], v[70:71], v[98:99], v[76:77]
	v_pk_fma_f32 v[68:69], v[68:69], v[96:97], v[78:79]
	v_pk_fma_f32 v[66:67], v[66:67], v[82:83], v[72:73]
	v_pk_fma_f32 v[64:65], v[64:65], v[80:81], v[74:75]

; DI float shx(float v, int lane, int mask) { return __int_as_float(__builtin_amdgcn_ds_bpermute((lane ^ mask) << 2, __float_as_int(v))); }
; DI u32x4 pk8(const f32x4& v0, const f32x4& v1) { u32x4 w; w.x = cvt_pk_bf16(v0[0], v0[1]); w.y = cvt_pk_bf16(v0[2], v0[3]); w.z = cvt_pk_bf16(v1[0], v1[1]); w.w = cvt_pk_bf16(v1[2], v1[3]); return w; }
;   DI void epi(const Acc& acc, const Unit& u, int wr, int wc, int fr, int fq, LAS unsigned char* lds) const {
;     ...
;           const int row = u.pm * 256 + ai * 128 + wr * 64 + m * 16 + fr; const int pos = tok_pos(row);
; #pragma unroll
;           for (int bj = 0; bj < 2; ++bj) {
;             f32x4 v0 = acc[ai][bj][m][0], v1 = acc[ai][bj][m][1];
;             if (rot) {
;               f32x4 o0, o1;
; #pragma unroll
;               for (int j = 0; j < 4; ++j) { o0[j] = shx(v0[j], fq * 16 + fr, 16); o1[j] = shx(v1[j], fq * 16 + fr, 16); }
;               if (fq < 2) {
;                 const f32x4 c0 = ldf4(cosA, (unsigned)pos * 32u), c1 = ldf4(cosA, (unsigned)pos * 32u + 16u);
;                 f32x4 s0 = ldf4(sinA, (unsigned)pos * 32u), s1 = ldf4(sinA, (unsigned)pos * 32u + 16u);
;                 if (fq == 0) { s0 = -s0; s1 = -s1; }
;                 v0 = v0 * c0 + o0 * s0; v1 = v1 * c1 + o1 * s1;
;               }
;             }
;             v0 *= sc; v1 *= sc;
;             {
;               const int hl = bj * 2 + (wc >> 1), head = isq ? u.pn * 4 + hl : hl, d0 = (wc & 1) * 32 + 8 * fq;
;               st16(isq ? q : k, (unsigned)((((head * 1024 + (row >> 5)) * 4 + (d0 >> 4)) * 64 + ((d0 >> 3) & 1) * 32 + (row & 31)) * 16), pk8(v0, v1)); }
.LBB0_303:
	s_waitcnt lgkmcnt(0)
	v_mov_b32_e32 v72, v140
	v_mov_b32_e32 v73, v140
	v_pk_mul_f32 v[74:75], v[72:73], v[66:67]
	v_pk_mul_f32 v[66:67], v[140:141], v[64:65]
	v_add_u32_e32 v64, s51, v88
	v_or_b32_e32 v64, v64, v90
	v_pk_mul_f32 v[68:69], v[140:141], v[68:69]
	v_lshlrev_b32_e32 v176, 4, v64
	v_pk_mul_f32 v[70:71], v[72:73], v[70:71]
	v_cvt_pk_bf16_f32 v64, v68, v69
	v_lshl_add_u64 v[68:69], s[0:1], 0, v[176:177]
	v_cvt_pk_bf16_f32 v65, v70, v71
	v_cvt_pk_bf16_f32 v66, v66, v67
	v_cvt_pk_bf16_f32 v67, v74, v75
	global_store_dwordx4 v[68:69], v[64:67], off
	s_add_i32 s52, s2, 0x80
	s_nop 0
	v_or_b32_e32 v64, s52, v156
	v_cmp_gt_i32_e32 vcc, s56, v64
	v_mov_b32_e32 v64, 0xfcf
	v_mov_b32_e32 v65, 0x7cf
	v_cndmask_b32_e32 v64, v64, v65, vcc
	v_bitop3_b32 v64, v64, s52, v156 bitop3:0xe0
	v_lshlrev_b32_e32 v176, 5, v64
	v_or_b32_e32 v70, 16, v176
	v_mov_b32_e32 v71, v177
	v_lshl_add_u64 v[64:65], s[4:5], 0, v[176:177]
	v_lshl_add_u64 v[66:67], s[4:5], 0, v[70:71]
	v_lshl_add_u64 v[68:69], s[30:31], 0, v[176:177]
	s_and_b64 vcc, exec, s[10:11]
	v_lshl_add_u64 v[70:71], s[30:31], 0, v[70:71]
	s_cbranch_vccnz .LBB0_307
	ds_bpermute_b32 v80, v164, v60
	ds_bpermute_b32 v76, v164, v56
	ds_bpermute_b32 v81, v164, v61
	ds_bpermute_b32 v77, v164, v57
	ds_bpermute_b32 v78, v164, v62
	ds_bpermute_b32 v74, v164, v58
	ds_bpermute_b32 v79, v164, v63
	ds_bpermute_b32 v75, v164, v59
	s_and_saveexec_b64 s[34:35], s[6:7]
	s_cbranch_execz .LBB0_306
	global_load_dwordx4 v[82:85], v[68:69], off
	global_load_dwordx4 v[86:89], v[70:71], off
	global_load_dwordx4 v[90:93], v[64:65], off
	global_load_dwordx4 v[94:97], v[66:67], off
	s_waitcnt vmcnt(0) lgkmcnt(0)
	v_xor_b32_e32 v98, 0x80000000, v82
	v_xor_b32_e32 v99, 0x80000000, v83
	v_xor_b32_e32 v100, 0x80000000, v84
	v_xor_b32_e32 v101, 0x80000000, v85
	v_xor_b32_e32 v102, 0x80000000, v86
	v_xor_b32_e32 v103, 0x80000000, v87
	v_xor_b32_e32 v104, 0x80000000, v88
	v_xor_b32_e32 v105, 0x80000000, v89
	v_cndmask_b32_e64 v89, v89, v105, s[8:9]
	v_cndmask_b32_e64 v88, v88, v104, s[8:9]
	v_cndmask_b32_e64 v87, v87, v103, s[8:9]
	v_cndmask_b32_e64 v86, v86, v102, s[8:9]
	v_cndmask_b32_e64 v85, v85, v101, s[8:9]
	v_cndmask_b32_e64 v84, v84, v100, s[8:9]
	v_cndmask_b32_e64 v83, v83, v99, s[8:9]
	v_cndmask_b32_e64 v82, v82, v98, s[8:9]
	v_pk_mul_f32 v[80:81], v[82:83], v[80:81]
	v_pk_mul_f32 v[78:79], v[84:85], v[78:79]
	v_pk_mul_f32 v[76:77], v[86:87], v[76:77]
	v_pk_mul_f32 v[74:75], v[88:89], v[74:75]
	v_pk_fma_f32 v[62:63], v[62:63], v[92:93], v[78:79]
	v_pk_fma_f32 v[60:61], v[60:61], v[90:91], v[80:81]
	v_pk_fma_f32 v[58:59], v[58:59], v[96:97], v[74:75]
	v_pk_fma_f32 v[56:57], v[56:57], v[94:95], v[76:77]

; DI float shx(float v, int lane, int mask) { return __int_as_float(__builtin_amdgcn_ds_bpermute((lane ^ mask) << 2, __float_as_int(v))); }
; DI u32x4 pk8(const f32x4& v0, const f32x4& v1) { u32x4 w; w.x = cvt_pk_bf16(v0[0], v0[1]); w.y = cvt_pk_bf16(v0[2], v0[3]); w.z = cvt_pk_bf16(v1[0], v1[1]); w.w = cvt_pk_bf16(v1[2], v1[3]); return w; }
;   DI void epi(const Acc& acc, const Unit& u, int wr, int wc, int fr, int fq, LAS unsigned char* lds) const {
;     ...
;           const int row = u.pm * 256 + ai * 128 + wr * 64 + m * 16 + fr; const int pos = tok_pos(row);
; #pragma unroll
;           for (int bj = 0; bj < 2; ++bj) {
;             f32x4 v0 = acc[ai][bj][m][0], v1 = acc[ai][bj][m][1];
;             if (rot) {
;               f32x4 o0, o1;
; #pragma unroll
;               for (int j = 0; j < 4; ++j) { o0[j] = shx(v0[j], fq * 16 + fr, 16); o1[j] = shx(v1[j], fq * 16 + fr, 16); }
;               if (fq < 2) {
;                 const f32x4 c0 = ldf4(cosA, (unsigned)pos * 32u), c1 = ldf4(cosA, (unsigned)pos * 32u + 16u);
;                 f32x4 s0 = ldf4(sinA, (unsigned)pos * 32u), s1 = ldf4(sinA, (unsigned)pos * 32u + 16u);
;                 if (fq == 0) { s0 = -s0; s1 = -s1; }
;                 v0 = v0 * c0 + o0 * s0; v1 = v1 * c1 + o1 * s1;
;               }
;             }
;             v0 *= sc; v1 *= sc;
;             {
;               const int hl = bj * 2 + (wc >> 1), head = isq ? u.pn * 4 + hl : hl, d0 = (wc & 1) * 32 + 8 * fq;
;               st16(isq ? q : k, (unsigned)((((head * 1024 + (row >> 5)) * 4 + (d0 >> 4)) * 64 + ((d0 >> 3) & 1) * 32 + (row & 31)) * 16), pk8(v0, v1)); }
.LBB0_307:
	s_lshr_b32 s34, s52, 3
	s_and_b32 s34, s34, 0x3fffff8
	s_waitcnt lgkmcnt(0)
	v_or_b32_e32 v76, s34, v162
	v_pk_mul_f32 v[62:63], v[72:73], v[62:63]
	v_pk_mul_f32 v[74:75], v[72:73], v[58:59]
	v_lshlrev_b32_e32 v72, 6, v76
	v_pk_mul_f32 v[58:59], v[140:141], v[56:57]
	v_add_u32_e32 v56, s23, v72
	v_or_b32_e32 v56, v56, v165
	v_pk_mul_f32 v[60:61], v[140:141], v[60:61]
	v_lshlrev_b32_e32 v176, 4, v56
	v_cvt_pk_bf16_f32 v56, v60, v61
	v_lshl_add_u64 v[60:61], s[0:1], 0, v[176:177]
	v_cvt_pk_bf16_f32 v57, v62, v63
	v_cvt_pk_bf16_f32 v58, v58, v59
	v_cvt_pk_bf16_f32 v59, v74, v75
	global_store_dwordx4 v[60:61], v[56:59], off
	s_and_b64 vcc, exec, s[10:11]
	s_cbranch_vccnz .LBB0_311
	ds_bpermute_b32 v62, v164, v52
	ds_bpermute_b32 v58, v164, v48
	ds_bpermute_b32 v63, v164, v53
	ds_bpermute_b32 v59, v164, v49
	ds_bpermute_b32 v60, v164, v54
	ds_bpermute_b32 v56, v164, v50
	ds_bpermute_b32 v61, v164, v55
	ds_bpermute_b32 v57, v164, v51
	s_and_saveexec_b64 s[34:35], s[6:7]
	s_cbranch_execz .LBB0_310
	global_load_dwordx4 v[74:77], v[68:69], off
	s_nop 0
	global_load_dwordx4 v[68:71], v[70:71], off
	s_nop 0
	global_load_dwordx4 v[78:81], v[64:65], off
	s_nop 0
	global_load_dwordx4 v[64:67], v[66:67], off
	s_waitcnt vmcnt(0) lgkmcnt(0)
	v_xor_b32_e32 v73, 0x80000000, v74
	v_xor_b32_e32 v82, 0x80000000, v75
	v_xor_b32_e32 v83, 0x80000000, v76
	v_xor_b32_e32 v84, 0x80000000, v77
	v_xor_b32_e32 v85, 0x80000000, v68
	v_xor_b32_e32 v86, 0x80000000, v69
	v_xor_b32_e32 v87, 0x80000000, v70
	v_xor_b32_e32 v88, 0x80000000, v71
	v_cndmask_b32_e64 v71, v71, v88, s[8:9]
	v_cndmask_b32_e64 v70, v70, v87, s[8:9]
	v_cndmask_b32_e64 v69, v69, v86, s[8:9]
	v_cndmask_b32_e64 v68, v68, v85, s[8:9]
	v_cndmask_b32_e64 v77, v77, v84, s[8:9]
	v_cndmask_b32_e64 v76, v76, v83, s[8:9]
	v_cndmask_b32_e64 v75, v75, v82, s[8:9]
	v_cndmask_b32_e64 v74, v74, v73, s[8:9]
	v_pk_mul_f32 v[62:63], v[74:75], v[62:63]
	v_pk_mul_f32 v[60:61], v[76:77], v[60:61]
	v_pk_mul_f32 v[58:59], v[68:69], v[58:59]
	v_pk_mul_f32 v[56:57], v[70:71], v[56:57]
	v_pk_fma_f32 v[54:55], v[54:55], v[80:81], v[60:61]
	v_pk_fma_f32 v[52:53], v[52:53], v[78:79], v[62:63]
	v_pk_fma_f32 v[50:51], v[50:51], v[66:67], v[56:57]
	v_pk_fma_f32 v[48:49], v[48:49], v[64:65], v[58:59]

; DI float shx(float v, int lane, int mask) { return __int_as_float(__builtin_amdgcn_ds_bpermute((lane ^ mask) << 2, __float_as_int(v))); }
; DI u32x4 pk8(const f32x4& v0, const f32x4& v1) { u32x4 w; w.x = cvt_pk_bf16(v0[0], v0[1]); w.y = cvt_pk_bf16(v0[2], v0[3]); w.z = cvt_pk_bf16(v1[0], v1[1]); w.w = cvt_pk_bf16(v1[2], v1[3]); return w; }
;   DI void epi(const Acc& acc, const Unit& u, int wr, int wc, int fr, int fq, LAS unsigned char* lds) const {
;     ...
;           const int row = u.pm * 256 + ai * 128 + wr * 64 + m * 16 + fr; const int pos = tok_pos(row);
; #pragma unroll
;           for (int bj = 0; bj < 2; ++bj) {
;             f32x4 v0 = acc[ai][bj][m][0], v1 = acc[ai][bj][m][1];
;             if (rot) {
;               f32x4 o0, o1;
; #pragma unroll
;               for (int j = 0; j < 4; ++j) { o0[j] = shx(v0[j], fq * 16 + fr, 16); o1[j] = shx(v1[j], fq * 16 + fr, 16); }
;               if (fq < 2) {
;                 const f32x4 c0 = ldf4(cosA, (unsigned)pos * 32u), c1 = ldf4(cosA, (unsigned)pos * 32u + 16u);
;                 f32x4 s0 = ldf4(sinA, (unsigned)pos * 32u), s1 = ldf4(sinA, (unsigned)pos * 32u + 16u);
;                 if (fq == 0) { s0 = -s0; s1 = -s1; }
;                 v0 = v0 * c0 + o0 * s0; v1 = v1 * c1 + o1 * s1;
;               }
;             }
;             v0 *= sc; v1 *= sc;
;             {
;               const int hl = bj * 2 + (wc >> 1), head = isq ? u.pn * 4 + hl : hl, d0 = (wc & 1) * 32 + 8 * fq;
;               st16(isq ? q : k, (unsigned)((((head * 1024 + (row >> 5)) * 4 + (d0 >> 4)) * 64 + ((d0 >> 3) & 1) * 32 + (row & 31)) * 16), pk8(v0, v1)); }
.LBB0_311:
	s_waitcnt lgkmcnt(0)
	v_mov_b32_e32 v56, v140
	v_mov_b32_e32 v57, v140
	v_pk_mul_f32 v[58:59], v[56:57], v[50:51]
	v_pk_mul_f32 v[50:51], v[140:141], v[48:49]
	v_add_u32_e32 v48, s51, v72
	v_or_b32_e32 v48, v48, v165
	v_pk_mul_f32 v[52:53], v[140:141], v[52:53]
	v_lshlrev_b32_e32 v176, 4, v48
	v_pk_mul_f32 v[54:55], v[56:57], v[54:55]
	v_cvt_pk_bf16_f32 v48, v52, v53
	v_lshl_add_u64 v[52:53], s[0:1], 0, v[176:177]
	v_cvt_pk_bf16_f32 v49, v54, v55
	v_cvt_pk_bf16_f32 v50, v50, v51
	v_cvt_pk_bf16_f32 v51, v58, v59
	global_store_dwordx4 v[52:53], v[48:51], off
	s_add_i32 s52, s2, 0x90
	v_or_b32_e32 v66, s52, v156
	v_cmp_gt_i32_e32 vcc, s56, v66
	v_mov_b32_e32 v48, 0xfdf
	v_mov_b32_e32 v49, 0x7df
	v_cndmask_b32_e32 v48, v48, v49, vcc
	v_bitop3_b32 v48, v48, s52, v156 bitop3:0xe0
	v_lshlrev_b32_e32 v176, 5, v48
	v_or_b32_e32 v54, 16, v176
	v_mov_b32_e32 v55, v177
	v_lshl_add_u64 v[48:49], s[4:5], 0, v[176:177]
	v_lshl_add_u64 v[50:51], s[4:5], 0, v[54:55]
	v_lshl_add_u64 v[52:53], s[30:31], 0, v[176:177]
	s_and_b64 vcc, exec, s[10:11]
	v_lshl_add_u64 v[54:55], s[30:31], 0, v[54:55]
	s_cbranch_vccnz .LBB0_315
	ds_bpermute_b32 v64, v164, v44
	ds_bpermute_b32 v60, v164, v40
	ds_bpermute_b32 v65, v164, v45
	ds_bpermute_b32 v61, v164, v41
	ds_bpermute_b32 v62, v164, v46
	ds_bpermute_b32 v58, v164, v42
	ds_bpermute_b32 v63, v164, v47
	ds_bpermute_b32 v59, v164, v43
	s_and_saveexec_b64 s[34:35], s[6:7]
	s_cbranch_execz .LBB0_314
	global_load_dwordx4 v[68:71], v[52:53], off
	global_load_dwordx4 v[72:75], v[54:55], off
	global_load_dwordx4 v[76:79], v[48:49], off
	global_load_dwordx4 v[80:83], v[50:51], off
	s_waitcnt vmcnt(0) lgkmcnt(0)
	v_xor_b32_e32 v67, 0x80000000, v68
	v_xor_b32_e32 v84, 0x80000000, v69
	v_xor_b32_e32 v85, 0x80000000, v70
	v_xor_b32_e32 v86, 0x80000000, v71
	v_xor_b32_e32 v87, 0x80000000, v72
	v_xor_b32_e32 v88, 0x80000000, v73
	v_xor_b32_e32 v89, 0x80000000, v74
	v_xor_b32_e32 v90, 0x80000000, v75
	v_cndmask_b32_e64 v75, v75, v90, s[8:9]
	v_cndmask_b32_e64 v74, v74, v89, s[8:9]
	v_cndmask_b32_e64 v73, v73, v88, s[8:9]
	v_cndmask_b32_e64 v72, v72, v87, s[8:9]
	v_cndmask_b32_e64 v71, v71, v86, s[8:9]
	v_cndmask_b32_e64 v70, v70, v85, s[8:9]
	v_cndmask_b32_e64 v69, v69, v84, s[8:9]
	v_cndmask_b32_e64 v68, v68, v67, s[8:9]
	v_pk_mul_f32 v[64:65], v[68:69], v[64:65]
	v_pk_mul_f32 v[62:63], v[70:71], v[62:63]
	v_pk_mul_f32 v[60:61], v[72:73], v[60:61]
	v_pk_mul_f32 v[58:59], v[74:75], v[58:59]
	v_pk_fma_f32 v[46:47], v[46:47], v[78:79], v[62:63]
	v_pk_fma_f32 v[44:45], v[44:45], v[76:77], v[64:65]
	v_pk_fma_f32 v[42:43], v[42:43], v[82:83], v[58:59]
	v_pk_fma_f32 v[40:41], v[40:41], v[80:81], v[60:61]

; DI float shx(float v, int lane, int mask) { return __int_as_float(__builtin_amdgcn_ds_bpermute((lane ^ mask) << 2, __float_as_int(v))); }
; DI u32x4 pk8(const f32x4& v0, const f32x4& v1) { u32x4 w; w.x = cvt_pk_bf16(v0[0], v0[1]); w.y = cvt_pk_bf16(v0[2], v0[3]); w.z = cvt_pk_bf16(v1[0], v1[1]); w.w = cvt_pk_bf16(v1[2], v1[3]); return w; }
;   DI void epi(const Acc& acc, const Unit& u, int wr, int wc, int fr, int fq, LAS unsigned char* lds) const {
;     ...
;           const int row = u.pm * 256 + ai * 128 + wr * 64 + m * 16 + fr; const int pos = tok_pos(row);
; #pragma unroll
;           for (int bj = 0; bj < 2; ++bj) {
;             f32x4 v0 = acc[ai][bj][m][0], v1 = acc[ai][bj][m][1];
;             if (rot) {
;               f32x4 o0, o1;
; #pragma unroll
;               for (int j = 0; j < 4; ++j) { o0[j] = shx(v0[j], fq * 16 + fr, 16); o1[j] = shx(v1[j], fq * 16 + fr, 16); }
;               if (fq < 2) {
;                 const f32x4 c0 = ldf4(cosA, (unsigned)pos * 32u), c1 = ldf4(cosA, (unsigned)pos * 32u + 16u);
;                 f32x4 s0 = ldf4(sinA, (unsigned)pos * 32u), s1 = ldf4(sinA, (unsigned)pos * 32u + 16u);
;                 if (fq == 0) { s0 = -s0; s1 = -s1; }
;                 v0 = v0 * c0 + o0 * s0; v1 = v1 * c1 + o1 * s1;
;               }
;             }
;             v0 *= sc; v1 *= sc;
;             {
;               const int hl = bj * 2 + (wc >> 1), head = isq ? u.pn * 4 + hl : hl, d0 = (wc & 1) * 32 + 8 * fq;
;               st16(isq ? q : k, (unsigned)((((head * 1024 + (row >> 5)) * 4 + (d0 >> 4)) * 64 + ((d0 >> 3) & 1) * 32 + (row & 31)) * 16), pk8(v0, v1)); }
.LBB0_315:
	s_lshr_b32 s34, s52, 3
	s_and_b32 s34, s34, 0x3fffff8
	s_waitcnt lgkmcnt(0)
	v_or_b32_e32 v59, s34, v162
	v_pk_mul_f32 v[46:47], v[56:57], v[46:47]
	v_pk_mul_f32 v[60:61], v[56:57], v[42:43]
	v_lshlrev_b32_e32 v56, 6, v59
	v_and_or_b32 v58, v66, 31, v163
	v_pk_mul_f32 v[42:43], v[140:141], v[40:41]
	v_add_u32_e32 v40, s23, v56
	v_or_b32_e32 v40, v40, v58
	v_pk_mul_f32 v[44:45], v[140:141], v[44:45]
	v_lshlrev_b32_e32 v176, 4, v40
	v_cvt_pk_bf16_f32 v40, v44, v45
	v_lshl_add_u64 v[44:45], s[0:1], 0, v[176:177]
	v_cvt_pk_bf16_f32 v41, v46, v47
	v_cvt_pk_bf16_f32 v42, v42, v43
	v_cvt_pk_bf16_f32 v43, v60, v61
	global_store_dwordx4 v[44:45], v[40:43], off
	s_and_b64 vcc, exec, s[10:11]
	s_cbranch_vccnz .LBB0_319
	ds_bpermute_b32 v46, v164, v36
	ds_bpermute_b32 v42, v164, v32
	ds_bpermute_b32 v47, v164, v37
	ds_bpermute_b32 v43, v164, v33
	ds_bpermute_b32 v44, v164, v38
	ds_bpermute_b32 v40, v164, v34
	ds_bpermute_b32 v45, v164, v39
	ds_bpermute_b32 v41, v164, v35
	s_and_saveexec_b64 s[34:35], s[6:7]
	s_cbranch_execz .LBB0_318
	global_load_dwordx4 v[60:63], v[52:53], off
	s_nop 0
	global_load_dwordx4 v[52:55], v[54:55], off
	s_nop 0
	global_load_dwordx4 v[64:67], v[48:49], off
	s_nop 0
	global_load_dwordx4 v[48:51], v[50:51], off
	s_waitcnt vmcnt(0) lgkmcnt(0)
	v_xor_b32_e32 v57, 0x80000000, v60
	v_xor_b32_e32 v59, 0x80000000, v61
	v_xor_b32_e32 v68, 0x80000000, v62
	v_xor_b32_e32 v69, 0x80000000, v63
	v_xor_b32_e32 v70, 0x80000000, v52
	v_xor_b32_e32 v71, 0x80000000, v53
	v_xor_b32_e32 v72, 0x80000000, v54
	v_xor_b32_e32 v73, 0x80000000, v55
	v_cndmask_b32_e64 v55, v55, v73, s[8:9]
	v_cndmask_b32_e64 v54, v54, v72, s[8:9]
	v_cndmask_b32_e64 v53, v53, v71, s[8:9]
	v_cndmask_b32_e64 v52, v52, v70, s[8:9]
	v_cndmask_b32_e64 v63, v63, v69, s[8:9]
	v_cndmask_b32_e64 v62, v62, v68, s[8:9]
	v_cndmask_b32_e64 v61, v61, v59, s[8:9]
	v_cndmask_b32_e64 v60, v60, v57, s[8:9]
	v_pk_mul_f32 v[46:47], v[60:61], v[46:47]
	v_pk_mul_f32 v[44:45], v[62:63], v[44:45]
	v_pk_mul_f32 v[42:43], v[52:53], v[42:43]
	v_pk_mul_f32 v[40:41], v[54:55], v[40:41]
	v_pk_fma_f32 v[38:39], v[38:39], v[66:67], v[44:45]
	v_pk_fma_f32 v[36:37], v[36:37], v[64:65], v[46:47]
	v_pk_fma_f32 v[34:35], v[34:35], v[50:51], v[40:41]
	v_pk_fma_f32 v[32:33], v[32:33], v[48:49], v[42:43]

; DI float shx(float v, int lane, int mask) { return __int_as_float(__builtin_amdgcn_ds_bpermute((lane ^ mask) << 2, __float_as_int(v))); }
; DI u32x4 pk8(const f32x4& v0, const f32x4& v1) { u32x4 w; w.x = cvt_pk_bf16(v0[0], v0[1]); w.y = cvt_pk_bf16(v0[2], v0[3]); w.z = cvt_pk_bf16(v1[0], v1[1]); w.w = cvt_pk_bf16(v1[2], v1[3]); return w; }
;   DI void epi(const Acc& acc, const Unit& u, int wr, int wc, int fr, int fq, LAS unsigned char* lds) const {
;     ...
;           for (int bj = 0; bj < 2; ++bj) {
;             f32x4 v0 = acc[ai][bj][m][0], v1 = acc[ai][bj][m][1];
;             if (rot) {
;               f32x4 o0, o1;
; #pragma unroll
;               for (int j = 0; j < 4; ++j) { o0[j] = shx(v0[j], fq * 16 + fr, 16); o1[j] = shx(v1[j], fq * 16 + fr, 16); }
;               if (fq < 2) {
;                 const f32x4 c0 = ldf4(cosA, (unsigned)pos * 32u), c1 = ldf4(cosA, (unsigned)pos * 32u + 16u);
;                 f32x4 s0 = ldf4(sinA, (unsigned)pos * 32u), s1 = ldf4(sinA, (unsigned)pos * 32u + 16u);
;                 if (fq == 0) { s0 = -s0; s1 = -s1; }
;                 v0 = v0 * c0 + o0 * s0; v1 = v1 * c1 + o1 * s1;
;               }
;             }
;             v0 *= sc; v1 *= sc;
;             {
;               const int hl = bj * 2 + (wc >> 1), head = isq ? u.pn * 4 + hl : hl, d0 = (wc & 1) * 32 + 8 * fq;
;               st16(isq ? q : k, (unsigned)((((head * 1024 + (row >> 5)) * 4 + (d0 >> 4)) * 64 + ((d0 >> 3) & 1) * 32 + (row & 31)) * 16), pk8(v0, v1)); }
.LBB0_319:
	s_waitcnt lgkmcnt(0)
	v_mov_b32_e32 v40, v140
	v_mov_b32_e32 v41, v140
	v_pk_mul_f32 v[42:43], v[40:41], v[34:35]
	v_pk_mul_f32 v[34:35], v[140:141], v[32:33]
	v_add_u32_e32 v32, s51, v56
	v_or_b32_e32 v32, v32, v58
	v_pk_mul_f32 v[36:37], v[140:141], v[36:37]
	v_lshlrev_b32_e32 v176, 4, v32
	v_pk_mul_f32 v[38:39], v[40:41], v[38:39]
	v_cvt_pk_bf16_f32 v32, v36, v37
	v_lshl_add_u64 v[36:37], s[0:1], 0, v[176:177]
	v_cvt_pk_bf16_f32 v33, v38, v39
	v_cvt_pk_bf16_f32 v34, v34, v35
	v_cvt_pk_bf16_f32 v35, v42, v43
	global_store_dwordx4 v[36:37], v[32:35], off
	s_add_i32 s52, s2, 0xa0
	s_nop 0
	v_or_b32_e32 v32, s52, v156
	v_cmp_gt_i32_e32 vcc, s56, v32
	v_mov_b32_e32 v32, 0xfef
	v_mov_b32_e32 v33, 0x7ef
	v_cndmask_b32_e32 v32, v32, v33, vcc
	v_bitop3_b32 v32, v32, s52, v156 bitop3:0xe0
	v_lshlrev_b32_e32 v176, 5, v32
	v_or_b32_e32 v38, 16, v176
	v_mov_b32_e32 v39, v177
	v_lshl_add_u64 v[32:33], s[4:5], 0, v[176:177]
	v_lshl_add_u64 v[34:35], s[4:5], 0, v[38:39]
	v_lshl_add_u64 v[36:37], s[30:31], 0, v[176:177]
	s_and_b64 vcc, exec, s[10:11]
	v_lshl_add_u64 v[38:39], s[30:31], 0, v[38:39]
	s_cbranch_vccnz .LBB0_323
	ds_bpermute_b32 v48, v164, v28
	ds_bpermute_b32 v44, v164, v24
	ds_bpermute_b32 v49, v164, v29
	ds_bpermute_b32 v45, v164, v25
	ds_bpermute_b32 v46, v164, v30
	ds_bpermute_b32 v42, v164, v26
	ds_bpermute_b32 v47, v164, v31
	ds_bpermute_b32 v43, v164, v27
	s_and_saveexec_b64 s[34:35], s[6:7]
	s_cbranch_execz .LBB0_322
	global_load_dwordx4 v[50:53], v[36:37], off
	global_load_dwordx4 v[54:57], v[38:39], off
	global_load_dwordx4 v[58:61], v[32:33], off
	global_load_dwordx4 v[62:65], v[34:35], off
	s_waitcnt vmcnt(0) lgkmcnt(0)
	v_xor_b32_e32 v66, 0x80000000, v50
	v_xor_b32_e32 v67, 0x80000000, v51
	v_xor_b32_e32 v68, 0x80000000, v52
	v_xor_b32_e32 v69, 0x80000000, v53
	v_xor_b32_e32 v70, 0x80000000, v54
	v_xor_b32_e32 v71, 0x80000000, v55
	v_xor_b32_e32 v72, 0x80000000, v56
	v_xor_b32_e32 v73, 0x80000000, v57
	v_cndmask_b32_e64 v57, v57, v73, s[8:9]
	v_cndmask_b32_e64 v56, v56, v72, s[8:9]
	v_cndmask_b32_e64 v55, v55, v71, s[8:9]
	v_cndmask_b32_e64 v54, v54, v70, s[8:9]
	v_cndmask_b32_e64 v53, v53, v69, s[8:9]
	v_cndmask_b32_e64 v52, v52, v68, s[8:9]
	v_cndmask_b32_e64 v51, v51, v67, s[8:9]
	v_cndmask_b32_e64 v50, v50, v66, s[8:9]
	v_pk_mul_f32 v[48:49], v[50:51], v[48:49]
	v_pk_mul_f32 v[46:47], v[52:53], v[46:47]
	v_pk_mul_f32 v[44:45], v[54:55], v[44:45]
	v_pk_mul_f32 v[42:43], v[56:57], v[42:43]
	v_pk_fma_f32 v[30:31], v[30:31], v[60:61], v[46:47]
	v_pk_fma_f32 v[28:29], v[28:29], v[58:59], v[48:49]
	v_pk_fma_f32 v[26:27], v[26:27], v[64:65], v[42:43]
	v_pk_fma_f32 v[24:25], v[24:25], v[62:63], v[44:45]

; DI float shx(float v, int lane, int mask) { return __int_as_float(__builtin_amdgcn_ds_bpermute((lane ^ mask) << 2, __float_as_int(v))); }
; DI u32x4 pk8(const f32x4& v0, const f32x4& v1) { u32x4 w; w.x = cvt_pk_bf16(v0[0], v0[1]); w.y = cvt_pk_bf16(v0[2], v0[3]); w.z = cvt_pk_bf16(v1[0], v1[1]); w.w = cvt_pk_bf16(v1[2], v1[3]); return w; }
;   DI void epi(const Acc& acc, const Unit& u, int wr, int wc, int fr, int fq, LAS unsigned char* lds) const {
;     ...
;           for (int bj = 0; bj < 2; ++bj) {
;             f32x4 v0 = acc[ai][bj][m][0], v1 = acc[ai][bj][m][1];
;             if (rot) {
;               f32x4 o0, o1;
; #pragma unroll
;               for (int j = 0; j < 4; ++j) { o0[j] = shx(v0[j], fq * 16 + fr, 16); o1[j] = shx(v1[j], fq * 16 + fr, 16); }
;               if (fq < 2) {
;                 const f32x4 c0 = ldf4(cosA, (unsigned)pos * 32u), c1 = ldf4(cosA, (unsigned)pos * 32u + 16u);
;                 f32x4 s0 = ldf4(sinA, (unsigned)pos * 32u), s1 = ldf4(sinA, (unsigned)pos * 32u + 16u);
;                 if (fq == 0) { s0 = -s0; s1 = -s1; }
;                 v0 = v0 * c0 + o0 * s0; v1 = v1 * c1 + o1 * s1;
;               }
;             }
;             v0 *= sc; v1 *= sc;
;             {
;               const int hl = bj * 2 + (wc >> 1), head = isq ? u.pn * 4 + hl : hl, d0 = (wc & 1) * 32 + 8 * fq;
;               st16(isq ? q : k, (unsigned)((((head * 1024 + (row >> 5)) * 4 + (d0 >> 4)) * 64 + ((d0 >> 3) & 1) * 32 + (row & 31)) * 16), pk8(v0, v1)); }
.LBB0_323:
	s_lshr_b32 s34, s52, 3
	s_and_b32 s34, s34, 0x3fffffc
	s_waitcnt lgkmcnt(0)
	v_or_b32_e32 v44, s34, v162
	v_pk_mul_f32 v[30:31], v[40:41], v[30:31]
	v_pk_mul_f32 v[42:43], v[40:41], v[26:27]
	v_lshlrev_b32_e32 v40, 6, v44
	v_pk_mul_f32 v[26:27], v[140:141], v[24:25]
	v_add_u32_e32 v24, s23, v40
	v_or_b32_e32 v24, v24, v165
	v_pk_mul_f32 v[28:29], v[140:141], v[28:29]
	v_lshlrev_b32_e32 v176, 4, v24
	v_cvt_pk_bf16_f32 v24, v28, v29
	v_lshl_add_u64 v[28:29], s[0:1], 0, v[176:177]
	v_cvt_pk_bf16_f32 v25, v30, v31
	v_cvt_pk_bf16_f32 v26, v26, v27
	v_cvt_pk_bf16_f32 v27, v42, v43
	global_store_dwordx4 v[28:29], v[24:27], off
	s_and_b64 vcc, exec, s[10:11]
	s_cbranch_vccnz .LBB0_327
	ds_bpermute_b32 v30, v164, v20
	ds_bpermute_b32 v26, v164, v16
	ds_bpermute_b32 v31, v164, v21
	ds_bpermute_b32 v27, v164, v17
	ds_bpermute_b32 v28, v164, v22
	ds_bpermute_b32 v24, v164, v18
	ds_bpermute_b32 v29, v164, v23
	ds_bpermute_b32 v25, v164, v19
	s_and_saveexec_b64 s[34:35], s[6:7]
	s_cbranch_execz .LBB0_326
	global_load_dwordx4 v[42:45], v[36:37], off
	s_nop 0
	global_load_dwordx4 v[36:39], v[38:39], off
	s_nop 0
	global_load_dwordx4 v[46:49], v[32:33], off
	s_nop 0
	global_load_dwordx4 v[32:35], v[34:35], off
	s_waitcnt vmcnt(0) lgkmcnt(0)
	v_xor_b32_e32 v41, 0x80000000, v42
	v_xor_b32_e32 v50, 0x80000000, v43
	v_xor_b32_e32 v51, 0x80000000, v44
	v_xor_b32_e32 v52, 0x80000000, v45
	v_xor_b32_e32 v53, 0x80000000, v36
	v_xor_b32_e32 v54, 0x80000000, v37
	v_xor_b32_e32 v55, 0x80000000, v38
	v_xor_b32_e32 v56, 0x80000000, v39
	v_cndmask_b32_e64 v39, v39, v56, s[8:9]
	v_cndmask_b32_e64 v38, v38, v55, s[8:9]
	v_cndmask_b32_e64 v37, v37, v54, s[8:9]
	v_cndmask_b32_e64 v36, v36, v53, s[8:9]
	v_cndmask_b32_e64 v45, v45, v52, s[8:9]
	v_cndmask_b32_e64 v44, v44, v51, s[8:9]
	v_cndmask_b32_e64 v43, v43, v50, s[8:9]
	v_cndmask_b32_e64 v42, v42, v41, s[8:9]
	v_pk_mul_f32 v[30:31], v[42:43], v[30:31]
	v_pk_mul_f32 v[28:29], v[44:45], v[28:29]
	v_pk_mul_f32 v[26:27], v[36:37], v[26:27]
	v_pk_mul_f32 v[24:25], v[38:39], v[24:25]
	v_pk_fma_f32 v[22:23], v[22:23], v[48:49], v[28:29]
	v_pk_fma_f32 v[20:21], v[20:21], v[46:47], v[30:31]
	v_pk_fma_f32 v[18:19], v[18:19], v[34:35], v[24:25]
	v_pk_fma_f32 v[16:17], v[16:17], v[32:33], v[26:27]

; DI float shx(float v, int lane, int mask) { return __int_as_float(__builtin_amdgcn_ds_bpermute((lane ^ mask) << 2, __float_as_int(v))); }
; DI u32x4 pk8(const f32x4& v0, const f32x4& v1) { u32x4 w; w.x = cvt_pk_bf16(v0[0], v0[1]); w.y = cvt_pk_bf16(v0[2], v0[3]); w.z = cvt_pk_bf16(v1[0], v1[1]); w.w = cvt_pk_bf16(v1[2], v1[3]); return w; }
;   DI void epi(const Acc& acc, const Unit& u, int wr, int wc, int fr, int fq, LAS unsigned char* lds) const {
;     ...
;           const int row = u.pm * 256 + ai * 128 + wr * 64 + m * 16 + fr; const int pos = tok_pos(row);
; #pragma unroll
;           for (int bj = 0; bj < 2; ++bj) {
;             f32x4 v0 = acc[ai][bj][m][0], v1 = acc[ai][bj][m][1];
;             if (rot) {
;               f32x4 o0, o1;
; #pragma unroll
;               for (int j = 0; j < 4; ++j) { o0[j] = shx(v0[j], fq * 16 + fr, 16); o1[j] = shx(v1[j], fq * 16 + fr, 16); }
;               if (fq < 2) {
;                 const f32x4 c0 = ldf4(cosA, (unsigned)pos * 32u), c1 = ldf4(cosA, (unsigned)pos * 32u + 16u);
;                 f32x4 s0 = ldf4(sinA, (unsigned)pos * 32u), s1 = ldf4(sinA, (unsigned)pos * 32u + 16u);
;                 if (fq == 0) { s0 = -s0; s1 = -s1; }
;                 v0 = v0 * c0 + o0 * s0; v1 = v1 * c1 + o1 * s1;
;               }
;             }
;             v0 *= sc; v1 *= sc;
;             {
;               const int hl = bj * 2 + (wc >> 1), head = isq ? u.pn * 4 + hl : hl, d0 = (wc & 1) * 32 + 8 * fq;
;               st16(isq ? q : k, (unsigned)((((head * 1024 + (row >> 5)) * 4 + (d0 >> 4)) * 64 + ((d0 >> 3) & 1) * 32 + (row & 31)) * 16), pk8(v0, v1)); }
.LBB0_327:
	s_waitcnt lgkmcnt(0)
	v_mov_b32_e32 v24, v140
	v_mov_b32_e32 v25, v140
	v_pk_mul_f32 v[26:27], v[24:25], v[18:19]
	v_pk_mul_f32 v[18:19], v[140:141], v[16:17]
	v_add_u32_e32 v16, s51, v40
	v_or_b32_e32 v16, v16, v165
	v_pk_mul_f32 v[20:21], v[140:141], v[20:21]
	v_lshlrev_b32_e32 v176, 4, v16
	v_pk_mul_f32 v[22:23], v[24:25], v[22:23]
	v_cvt_pk_bf16_f32 v16, v20, v21
	v_lshl_add_u64 v[20:21], s[0:1], 0, v[176:177]
	v_cvt_pk_bf16_f32 v17, v22, v23
	v_cvt_pk_bf16_f32 v18, v18, v19
	v_cvt_pk_bf16_f32 v19, v26, v27
	global_store_dwordx4 v[20:21], v[16:19], off
	s_addk_i32 s2, 0xb0
	v_or_b32_e32 v34, s2, v156
	v_cmp_gt_i32_e32 vcc, s56, v34
	v_mov_b32_e32 v16, 0xfff
	v_mov_b32_e32 v17, 0x7ff
	v_cndmask_b32_e32 v16, v16, v17, vcc
	v_bitop3_b32 v16, v16, s2, v156 bitop3:0xe0
	v_lshlrev_b32_e32 v176, 5, v16
	v_or_b32_e32 v22, 16, v176
	v_mov_b32_e32 v23, v177
	v_lshl_add_u64 v[16:17], s[4:5], 0, v[176:177]
	v_lshl_add_u64 v[18:19], s[4:5], 0, v[22:23]
	v_lshl_add_u64 v[20:21], s[30:31], 0, v[176:177]
	s_and_b64 vcc, exec, s[10:11]
	v_lshl_add_u64 v[22:23], s[30:31], 0, v[22:23]
	s_cbranch_vccnz .LBB0_331
	ds_bpermute_b32 v32, v164, v12
	ds_bpermute_b32 v28, v164, v8
	ds_bpermute_b32 v33, v164, v13
	ds_bpermute_b32 v29, v164, v9
	ds_bpermute_b32 v30, v164, v14
	ds_bpermute_b32 v26, v164, v10
	ds_bpermute_b32 v31, v164, v15
	ds_bpermute_b32 v27, v164, v11
	s_and_saveexec_b64 s[4:5], s[6:7]
	s_cbranch_execz .LBB0_330
	global_load_dwordx4 v[36:39], v[20:21], off
	global_load_dwordx4 v[40:43], v[22:23], off
	global_load_dwordx4 v[44:47], v[16:17], off
	global_load_dwordx4 v[48:51], v[18:19], off
	s_waitcnt vmcnt(0) lgkmcnt(0)
	v_xor_b32_e32 v35, 0x80000000, v36
	v_xor_b32_e32 v52, 0x80000000, v37
	v_xor_b32_e32 v53, 0x80000000, v38
	v_xor_b32_e32 v54, 0x80000000, v39
	v_xor_b32_e32 v55, 0x80000000, v40
	v_xor_b32_e32 v56, 0x80000000, v41
	v_xor_b32_e32 v57, 0x80000000, v42
	v_xor_b32_e32 v58, 0x80000000, v43
	v_cndmask_b32_e64 v43, v43, v58, s[8:9]
	v_cndmask_b32_e64 v42, v42, v57, s[8:9]
	v_cndmask_b32_e64 v41, v41, v56, s[8:9]
	v_cndmask_b32_e64 v40, v40, v55, s[8:9]
	v_cndmask_b32_e64 v39, v39, v54, s[8:9]
	v_cndmask_b32_e64 v38, v38, v53, s[8:9]
	v_cndmask_b32_e64 v37, v37, v52, s[8:9]
	v_cndmask_b32_e64 v36, v36, v35, s[8:9]
	v_pk_mul_f32 v[32:33], v[36:37], v[32:33]
	v_pk_mul_f32 v[30:31], v[38:39], v[30:31]
	v_pk_mul_f32 v[28:29], v[40:41], v[28:29]
	v_pk_mul_f32 v[26:27], v[42:43], v[26:27]
	v_pk_fma_f32 v[14:15], v[14:15], v[46:47], v[30:31]
	v_pk_fma_f32 v[12:13], v[12:13], v[44:45], v[32:33]
	v_pk_fma_f32 v[10:11], v[10:11], v[50:51], v[26:27]
	v_pk_fma_f32 v[8:9], v[8:9], v[48:49], v[28:29]

; DI float shx(float v, int lane, int mask) { return __int_as_float(__builtin_amdgcn_ds_bpermute((lane ^ mask) << 2, __float_as_int(v))); }
; DI u32x4 pk8(const f32x4& v0, const f32x4& v1) { u32x4 w; w.x = cvt_pk_bf16(v0[0], v0[1]); w.y = cvt_pk_bf16(v0[2], v0[3]); w.z = cvt_pk_bf16(v1[0], v1[1]); w.w = cvt_pk_bf16(v1[2], v1[3]); return w; }
;   DI void epi(const Acc& acc, const Unit& u, int wr, int wc, int fr, int fq, LAS unsigned char* lds) const {
;     ...
;           for (int bj = 0; bj < 2; ++bj) {
;             f32x4 v0 = acc[ai][bj][m][0], v1 = acc[ai][bj][m][1];
;             if (rot) {
;               f32x4 o0, o1;
; #pragma unroll
;               for (int j = 0; j < 4; ++j) { o0[j] = shx(v0[j], fq * 16 + fr, 16); o1[j] = shx(v1[j], fq * 16 + fr, 16); }
;               if (fq < 2) {
;                 const f32x4 c0 = ldf4(cosA, (unsigned)pos * 32u), c1 = ldf4(cosA, (unsigned)pos * 32u + 16u);
;                 f32x4 s0 = ldf4(sinA, (unsigned)pos * 32u), s1 = ldf4(sinA, (unsigned)pos * 32u + 16u);
;                 if (fq == 0) { s0 = -s0; s1 = -s1; }
;                 v0 = v0 * c0 + o0 * s0; v1 = v1 * c1 + o1 * s1;
;               }
;             }
;             v0 *= sc; v1 *= sc;
;             {
;               const int hl = bj * 2 + (wc >> 1), head = isq ? u.pn * 4 + hl : hl, d0 = (wc & 1) * 32 + 8 * fq;
;               st16(isq ? q : k, (unsigned)((((head * 1024 + (row >> 5)) * 4 + (d0 >> 4)) * 64 + ((d0 >> 3) & 1) * 32 + (row & 31)) * 16), pk8(v0, v1)); }
.LBB0_331:
	s_lshr_b32 s2, s2, 3
	s_and_b32 s2, s2, 0x3fffffc
	s_waitcnt lgkmcnt(0)
	v_or_b32_e32 v27, s2, v162
	v_pk_mul_f32 v[14:15], v[24:25], v[14:15]
	v_pk_mul_f32 v[28:29], v[24:25], v[10:11]
	v_lshlrev_b32_e32 v24, 6, v27
	v_and_or_b32 v26, v34, 31, v163
	v_pk_mul_f32 v[10:11], v[140:141], v[8:9]
	v_add_u32_e32 v8, s23, v24
	v_or_b32_e32 v8, v8, v26
	v_pk_mul_f32 v[12:13], v[140:141], v[12:13]
	v_lshlrev_b32_e32 v176, 4, v8
	v_cvt_pk_bf16_f32 v8, v12, v13
	v_lshl_add_u64 v[12:13], s[0:1], 0, v[176:177]
	v_cvt_pk_bf16_f32 v9, v14, v15
	v_cvt_pk_bf16_f32 v10, v10, v11
	v_cvt_pk_bf16_f32 v11, v28, v29
	global_store_dwordx4 v[12:13], v[8:11], off
	s_and_b64 vcc, exec, s[10:11]
	s_cbranch_vccnz .LBB0_335
	ds_bpermute_b32 v14, v164, v4
	ds_bpermute_b32 v10, v164, v0
	ds_bpermute_b32 v15, v164, v5
	ds_bpermute_b32 v11, v164, v1
	ds_bpermute_b32 v12, v164, v6
	ds_bpermute_b32 v8, v164, v2
	ds_bpermute_b32 v13, v164, v7
	ds_bpermute_b32 v9, v164, v3
	s_and_saveexec_b64 s[4:5], s[6:7]
	s_cbranch_execz .LBB0_334
	global_load_dwordx4 v[28:31], v[20:21], off
	s_nop 0
	global_load_dwordx4 v[20:23], v[22:23], off
	s_nop 0
	global_load_dwordx4 v[32:35], v[16:17], off
	s_nop 0
	global_load_dwordx4 v[16:19], v[18:19], off
	s_waitcnt vmcnt(0) lgkmcnt(0)
	v_xor_b32_e32 v25, 0x80000000, v28
	v_xor_b32_e32 v27, 0x80000000, v29
	v_xor_b32_e32 v36, 0x80000000, v30
	v_xor_b32_e32 v37, 0x80000000, v31
	v_xor_b32_e32 v38, 0x80000000, v20
	v_xor_b32_e32 v39, 0x80000000, v21
	v_xor_b32_e32 v40, 0x80000000, v22
	v_xor_b32_e32 v41, 0x80000000, v23
	v_cndmask_b32_e64 v23, v23, v41, s[8:9]
	v_cndmask_b32_e64 v22, v22, v40, s[8:9]
	v_cndmask_b32_e64 v21, v21, v39, s[8:9]
	v_cndmask_b32_e64 v20, v20, v38, s[8:9]
	v_cndmask_b32_e64 v31, v31, v37, s[8:9]
	v_cndmask_b32_e64 v30, v30, v36, s[8:9]
	v_cndmask_b32_e64 v29, v29, v27, s[8:9]
	v_cndmask_b32_e64 v28, v28, v25, s[8:9]
	v_pk_mul_f32 v[14:15], v[28:29], v[14:15]
	v_pk_mul_f32 v[12:13], v[30:31], v[12:13]
	v_pk_mul_f32 v[10:11], v[20:21], v[10:11]
	v_pk_mul_f32 v[8:9], v[22:23], v[8:9]
	v_pk_fma_f32 v[6:7], v[6:7], v[34:35], v[12:13]
	v_pk_fma_f32 v[4:5], v[4:5], v[32:33], v[14:15]
	v_pk_fma_f32 v[2:3], v[2:3], v[18:19], v[8:9]
	v_pk_fma_f32 v[0:1], v[0:1], v[16:17], v[10:11]

; DI u32x4 pk8(const f32x4& v0, const f32x4& v1) { u32x4 w; w.x = cvt_pk_bf16(v0[0], v0[1]); w.y = cvt_pk_bf16(v0[2], v0[3]); w.z = cvt_pk_bf16(v1[0], v1[1]); w.w = cvt_pk_bf16(v1[2], v1[3]); return w; }
;   DI void epi(const Acc& acc, const Unit& u, int wr, int wc, int fr, int fq, LAS unsigned char* lds) const {
;     ...
;             v0 *= sc; v1 *= sc;
;             {
;               const int hl = bj * 2 + (wc >> 1), head = isq ? u.pn * 4 + hl : hl, d0 = (wc & 1) * 32 + 8 * fq;
;               st16(isq ? q : k, (unsigned)((((head * 1024 + (row >> 5)) * 4 + (d0 >> 4)) * 64 + ((d0 >> 3) & 1) * 32 + (row & 31)) * 16), pk8(v0, v1)); }
;             __builtin_amdgcn_sched_barrier(0);
;           }
.LBB0_335:
	s_waitcnt lgkmcnt(0)
	v_mov_b32_e32 v8, v140
	v_mov_b32_e32 v9, v140
	v_pk_mul_f32 v[6:7], v[8:9], v[6:7]
	v_pk_mul_f32 v[8:9], v[8:9], v[2:3]
	v_pk_mul_f32 v[2:3], v[140:141], v[0:1]
	v_add_u32_e32 v0, s51, v24
	v_or_b32_e32 v0, v0, v26
	v_pk_mul_f32 v[4:5], v[140:141], v[4:5]
	v_lshlrev_b32_e32 v176, 4, v0
	v_cvt_pk_bf16_f32 v0, v4, v5
	v_lshl_add_u64 v[4:5], s[0:1], 0, v[176:177]
	v_cvt_pk_bf16_f32 v1, v6, v7
	v_cvt_pk_bf16_f32 v2, v2, v3
	v_cvt_pk_bf16_f32 v3, v8, v9
	global_store_dwordx4 v[4:5], v[0:3], off
	s_andn2_b64 vcc, exec, s[24:25]
	s_mov_b64 s[0:1], -1
	s_cbranch_vccnz .LBB0_258
	s_branch .LBB0_338

; DI void build_tables(const Params& p) {
;     ...
;   for (int e = gt; e < 4096 * 136; e += gn) {
;     int pos, i; float invf;
;     const bool isA = e < 4096 * 8;
;     if (isA) { pos = e >> 3; i = e & 7; invf = exp2f(-(float)i * (18.931568569324174f / 8.0f)); }
;     else { const int e2 = e - 4096 * 8; pos = e2 >> 7; i = e2 & 127; invf = exp2f(-(float)i * (13.287712379549449f / 128.0f)); }
;     const double rev = (double)pos * (double)invf * 0.15915494309189535;
;     const float fr = (float)(rev - rint(rev));
;     const float c = __builtin_amdgcn_cosf(fr), s = __builtin_amdgcn_sinf(fr);
;     if (isA) { cosA[e] = c; sinA[e] = s; }
;     else { cosR[pos * 128 + i] = c; sinR[pos * 128 + i] = s; cosRT[i * 4096 + pos] = c; sinRT[i * 4096 + pos] = s; }
;   }
.LBB0_382:
	s_or_b64 exec, exec, s[6:7]
	v_ashrrev_i32_e32 v1, 31, v0
	v_lshl_add_u64 v[2:3], s[86:87], 0, v[2:3]
	v_lshl_add_u64 v[4:5], s[86:87], 0, v[4:5]
	v_lshlrev_b64 v[0:1], 2, v[0:1]
	v_cmp_gt_i32_e32 vcc, 0x8000, v6
	v_lshl_add_u64 v[4:5], v[4:5], 0, v[0:1]
	v_lshl_add_u64 v[0:1], v[2:3], 0, v[0:1]
	s_and_saveexec_b64 s[6:7], vcc
	global_store_dword v[4:5], v12, off
	global_store_dword v[0:1], v11, off
	s_or_b64 exec, exec, s[6:7]
	v_add_u32_e32 v6, s12, v6
	s_mov_b32 s6, 0x87fff
	v_cmp_lt_i32_e32 vcc, s6, v6
	s_nop 1
	s_or_b64 s[10:11], vcc, s[10:11]
	s_andn2_b64 exec, exec, s[10:11]
	s_cbranch_execz .LBB0_617

; DI u32x4 pk8(const f32x4& v0, const f32x4& v1) { u32x4 w; w.x = cvt_pk_bf16(v0[0], v0[1]); w.y = cvt_pk_bf16(v0[2], v0[3]); w.z = cvt_pk_bf16(v1[0], v1[1]); w.w = cvt_pk_bf16(v1[2], v1[3]); return w; }
; DI float silu_f(float x) { return x * __builtin_amdgcn_rcpf(1.0f + __expf(-x)); }
;   DI void epi(const Acc& acc, const Unit& u, int wr, int wc, int fr, int fq, LAS unsigned char* lds) const {
;     const int row0 = u.pm * 256 + wr * 64 + fr, col0 = u.pn * 128 + wc * 32 + 8 * fq;
; #pragma unroll
;     for (int ai = 0; ai < 2; ++ai)
; #pragma unroll
;       for (int m = 0; m < 4; ++m) {
;         f32x4 v0, v1;
; #pragma unroll
;         for (int j = 0; j < 4; ++j) { v0[j] = silu_f(acc[ai][0][m][0][j]) * acc[ai][1][m][0][j]; v1[j] = silu_f(acc[ai][0][m][1][j]) * acc[ai][1][m][1][j]; }
;         st16(act, (unsigned)((row0 + ai * 128 + m * 16) * DFF + col0) * 2u, pk8(v0, v1));
;       }
.LBB0_612:
	v_lshl_add_u32 v238, s31, 8, v138
	s_movk_i32 s7, 0xb00
	v_lshl_or_b32 v239, s30, 7, v140
	v_mul_lo_u32 v238, v238, s7
	s_andn2_b64 vcc, exec, s[12:13]
	s_mov_b64 s[12:13], -1
	v_mov_b32_e32 v222, 0xbfb8aa3b
	v_mov_b32_e32 v223, 0xbfb8aa3b
	v_mov_b32_e32 v224, 1.0
	v_mov_b32_e32 v225, 1.0
	v_add_lshl_u32 v238, v239, v238, 1
	v_pk_mul_f32 v[226:227], v[124:125], v[222:223]
	v_pk_mul_f32 v[228:229], v[126:127], v[222:223]
	v_pk_mul_f32 v[230:231], v[120:121], v[222:223]
	v_pk_mul_f32 v[232:233], v[122:123], v[222:223]
	v_exp_f32_e32 v226, v226
	v_exp_f32_e32 v227, v227
	v_exp_f32_e32 v228, v228
	v_exp_f32_e32 v229, v229
	v_exp_f32_e32 v230, v230
	v_exp_f32_e32 v231, v231
	v_exp_f32_e32 v232, v232
	v_exp_f32_e32 v233, v233
	v_pk_add_f32 v[226:227], v[226:227], v[224:225]
	v_pk_add_f32 v[228:229], v[228:229], v[224:225]
	v_pk_add_f32 v[230:231], v[230:231], v[224:225]
	v_pk_add_f32 v[232:233], v[232:233], v[224:225]
	v_rcp_f32_e32 v226, v226
	v_rcp_f32_e32 v227, v227
	v_rcp_f32_e32 v228, v228
	v_rcp_f32_e32 v229, v229
	v_rcp_f32_e32 v230, v230
	v_rcp_f32_e32 v231, v231
	v_rcp_f32_e32 v232, v232
	v_rcp_f32_e32 v233, v233
	v_pk_mul_f32 v[124:125], v[124:125], v[226:227]
	v_pk_mul_f32 v[126:127], v[126:127], v[228:229]
	v_pk_mul_f32 v[120:121], v[120:121], v[230:231]
	v_pk_mul_f32 v[122:123], v[122:123], v[232:233]
	v_pk_mul_f32 v[124:125], v[124:125], v[116:117]
	v_pk_mul_f32 v[126:127], v[126:127], v[118:119]
	v_pk_mul_f32 v[120:121], v[120:121], v[112:113]
	v_pk_mul_f32 v[122:123], v[122:123], v[114:115]
	v_cvt_pk_bf16_f32 v234, v124, v125
	v_cvt_pk_bf16_f32 v235, v126, v127
	v_cvt_pk_bf16_f32 v236, v120, v121
	v_cvt_pk_bf16_f32 v237, v122, v123
	global_store_dwordx4 v238, v[234:237], s[92:93]
	v_pk_mul_f32 v[226:227], v[108:109], v[222:223]
	v_pk_mul_f32 v[228:229], v[110:111], v[222:223]
	v_pk_mul_f32 v[230:231], v[104:105], v[222:223]
	v_pk_mul_f32 v[232:233], v[106:107], v[222:223]
	v_exp_f32_e32 v226, v226
	v_exp_f32_e32 v227, v227
	v_exp_f32_e32 v228, v228
	v_exp_f32_e32 v229, v229
	v_exp_f32_e32 v230, v230
	v_exp_f32_e32 v231, v231
	v_exp_f32_e32 v232, v232
	v_exp_f32_e32 v233, v233
	v_pk_add_f32 v[226:227], v[226:227], v[224:225]
	v_pk_add_f32 v[228:229], v[228:229], v[224:225]
	v_pk_add_f32 v[230:231], v[230:231], v[224:225]
	v_pk_add_f32 v[232:233], v[232:233], v[224:225]
	v_rcp_f32_e32 v226, v226
	v_rcp_f32_e32 v227, v227
	v_rcp_f32_e32 v228, v228
	v_rcp_f32_e32 v229, v229
	v_rcp_f32_e32 v230, v230
	v_rcp_f32_e32 v231, v231
	v_rcp_f32_e32 v232, v232
	v_rcp_f32_e32 v233, v233
	v_pk_mul_f32 v[108:109], v[108:109], v[226:227]
	v_pk_mul_f32 v[110:111], v[110:111], v[228:229]
	v_pk_mul_f32 v[104:105], v[104:105], v[230:231]
	v_pk_mul_f32 v[106:107], v[106:107], v[232:233]
	v_pk_mul_f32 v[108:109], v[108:109], v[100:101]
	v_pk_mul_f32 v[110:111], v[110:111], v[102:103]
	v_pk_mul_f32 v[104:105], v[104:105], v[96:97]
	v_pk_mul_f32 v[106:107], v[106:107], v[98:99]
	v_cvt_pk_bf16_f32 v234, v108, v109
	v_cvt_pk_bf16_f32 v235, v110, v111
	v_cvt_pk_bf16_f32 v236, v104, v105
	v_cvt_pk_bf16_f32 v237, v106, v107
	v_add_u32_e32 v239, 0x16000, v238
	global_store_dwordx4 v239, v[234:237], s[92:93]
	v_pk_mul_f32 v[226:227], v[92:93], v[222:223]
	v_pk_mul_f32 v[228:229], v[94:95], v[222:223]
	v_pk_mul_f32 v[230:231], v[88:89], v[222:223]
	v_pk_mul_f32 v[232:233], v[90:91], v[222:223]
	v_exp_f32_e32 v226, v226
	v_exp_f32_e32 v227, v227
	v_exp_f32_e32 v228, v228
	v_exp_f32_e32 v229, v229
	v_exp_f32_e32 v230, v230
	v_exp_f32_e32 v231, v231
	v_exp_f32_e32 v232, v232
	v_exp_f32_e32 v233, v233
	v_pk_add_f32 v[226:227], v[226:227], v[224:225]
	v_pk_add_f32 v[228:229], v[228:229], v[224:225]
	v_pk_add_f32 v[230:231], v[230:231], v[224:225]
	v_pk_add_f32 v[232:233], v[232:233], v[224:225]
	v_rcp_f32_e32 v226, v226
	v_rcp_f32_e32 v227, v227
	v_rcp_f32_e32 v228, v228
	v_rcp_f32_e32 v229, v229
	v_rcp_f32_e32 v230, v230
	v_rcp_f32_e32 v231, v231
	v_rcp_f32_e32 v232, v232
	v_rcp_f32_e32 v233, v233
	v_pk_mul_f32 v[92:93], v[92:93], v[226:227]
	v_pk_mul_f32 v[94:95], v[94:95], v[228:229]
	v_pk_mul_f32 v[88:89], v[88:89], v[230:231]
	v_pk_mul_f32 v[90:91], v[90:91], v[232:233]
	v_pk_mul_f32 v[92:93], v[92:93], v[84:85]
	v_pk_mul_f32 v[94:95], v[94:95], v[86:87]
	v_pk_mul_f32 v[88:89], v[88:89], v[80:81]
	v_pk_mul_f32 v[90:91], v[90:91], v[82:83]
	v_cvt_pk_bf16_f32 v234, v92, v93
	v_cvt_pk_bf16_f32 v235, v94, v95
	v_cvt_pk_bf16_f32 v236, v88, v89
	v_cvt_pk_bf16_f32 v237, v90, v91
	v_add_u32_e32 v239, 0x2c000, v238
	global_store_dwordx4 v239, v[234:237], s[92:93]
	v_pk_mul_f32 v[226:227], v[76:77], v[222:223]
	v_pk_mul_f32 v[228:229], v[78:79], v[222:223]
	v_pk_mul_f32 v[230:231], v[72:73], v[222:223]
	v_pk_mul_f32 v[232:233], v[74:75], v[222:223]
	v_exp_f32_e32 v226, v226
	v_exp_f32_e32 v227, v227
	v_exp_f32_e32 v228, v228
	v_exp_f32_e32 v229, v229
	v_exp_f32_e32 v230, v230
	v_exp_f32_e32 v231, v231
	v_exp_f32_e32 v232, v232
	v_exp_f32_e32 v233, v233
	v_pk_add_f32 v[226:227], v[226:227], v[224:225]
	v_pk_add_f32 v[228:229], v[228:229], v[224:225]
	v_pk_add_f32 v[230:231], v[230:231], v[224:225]
	v_pk_add_f32 v[232:233], v[232:233], v[224:225]
	v_rcp_f32_e32 v226, v226
	v_rcp_f32_e32 v227, v227
	v_rcp_f32_e32 v228, v228
	v_rcp_f32_e32 v229, v229
	v_rcp_f32_e32 v230, v230
	v_rcp_f32_e32 v231, v231
	v_rcp_f32_e32 v232, v232
	v_rcp_f32_e32 v233, v233
	v_pk_mul_f32 v[76:77], v[76:77], v[226:227]
	v_pk_mul_f32 v[78:79], v[78:79], v[228:229]
	v_pk_mul_f32 v[72:73], v[72:73], v[230:231]
	v_pk_mul_f32 v[74:75], v[74:75], v[232:233]
	v_pk_mul_f32 v[76:77], v[76:77], v[68:69]
	v_pk_mul_f32 v[78:79], v[78:79], v[70:71]
	v_pk_mul_f32 v[72:73], v[72:73], v[64:65]
; DI float silu_f(float x) { return x * __builtin_amdgcn_rcpf(1.0f + __expf(-x)); }
; DI u32x4 pk8(const f32x4& v0, const f32x4& v1) { u32x4 w; w.x = cvt_pk_bf16(v0[0], v0[1]); w.y = cvt_pk_bf16(v0[2], v0[3]); w.z = cvt_pk_bf16(v1[0], v1[1]); w.w = cvt_pk_bf16(v1[2], v1[3]); return w; }
;   DI void epi(const Acc& acc, const Unit& u, int wr, int wc, int fr, int fq, LAS unsigned char* lds) const {
;     ...
;     for (int ai = 0; ai < 2; ++ai)
; #pragma unroll
;       for (int m = 0; m < 4; ++m) {
;         f32x4 v0, v1;
; #pragma unroll
;         for (int j = 0; j < 4; ++j) { v0[j] = silu_f(acc[ai][0][m][0][j]) * acc[ai][1][m][0][j]; v1[j] = silu_f(acc[ai][0][m][1][j]) * acc[ai][1][m][1][j]; }
;         st16(act, (unsigned)((row0 + ai * 128 + m * 16) * DFF + col0) * 2u, pk8(v0, v1));
;       }
	v_pk_mul_f32 v[74:75], v[74:75], v[66:67]
	v_cvt_pk_bf16_f32 v234, v76, v77
	v_cvt_pk_bf16_f32 v235, v78, v79
	v_cvt_pk_bf16_f32 v236, v72, v73
	v_cvt_pk_bf16_f32 v237, v74, v75
	v_add_u32_e32 v239, 0x42000, v238
	global_store_dwordx4 v239, v[234:237], s[92:93]
	v_pk_mul_f32 v[226:227], v[60:61], v[222:223]
	v_pk_mul_f32 v[228:229], v[62:63], v[222:223]
	v_pk_mul_f32 v[230:231], v[56:57], v[222:223]
	v_pk_mul_f32 v[232:233], v[58:59], v[222:223]
	v_exp_f32_e32 v226, v226
	v_exp_f32_e32 v227, v227
	v_exp_f32_e32 v228, v228
	v_exp_f32_e32 v229, v229
	v_exp_f32_e32 v230, v230
	v_exp_f32_e32 v231, v231
	v_exp_f32_e32 v232, v232
	v_exp_f32_e32 v233, v233
	v_pk_add_f32 v[226:227], v[226:227], v[224:225]
	v_pk_add_f32 v[228:229], v[228:229], v[224:225]
	v_pk_add_f32 v[230:231], v[230:231], v[224:225]
	v_pk_add_f32 v[232:233], v[232:233], v[224:225]
	v_rcp_f32_e32 v226, v226
	v_rcp_f32_e32 v227, v227
	v_rcp_f32_e32 v228, v228
	v_rcp_f32_e32 v229, v229
	v_rcp_f32_e32 v230, v230
	v_rcp_f32_e32 v231, v231
	v_rcp_f32_e32 v232, v232
	v_rcp_f32_e32 v233, v233
	v_pk_mul_f32 v[60:61], v[60:61], v[226:227]
	v_pk_mul_f32 v[62:63], v[62:63], v[228:229]
	v_pk_mul_f32 v[56:57], v[56:57], v[230:231]
	v_pk_mul_f32 v[58:59], v[58:59], v[232:233]
	v_pk_mul_f32 v[60:61], v[60:61], v[52:53]
	v_pk_mul_f32 v[62:63], v[62:63], v[54:55]
	v_pk_mul_f32 v[56:57], v[56:57], v[48:49]
	v_pk_mul_f32 v[58:59], v[58:59], v[50:51]
	v_cvt_pk_bf16_f32 v234, v60, v61
	v_cvt_pk_bf16_f32 v235, v62, v63
	v_cvt_pk_bf16_f32 v236, v56, v57
	v_cvt_pk_bf16_f32 v237, v58, v59
	v_add_u32_e32 v239, 0xb0000, v238
	global_store_dwordx4 v239, v[234:237], s[92:93]
	v_pk_mul_f32 v[226:227], v[44:45], v[222:223]
	v_pk_mul_f32 v[228:229], v[46:47], v[222:223]
	v_pk_mul_f32 v[230:231], v[40:41], v[222:223]
	v_pk_mul_f32 v[232:233], v[42:43], v[222:223]
	v_exp_f32_e32 v226, v226
	v_exp_f32_e32 v227, v227
	v_exp_f32_e32 v228, v228
	v_exp_f32_e32 v229, v229
	v_exp_f32_e32 v230, v230
	v_exp_f32_e32 v231, v231
	v_exp_f32_e32 v232, v232
	v_exp_f32_e32 v233, v233
	v_pk_add_f32 v[226:227], v[226:227], v[224:225]
	v_pk_add_f32 v[228:229], v[228:229], v[224:225]
	v_pk_add_f32 v[230:231], v[230:231], v[224:225]
	v_pk_add_f32 v[232:233], v[232:233], v[224:225]
	v_rcp_f32_e32 v226, v226
	v_rcp_f32_e32 v227, v227
	v_rcp_f32_e32 v228, v228
	v_rcp_f32_e32 v229, v229
	v_rcp_f32_e32 v230, v230
	v_rcp_f32_e32 v231, v231
	v_rcp_f32_e32 v232, v232
	v_rcp_f32_e32 v233, v233
	v_pk_mul_f32 v[44:45], v[44:45], v[226:227]
	v_pk_mul_f32 v[46:47], v[46:47], v[228:229]
	v_pk_mul_f32 v[40:41], v[40:41], v[230:231]
	v_pk_mul_f32 v[42:43], v[42:43], v[232:233]
	v_pk_mul_f32 v[44:45], v[44:45], v[36:37]
	v_pk_mul_f32 v[46:47], v[46:47], v[38:39]
	v_pk_mul_f32 v[40:41], v[40:41], v[32:33]
	v_pk_mul_f32 v[42:43], v[42:43], v[34:35]
	v_cvt_pk_bf16_f32 v234, v44, v45
	v_cvt_pk_bf16_f32 v235, v46, v47
	v_cvt_pk_bf16_f32 v236, v40, v41
	v_cvt_pk_bf16_f32 v237, v42, v43
	v_add_u32_e32 v239, 0xc6000, v238
	global_store_dwordx4 v239, v[234:237], s[92:93]
	v_pk_mul_f32 v[226:227], v[28:29], v[222:223]
	v_pk_mul_f32 v[228:229], v[30:31], v[222:223]
	v_pk_mul_f32 v[230:231], v[24:25], v[222:223]
	v_pk_mul_f32 v[232:233], v[26:27], v[222:223]
	v_exp_f32_e32 v226, v226
	v_exp_f32_e32 v227, v227
	v_exp_f32_e32 v228, v228
	v_exp_f32_e32 v229, v229
	v_exp_f32_e32 v230, v230
	v_exp_f32_e32 v231, v231
	v_exp_f32_e32 v232, v232
	v_exp_f32_e32 v233, v233
	v_pk_add_f32 v[226:227], v[226:227], v[224:225]
	v_pk_add_f32 v[228:229], v[228:229], v[224:225]
	v_pk_add_f32 v[230:231], v[230:231], v[224:225]
	v_pk_add_f32 v[232:233], v[232:233], v[224:225]
	v_rcp_f32_e32 v226, v226
	v_rcp_f32_e32 v227, v227
	v_rcp_f32_e32 v228, v228
	v_rcp_f32_e32 v229, v229
	v_rcp_f32_e32 v230, v230
	v_rcp_f32_e32 v231, v231
	v_rcp_f32_e32 v232, v232
	v_rcp_f32_e32 v233, v233
	v_pk_mul_f32 v[28:29], v[28:29], v[226:227]
	v_pk_mul_f32 v[30:31], v[30:31], v[228:229]
	v_pk_mul_f32 v[24:25], v[24:25], v[230:231]
	v_pk_mul_f32 v[26:27], v[26:27], v[232:233]
	v_pk_mul_f32 v[28:29], v[28:29], v[20:21]
	v_pk_mul_f32 v[30:31], v[30:31], v[22:23]
	v_pk_mul_f32 v[24:25], v[24:25], v[16:17]
	v_pk_mul_f32 v[26:27], v[26:27], v[18:19]
	v_cvt_pk_bf16_f32 v234, v28, v29
	v_cvt_pk_bf16_f32 v235, v30, v31
	v_cvt_pk_bf16_f32 v236, v24, v25
	v_cvt_pk_bf16_f32 v237, v26, v27
	v_add_u32_e32 v239, 0xdc000, v238
	global_store_dwordx4 v239, v[234:237], s[92:93]
	v_pk_mul_f32 v[226:227], v[12:13], v[222:223]
	v_pk_mul_f32 v[228:229], v[14:15], v[222:223]
	v_pk_mul_f32 v[230:231], v[8:9], v[222:223]
	v_pk_mul_f32 v[232:233], v[10:11], v[222:223]
	v_exp_f32_e32 v226, v226
	v_exp_f32_e32 v227, v227
	v_exp_f32_e32 v228, v228
	v_exp_f32_e32 v229, v229
	v_exp_f32_e32 v230, v230
	v_exp_f32_e32 v231, v231
	v_exp_f32_e32 v232, v232
	v_exp_f32_e32 v233, v233
	v_pk_add_f32 v[226:227], v[226:227], v[224:225]
	v_pk_add_f32 v[228:229], v[228:229], v[224:225]
	v_pk_add_f32 v[230:231], v[230:231], v[224:225]
	v_pk_add_f32 v[232:233], v[232:233], v[224:225]
	v_rcp_f32_e32 v226, v226
	v_rcp_f32_e32 v227, v227
	v_rcp_f32_e32 v228, v228
	v_rcp_f32_e32 v229, v229
	v_rcp_f32_e32 v230, v230
	v_rcp_f32_e32 v231, v231
	v_rcp_f32_e32 v232, v232
	v_rcp_f32_e32 v233, v233
	v_pk_mul_f32 v[12:13], v[12:13], v[226:227]
	v_pk_mul_f32 v[14:15], v[14:15], v[228:229]
	v_pk_mul_f32 v[8:9], v[8:9], v[230:231]
	v_pk_mul_f32 v[10:11], v[10:11], v[232:233]
	v_pk_mul_f32 v[12:13], v[12:13], v[4:5]
	v_pk_mul_f32 v[14:15], v[14:15], v[6:7]
	v_pk_mul_f32 v[8:9], v[8:9], v[0:1]
	v_pk_mul_f32 v[10:11], v[10:11], v[2:3]
	v_cvt_pk_bf16_f32 v234, v12, v13
	v_cvt_pk_bf16_f32 v235, v14, v15
	v_cvt_pk_bf16_f32 v236, v8, v9
	v_cvt_pk_bf16_f32 v237, v10, v11
	v_add_u32_e32 v239, 0xf2000, v238
	global_store_dwordx4 v239, v[234:237], s[92:93]
	s_cbranch_vccnz .LBB0_605
	s_andn2_b64 vcc, exec, s[0:1]
	s_cbranch_vccnz .LBB0_604
	s_barrier
	s_branch .LBB0_604
